# P8b EpiGrp epilogue: batched loads, permlane16-widened dwordx4 stores; P0 adaLN: batched cond staging + 12-deep load pipeline
# speedup vs baseline: 1.0157x; 1.0157x over previous
.LBB0_17:
	s_mul_hi_i32 s12, s26, 0x2aaaaaab
	s_lshr_b32 s13, s12, 31
	s_ashr_i32 s12, s12, 5
	s_add_i32 s12, s12, s13
	s_mul_i32 s13, s12, 0xc0
	s_sub_i32 s13, s26, s13
	s_and_b32 s27, s13, 7
	s_lshl_b32 s28, s27, 8
	s_barrier
	s_and_saveexec_b64 s[14:15], s[4:5]
	s_cbranch_execz .LBB0_24
	v_and_b32_e32 v20, 0xff, v10
	v_lshrrev_b32_e32 v21, 8, v10
	v_lshl_or_b32 v21, v21, 11, v20
	v_or_b32_e32 v21, s28, v21
	v_lshlrev_b32_e32 v21, 2, v21
	global_load_dword v22, v21, s[72:73]
	global_load_dword v23, v21, s[74:75]
	v_add_u32_e32 v41, 0x4000, v21
	global_load_dword v24, v41, s[74:75]
	v_add_u32_e32 v42, 0x8000, v21
	global_load_dword v25, v42, s[74:75]
	v_add_u32_e32 v43, 0xc000, v21
	global_load_dword v26, v43, s[74:75]
	v_add_u32_e32 v44, 0x10000, v21
	global_load_dword v27, v44, s[74:75]
	v_add_u32_e32 v45, 0x14000, v21
	global_load_dword v28, v45, s[74:75]
	v_add_u32_e32 v46, 0x18000, v21
	global_load_dword v29, v46, s[74:75]
	v_add_u32_e32 v47, 0x1c000, v21
	global_load_dword v30, v47, s[74:75]
	s_waitcnt vmcnt(0)
	v_mul_f32_e32 v31, 0xbfb8aa3b, v22
	v_mul_f32_e32 v32, 0xbfb8aa3b, v23
	v_mul_f32_e32 v33, 0xbfb8aa3b, v24
	v_mul_f32_e32 v34, 0xbfb8aa3b, v25
	v_mul_f32_e32 v35, 0xbfb8aa3b, v26
	v_mul_f32_e32 v36, 0xbfb8aa3b, v27
	v_mul_f32_e32 v37, 0xbfb8aa3b, v28
	v_mul_f32_e32 v38, 0xbfb8aa3b, v29
	v_mul_f32_e32 v39, 0xbfb8aa3b, v30
	v_exp_f32_e32 v31, v31
	v_exp_f32_e32 v32, v32
	v_exp_f32_e32 v33, v33
	v_exp_f32_e32 v34, v34
	v_exp_f32_e32 v35, v35
	v_exp_f32_e32 v36, v36
	v_exp_f32_e32 v37, v37
	v_exp_f32_e32 v38, v38
	v_exp_f32_e32 v39, v39
	v_add_f32_e32 v31, 1.0, v31
	v_add_f32_e32 v32, 1.0, v32
	v_add_f32_e32 v33, 1.0, v33
	v_add_f32_e32 v34, 1.0, v34
	v_add_f32_e32 v35, 1.0, v35
	v_add_f32_e32 v36, 1.0, v36
	v_add_f32_e32 v37, 1.0, v37
	v_add_f32_e32 v38, 1.0, v38
	v_add_f32_e32 v39, 1.0, v39
	v_rcp_f32_e32 v31, v31
	v_rcp_f32_e32 v32, v32
	v_rcp_f32_e32 v33, v33
	v_rcp_f32_e32 v34, v34
	v_rcp_f32_e32 v35, v35
	v_rcp_f32_e32 v36, v36
	v_rcp_f32_e32 v37, v37
	v_rcp_f32_e32 v38, v38
	v_rcp_f32_e32 v39, v39
	v_mul_f32_e32 v22, v22, v31
	v_mul_f32_e32 v23, v23, v32
	v_mul_f32_e32 v24, v24, v33
	v_mul_f32_e32 v25, v25, v34
	v_mul_f32_e32 v26, v26, v35
	v_mul_f32_e32 v27, v27, v36
	v_mul_f32_e32 v28, v28, v37
	v_mul_f32_e32 v29, v29, v38
	v_mul_f32_e32 v30, v30, v39
	ds_write_b32 v159, v22
	ds_write_b32 v159, v23 offset:2048
	ds_write_b32 v159, v24 offset:4096
	ds_write_b32 v159, v25 offset:6144
	ds_write_b32 v159, v26 offset:8192
	ds_write_b32 v159, v27 offset:10240
	ds_write_b32 v159, v28 offset:12288
	ds_write_b32 v159, v29 offset:14336
	ds_write_b32 v159, v30 offset:16384
.LBB0_24:
	s_or_b64 exec, exec, s[14:15]
	s_lshl_b32 s13, s13, 5
	s_and_b32 s16, s13, 0xffffff00
	s_ashr_i32 s13, s12, 31
	s_lshl_b64 s[14:15], s[12:13], 11
	v_add_u32_e32 v16, s16, v154
	s_or_b32 s14, s14, s28
	v_ashrrev_i32_e32 v17, 31, v16
	v_lshl_add_u64 v[2:3], s[14:15], 0, v[12:13]
	v_lshlrev_b64 v[4:5], 2, v[16:17]
	v_mad_u64_u32 v[4:5], s[14:15], v2, s2, v[4:5]
	v_mad_i32_i24 v5, v3, s2, v5
	v_mov_b32_e32 v66, 0
	v_lshl_add_u64 v[18:19], s[0:1], 0, v[4:5]
	s_mov_b32 s13, -8
	v_mov_b32_e32 v67, v66
	v_mov_b32_e32 v64, v66
	v_mov_b32_e32 v65, v66
	v_mov_b32_e32 v62, v66
	v_mov_b32_e32 v63, v66
	v_mov_b32_e32 v60, v66
	v_mov_b32_e32 v61, v66
	v_mov_b32_e32 v58, v66
	v_mov_b32_e32 v59, v66
	v_mov_b32_e32 v56, v66
	v_mov_b32_e32 v57, v66
	v_mov_b32_e32 v54, v66
	v_mov_b32_e32 v55, v66
	v_mov_b32_e32 v52, v66
	v_mov_b32_e32 v53, v66
	v_mov_b32_e32 v50, v66
	v_mov_b32_e32 v51, v66
	v_mov_b32_e32 v48, v66
	v_mov_b32_e32 v49, v66
	v_mov_b32_e32 v46, v66
	v_mov_b32_e32 v47, v66
	v_mov_b32_e32 v44, v66
	v_mov_b32_e32 v45, v66
	v_mov_b32_e32 v42, v66
	v_mov_b32_e32 v43, v66
	v_mov_b32_e32 v40, v66
	v_mov_b32_e32 v41, v66
	v_mov_b32_e32 v38, v66
	v_mov_b32_e32 v39, v66
	v_mov_b32_e32 v36, v66
	v_mov_b32_e32 v37, v66
	v_mov_b32_e32 v34, v66
	v_mov_b32_e32 v35, v66
	v_mov_b32_e32 v32, v66
	v_mov_b32_e32 v33, v66
	v_mov_b32_e32 v30, v66
	v_mov_b32_e32 v31, v66
	v_mov_b32_e32 v28, v66
	v_mov_b32_e32 v29, v66
	v_mov_b32_e32 v26, v66
	v_mov_b32_e32 v27, v66
	s_waitcnt lgkmcnt(14)
	v_mov_b32_e32 v24, v66
	v_mov_b32_e32 v25, v66
	v_mov_b32_e32 v22, v66
	v_mov_b32_e32 v23, v66
	v_mov_b32_e32 v20, v66
	v_mov_b32_e32 v21, v66
	v_mov_b32_e32 v98, v66
	v_mov_b32_e32 v99, v66
	v_mov_b32_e32 v96, v66
	v_mov_b32_e32 v97, v66
	v_mov_b32_e32 v94, v66
	v_mov_b32_e32 v95, v66
	v_mov_b32_e32 v92, v66
	v_mov_b32_e32 v93, v66
	v_mov_b32_e32 v90, v66
	v_mov_b32_e32 v91, v66
	s_waitcnt lgkmcnt(13)
	v_mov_b32_e32 v88, v66
	s_waitcnt lgkmcnt(12)
	v_mov_b32_e32 v89, v66
	v_mov_b32_e32 v78, v66
	v_mov_b32_e32 v79, v66
	s_waitcnt lgkmcnt(9)
	v_mov_b32_e32 v76, v66
	s_waitcnt lgkmcnt(8)
	v_mov_b32_e32 v77, v66
	v_mov_b32_e32 v74, v66
	v_mov_b32_e32 v75, v66
	s_waitcnt lgkmcnt(7)
	v_mov_b32_e32 v72, v66
	s_waitcnt lgkmcnt(6)
	v_mov_b32_e32 v73, v66
	s_waitcnt lgkmcnt(1)
	v_mov_b32_e32 v70, v66
	s_waitcnt lgkmcnt(0)
	v_mov_b32_e32 v71, v66
	v_mov_b32_e32 v68, v66
	v_mov_b32_e32 v69, v66
	v_mov_b32_e32 v128, v155
	s_waitcnt lgkmcnt(0)
	s_barrier
	s_mov_b32 s14, 0xfff40000
	v_add_co_u32_e32 v18, vcc, s14, v18
	s_nop 1
	v_addc_co_u32_e32 v19, vcc, -1, v19, vcc
	s_mov_b64 s[14:15], 0x30000
	global_load_dwordx4 v[100:103], v[18:19], off
	v_lshl_add_u64 v[18:19], v[18:19], 0, s[14:15]
	global_load_dwordx4 v[104:107], v[18:19], off
	v_lshl_add_u64 v[18:19], v[18:19], 0, s[14:15]
	global_load_dwordx4 v[108:111], v[18:19], off
	v_lshl_add_u64 v[18:19], v[18:19], 0, s[14:15]
	global_load_dwordx4 v[112:115], v[18:19], off
	v_lshl_add_u64 v[18:19], v[18:19], 0, s[14:15]
	global_load_dwordx4 v[116:119], v[18:19], off
	v_lshl_add_u64 v[18:19], v[18:19], 0, s[14:15]
	global_load_dwordx4 v[120:123], v[18:19], off
	v_lshl_add_u64 v[18:19], v[18:19], 0, s[14:15]
	global_load_dwordx4 v[124:127], v[18:19], off
	v_lshl_add_u64 v[18:19], v[18:19], 0, s[14:15]
	global_load_dwordx4 v[130:133], v[18:19], off
	v_lshl_add_u64 v[18:19], v[18:19], 0, s[14:15]
	global_load_dwordx4 v[134:137], v[18:19], off
	v_lshl_add_u64 v[18:19], v[18:19], 0, s[14:15]
	global_load_dwordx4 v[138:141], v[18:19], off
	v_lshl_add_u64 v[18:19], v[18:19], 0, s[14:15]
	global_load_dwordx4 v[146:149], v[18:19], off
	v_lshl_add_u64 v[18:19], v[18:19], 0, s[14:15]
	global_load_dwordx4 v[150:153], v[18:19], off
	ds_read2st64_b32 v[162:163], v128 offset1:4
	ds_read2st64_b32 v[164:165], v128 offset0:8 offset1:12
	ds_read2st64_b32 v[166:167], v128 offset0:16 offset1:20
	ds_read2st64_b32 v[168:169], v128 offset0:24 offset1:28
	ds_read2st64_b32 v[170:171], v128 offset0:32 offset1:36
	ds_read2st64_b32 v[172:173], v128 offset0:40 offset1:44
	ds_read2st64_b32 v[174:175], v128 offset0:48 offset1:52
	ds_read2st64_b32 v[176:177], v128 offset0:56 offset1:60
	ds_read2st64_b32 v[178:179], v128 offset0:64 offset1:68
	v_add_u32_e32 v14, 32, v128
	ds_read2st64_b32 v[80:81], v14 offset1:4
	ds_read2st64_b32 v[82:83], v14 offset0:8 offset1:12
	ds_read2st64_b32 v[84:85], v14 offset0:16 offset1:20
	ds_read2st64_b32 v[86:87], v14 offset0:24 offset1:28
	ds_read2st64_b32 v[2:3], v14 offset0:32 offset1:36
	ds_read2st64_b32 v[4:5], v14 offset0:40 offset1:44
	ds_read2st64_b32 v[6:7], v14 offset0:48 offset1:52
	ds_read2st64_b32 v[8:9], v14 offset0:56 offset1:60
	ds_read2st64_b32 v[142:143], v14 offset0:64 offset1:68
	s_waitcnt vmcnt(11) lgkmcnt(9)
	v_pk_fma_f32 v[64:65], v[102:103], v[162:163], v[64:65] op_sel_hi:[1,0,1]
	v_pk_fma_f32 v[66:67], v[100:101], v[162:163], v[66:67] op_sel_hi:[1,0,1]
	v_pk_fma_f32 v[60:61], v[102:103], v[162:163], v[60:61] op_sel:[0,1,0]
	v_pk_fma_f32 v[62:63], v[100:101], v[162:163], v[62:63] op_sel:[0,1,0]
	v_pk_fma_f32 v[56:57], v[102:103], v[164:165], v[56:57] op_sel_hi:[1,0,1]
	v_pk_fma_f32 v[58:59], v[100:101], v[164:165], v[58:59] op_sel_hi:[1,0,1]
	v_pk_fma_f32 v[52:53], v[102:103], v[164:165], v[52:53] op_sel:[0,1,0]
	v_pk_fma_f32 v[54:55], v[100:101], v[164:165], v[54:55] op_sel:[0,1,0]
	v_pk_fma_f32 v[48:49], v[102:103], v[166:167], v[48:49] op_sel_hi:[1,0,1]
	v_pk_fma_f32 v[50:51], v[100:101], v[166:167], v[50:51] op_sel_hi:[1,0,1]
	v_pk_fma_f32 v[44:45], v[102:103], v[166:167], v[44:45] op_sel:[0,1,0]
	v_pk_fma_f32 v[46:47], v[100:101], v[166:167], v[46:47] op_sel:[0,1,0]
	v_pk_fma_f32 v[40:41], v[102:103], v[168:169], v[40:41] op_sel_hi:[1,0,1]
	v_pk_fma_f32 v[42:43], v[100:101], v[168:169], v[42:43] op_sel_hi:[1,0,1]
	v_pk_fma_f32 v[36:37], v[102:103], v[168:169], v[36:37] op_sel:[0,1,0]
	v_pk_fma_f32 v[38:39], v[100:101], v[168:169], v[38:39] op_sel:[0,1,0]
	v_pk_fma_f32 v[32:33], v[102:103], v[170:171], v[32:33] op_sel_hi:[1,0,1]
	v_pk_fma_f32 v[34:35], v[100:101], v[170:171], v[34:35] op_sel_hi:[1,0,1]
	v_pk_fma_f32 v[28:29], v[102:103], v[170:171], v[28:29] op_sel:[0,1,0]
	v_pk_fma_f32 v[30:31], v[100:101], v[170:171], v[30:31] op_sel:[0,1,0]
	v_pk_fma_f32 v[24:25], v[102:103], v[172:173], v[24:25] op_sel_hi:[1,0,1]
	v_pk_fma_f32 v[26:27], v[100:101], v[172:173], v[26:27] op_sel_hi:[1,0,1]
	v_pk_fma_f32 v[20:21], v[102:103], v[172:173], v[20:21] op_sel:[0,1,0]
	v_pk_fma_f32 v[22:23], v[100:101], v[172:173], v[22:23] op_sel:[0,1,0]
	v_pk_fma_f32 v[96:97], v[102:103], v[174:175], v[96:97] op_sel_hi:[1,0,1]
	v_pk_fma_f32 v[98:99], v[100:101], v[174:175], v[98:99] op_sel_hi:[1,0,1]
	v_pk_fma_f32 v[92:93], v[102:103], v[174:175], v[92:93] op_sel:[0,1,0]
	v_pk_fma_f32 v[94:95], v[100:101], v[174:175], v[94:95] op_sel:[0,1,0]
	v_pk_fma_f32 v[88:89], v[102:103], v[176:177], v[88:89] op_sel_hi:[1,0,1]
	v_pk_fma_f32 v[90:91], v[100:101], v[176:177], v[90:91] op_sel_hi:[1,0,1]
	v_pk_fma_f32 v[76:77], v[102:103], v[176:177], v[76:77] op_sel:[0,1,0]
	v_pk_fma_f32 v[78:79], v[100:101], v[176:177], v[78:79] op_sel:[0,1,0]
	v_pk_fma_f32 v[72:73], v[102:103], v[178:179], v[72:73] op_sel_hi:[1,0,1]
	v_pk_fma_f32 v[74:75], v[100:101], v[178:179], v[74:75] op_sel_hi:[1,0,1]
	v_pk_fma_f32 v[68:69], v[102:103], v[178:179], v[68:69] op_sel:[0,1,0]
	v_pk_fma_f32 v[70:71], v[100:101], v[178:179], v[70:71] op_sel:[0,1,0]
	v_lshl_add_u64 v[18:19], v[18:19], 0, s[14:15]
	global_load_dwordx4 v[100:103], v[18:19], off
	v_add_u32_e32 v14, 64, v128
	ds_read2st64_b32 v[162:163], v14 offset1:4
	ds_read2st64_b32 v[164:165], v14 offset0:8 offset1:12
	ds_read2st64_b32 v[166:167], v14 offset0:16 offset1:20
	ds_read2st64_b32 v[168:169], v14 offset0:24 offset1:28
	ds_read2st64_b32 v[170:171], v14 offset0:32 offset1:36
	ds_read2st64_b32 v[172:173], v14 offset0:40 offset1:44
	ds_read2st64_b32 v[174:175], v14 offset0:48 offset1:52
	ds_read2st64_b32 v[176:177], v14 offset0:56 offset1:60
	ds_read2st64_b32 v[178:179], v14 offset0:64 offset1:68
	s_waitcnt vmcnt(11) lgkmcnt(9)
	v_pk_fma_f32 v[64:65], v[106:107], v[80:81], v[64:65] op_sel_hi:[1,0,1]
	v_pk_fma_f32 v[66:67], v[104:105], v[80:81], v[66:67] op_sel_hi:[1,0,1]
	v_pk_fma_f32 v[60:61], v[106:107], v[80:81], v[60:61] op_sel:[0,1,0]
	v_pk_fma_f32 v[62:63], v[104:105], v[80:81], v[62:63] op_sel:[0,1,0]
	v_pk_fma_f32 v[56:57], v[106:107], v[82:83], v[56:57] op_sel_hi:[1,0,1]
	v_pk_fma_f32 v[58:59], v[104:105], v[82:83], v[58:59] op_sel_hi:[1,0,1]
	v_pk_fma_f32 v[52:53], v[106:107], v[82:83], v[52:53] op_sel:[0,1,0]
	v_pk_fma_f32 v[54:55], v[104:105], v[82:83], v[54:55] op_sel:[0,1,0]
	v_pk_fma_f32 v[48:49], v[106:107], v[84:85], v[48:49] op_sel_hi:[1,0,1]
	v_pk_fma_f32 v[50:51], v[104:105], v[84:85], v[50:51] op_sel_hi:[1,0,1]
	v_pk_fma_f32 v[44:45], v[106:107], v[84:85], v[44:45] op_sel:[0,1,0]
	v_pk_fma_f32 v[46:47], v[104:105], v[84:85], v[46:47] op_sel:[0,1,0]
	v_pk_fma_f32 v[40:41], v[106:107], v[86:87], v[40:41] op_sel_hi:[1,0,1]
	v_pk_fma_f32 v[42:43], v[104:105], v[86:87], v[42:43] op_sel_hi:[1,0,1]
	v_pk_fma_f32 v[36:37], v[106:107], v[86:87], v[36:37] op_sel:[0,1,0]
	v_pk_fma_f32 v[38:39], v[104:105], v[86:87], v[38:39] op_sel:[0,1,0]
	v_pk_fma_f32 v[32:33], v[106:107], v[2:3], v[32:33] op_sel_hi:[1,0,1]
	v_pk_fma_f32 v[34:35], v[104:105], v[2:3], v[34:35] op_sel_hi:[1,0,1]
	v_pk_fma_f32 v[28:29], v[106:107], v[2:3], v[28:29] op_sel:[0,1,0]
	v_pk_fma_f32 v[30:31], v[104:105], v[2:3], v[30:31] op_sel:[0,1,0]
	v_pk_fma_f32 v[24:25], v[106:107], v[4:5], v[24:25] op_sel_hi:[1,0,1]
	v_pk_fma_f32 v[26:27], v[104:105], v[4:5], v[26:27] op_sel_hi:[1,0,1]
	v_pk_fma_f32 v[20:21], v[106:107], v[4:5], v[20:21] op_sel:[0,1,0]
	v_pk_fma_f32 v[22:23], v[104:105], v[4:5], v[22:23] op_sel:[0,1,0]
	v_pk_fma_f32 v[96:97], v[106:107], v[6:7], v[96:97] op_sel_hi:[1,0,1]
	v_pk_fma_f32 v[98:99], v[104:105], v[6:7], v[98:99] op_sel_hi:[1,0,1]
	v_pk_fma_f32 v[92:93], v[106:107], v[6:7], v[92:93] op_sel:[0,1,0]
	v_pk_fma_f32 v[94:95], v[104:105], v[6:7], v[94:95] op_sel:[0,1,0]
	v_pk_fma_f32 v[88:89], v[106:107], v[8:9], v[88:89] op_sel_hi:[1,0,1]
	v_pk_fma_f32 v[90:91], v[104:105], v[8:9], v[90:91] op_sel_hi:[1,0,1]
	v_pk_fma_f32 v[76:77], v[106:107], v[8:9], v[76:77] op_sel:[0,1,0]
	v_pk_fma_f32 v[78:79], v[104:105], v[8:9], v[78:79] op_sel:[0,1,0]
	v_pk_fma_f32 v[72:73], v[106:107], v[142:143], v[72:73] op_sel_hi:[1,0,1]
	v_pk_fma_f32 v[74:75], v[104:105], v[142:143], v[74:75] op_sel_hi:[1,0,1]
	v_pk_fma_f32 v[68:69], v[106:107], v[142:143], v[68:69] op_sel:[0,1,0]
	v_pk_fma_f32 v[70:71], v[104:105], v[142:143], v[70:71] op_sel:[0,1,0]
	v_lshl_add_u64 v[18:19], v[18:19], 0, s[14:15]
	global_load_dwordx4 v[104:107], v[18:19], off
	v_add_u32_e32 v14, 0x60, v128
	ds_read2st64_b32 v[80:81], v14 offset1:4
	ds_read2st64_b32 v[82:83], v14 offset0:8 offset1:12
	ds_read2st64_b32 v[84:85], v14 offset0:16 offset1:20
	ds_read2st64_b32 v[86:87], v14 offset0:24 offset1:28
	ds_read2st64_b32 v[2:3], v14 offset0:32 offset1:36
	ds_read2st64_b32 v[4:5], v14 offset0:40 offset1:44
	ds_read2st64_b32 v[6:7], v14 offset0:48 offset1:52
	ds_read2st64_b32 v[8:9], v14 offset0:56 offset1:60
	ds_read2st64_b32 v[142:143], v14 offset0:64 offset1:68
	s_waitcnt vmcnt(11) lgkmcnt(9)
	v_pk_fma_f32 v[64:65], v[110:111], v[162:163], v[64:65] op_sel_hi:[1,0,1]
	v_pk_fma_f32 v[66:67], v[108:109], v[162:163], v[66:67] op_sel_hi:[1,0,1]
	v_pk_fma_f32 v[60:61], v[110:111], v[162:163], v[60:61] op_sel:[0,1,0]
	v_pk_fma_f32 v[62:63], v[108:109], v[162:163], v[62:63] op_sel:[0,1,0]
	v_pk_fma_f32 v[56:57], v[110:111], v[164:165], v[56:57] op_sel_hi:[1,0,1]
	v_pk_fma_f32 v[58:59], v[108:109], v[164:165], v[58:59] op_sel_hi:[1,0,1]
	v_pk_fma_f32 v[52:53], v[110:111], v[164:165], v[52:53] op_sel:[0,1,0]
	v_pk_fma_f32 v[54:55], v[108:109], v[164:165], v[54:55] op_sel:[0,1,0]
	v_pk_fma_f32 v[48:49], v[110:111], v[166:167], v[48:49] op_sel_hi:[1,0,1]
	v_pk_fma_f32 v[50:51], v[108:109], v[166:167], v[50:51] op_sel_hi:[1,0,1]
	v_pk_fma_f32 v[44:45], v[110:111], v[166:167], v[44:45] op_sel:[0,1,0]
	v_pk_fma_f32 v[46:47], v[108:109], v[166:167], v[46:47] op_sel:[0,1,0]
	v_pk_fma_f32 v[40:41], v[110:111], v[168:169], v[40:41] op_sel_hi:[1,0,1]
	v_pk_fma_f32 v[42:43], v[108:109], v[168:169], v[42:43] op_sel_hi:[1,0,1]
	v_pk_fma_f32 v[36:37], v[110:111], v[168:169], v[36:37] op_sel:[0,1,0]
	v_pk_fma_f32 v[38:39], v[108:109], v[168:169], v[38:39] op_sel:[0,1,0]
	v_pk_fma_f32 v[32:33], v[110:111], v[170:171], v[32:33] op_sel_hi:[1,0,1]
	v_pk_fma_f32 v[34:35], v[108:109], v[170:171], v[34:35] op_sel_hi:[1,0,1]
	v_pk_fma_f32 v[28:29], v[110:111], v[170:171], v[28:29] op_sel:[0,1,0]
	v_pk_fma_f32 v[30:31], v[108:109], v[170:171], v[30:31] op_sel:[0,1,0]
	v_pk_fma_f32 v[24:25], v[110:111], v[172:173], v[24:25] op_sel_hi:[1,0,1]
	v_pk_fma_f32 v[26:27], v[108:109], v[172:173], v[26:27] op_sel_hi:[1,0,1]
	v_pk_fma_f32 v[20:21], v[110:111], v[172:173], v[20:21] op_sel:[0,1,0]
	v_pk_fma_f32 v[22:23], v[108:109], v[172:173], v[22:23] op_sel:[0,1,0]
	v_pk_fma_f32 v[96:97], v[110:111], v[174:175], v[96:97] op_sel_hi:[1,0,1]
	v_pk_fma_f32 v[98:99], v[108:109], v[174:175], v[98:99] op_sel_hi:[1,0,1]
	v_pk_fma_f32 v[92:93], v[110:111], v[174:175], v[92:93] op_sel:[0,1,0]
	v_pk_fma_f32 v[94:95], v[108:109], v[174:175], v[94:95] op_sel:[0,1,0]
	v_pk_fma_f32 v[88:89], v[110:111], v[176:177], v[88:89] op_sel_hi:[1,0,1]
	v_pk_fma_f32 v[90:91], v[108:109], v[176:177], v[90:91] op_sel_hi:[1,0,1]
	v_pk_fma_f32 v[76:77], v[110:111], v[176:177], v[76:77] op_sel:[0,1,0]
	v_pk_fma_f32 v[78:79], v[108:109], v[176:177], v[78:79] op_sel:[0,1,0]
	v_pk_fma_f32 v[72:73], v[110:111], v[178:179], v[72:73] op_sel_hi:[1,0,1]
	v_pk_fma_f32 v[74:75], v[108:109], v[178:179], v[74:75] op_sel_hi:[1,0,1]
	v_pk_fma_f32 v[68:69], v[110:111], v[178:179], v[68:69] op_sel:[0,1,0]
	v_pk_fma_f32 v[70:71], v[108:109], v[178:179], v[70:71] op_sel:[0,1,0]
	v_lshl_add_u64 v[18:19], v[18:19], 0, s[14:15]
	global_load_dwordx4 v[108:111], v[18:19], off
	v_add_u32_e32 v14, 0x80, v128
	ds_read2st64_b32 v[162:163], v14 offset1:4
	ds_read2st64_b32 v[164:165], v14 offset0:8 offset1:12
	ds_read2st64_b32 v[166:167], v14 offset0:16 offset1:20
	ds_read2st64_b32 v[168:169], v14 offset0:24 offset1:28
	ds_read2st64_b32 v[170:171], v14 offset0:32 offset1:36
	ds_read2st64_b32 v[172:173], v14 offset0:40 offset1:44
	ds_read2st64_b32 v[174:175], v14 offset0:48 offset1:52
	ds_read2st64_b32 v[176:177], v14 offset0:56 offset1:60
	ds_read2st64_b32 v[178:179], v14 offset0:64 offset1:68
	s_waitcnt vmcnt(11) lgkmcnt(9)
	v_pk_fma_f32 v[64:65], v[114:115], v[80:81], v[64:65] op_sel_hi:[1,0,1]
	v_pk_fma_f32 v[66:67], v[112:113], v[80:81], v[66:67] op_sel_hi:[1,0,1]
	v_pk_fma_f32 v[60:61], v[114:115], v[80:81], v[60:61] op_sel:[0,1,0]
	v_pk_fma_f32 v[62:63], v[112:113], v[80:81], v[62:63] op_sel:[0,1,0]
	v_pk_fma_f32 v[56:57], v[114:115], v[82:83], v[56:57] op_sel_hi:[1,0,1]
	v_pk_fma_f32 v[58:59], v[112:113], v[82:83], v[58:59] op_sel_hi:[1,0,1]
	v_pk_fma_f32 v[52:53], v[114:115], v[82:83], v[52:53] op_sel:[0,1,0]
	v_pk_fma_f32 v[54:55], v[112:113], v[82:83], v[54:55] op_sel:[0,1,0]
	v_pk_fma_f32 v[48:49], v[114:115], v[84:85], v[48:49] op_sel_hi:[1,0,1]
	v_pk_fma_f32 v[50:51], v[112:113], v[84:85], v[50:51] op_sel_hi:[1,0,1]
	v_pk_fma_f32 v[44:45], v[114:115], v[84:85], v[44:45] op_sel:[0,1,0]
	v_pk_fma_f32 v[46:47], v[112:113], v[84:85], v[46:47] op_sel:[0,1,0]
	v_pk_fma_f32 v[40:41], v[114:115], v[86:87], v[40:41] op_sel_hi:[1,0,1]
	v_pk_fma_f32 v[42:43], v[112:113], v[86:87], v[42:43] op_sel_hi:[1,0,1]
	v_pk_fma_f32 v[36:37], v[114:115], v[86:87], v[36:37] op_sel:[0,1,0]
	v_pk_fma_f32 v[38:39], v[112:113], v[86:87], v[38:39] op_sel:[0,1,0]
	v_pk_fma_f32 v[32:33], v[114:115], v[2:3], v[32:33] op_sel_hi:[1,0,1]
	v_pk_fma_f32 v[34:35], v[112:113], v[2:3], v[34:35] op_sel_hi:[1,0,1]
	v_pk_fma_f32 v[28:29], v[114:115], v[2:3], v[28:29] op_sel:[0,1,0]
	v_pk_fma_f32 v[30:31], v[112:113], v[2:3], v[30:31] op_sel:[0,1,0]
	v_pk_fma_f32 v[24:25], v[114:115], v[4:5], v[24:25] op_sel_hi:[1,0,1]
	v_pk_fma_f32 v[26:27], v[112:113], v[4:5], v[26:27] op_sel_hi:[1,0,1]
	v_pk_fma_f32 v[20:21], v[114:115], v[4:5], v[20:21] op_sel:[0,1,0]
	v_pk_fma_f32 v[22:23], v[112:113], v[4:5], v[22:23] op_sel:[0,1,0]
	v_pk_fma_f32 v[96:97], v[114:115], v[6:7], v[96:97] op_sel_hi:[1,0,1]
	v_pk_fma_f32 v[98:99], v[112:113], v[6:7], v[98:99] op_sel_hi:[1,0,1]
	v_pk_fma_f32 v[92:93], v[114:115], v[6:7], v[92:93] op_sel:[0,1,0]
	v_pk_fma_f32 v[94:95], v[112:113], v[6:7], v[94:95] op_sel:[0,1,0]
	v_pk_fma_f32 v[88:89], v[114:115], v[8:9], v[88:89] op_sel_hi:[1,0,1]
	v_pk_fma_f32 v[90:91], v[112:113], v[8:9], v[90:91] op_sel_hi:[1,0,1]
	v_pk_fma_f32 v[76:77], v[114:115], v[8:9], v[76:77] op_sel:[0,1,0]
	v_pk_fma_f32 v[78:79], v[112:113], v[8:9], v[78:79] op_sel:[0,1,0]
	v_pk_fma_f32 v[72:73], v[114:115], v[142:143], v[72:73] op_sel_hi:[1,0,1]
	v_pk_fma_f32 v[74:75], v[112:113], v[142:143], v[74:75] op_sel_hi:[1,0,1]
	v_pk_fma_f32 v[68:69], v[114:115], v[142:143], v[68:69] op_sel:[0,1,0]
	v_pk_fma_f32 v[70:71], v[112:113], v[142:143], v[70:71] op_sel:[0,1,0]
	v_lshl_add_u64 v[18:19], v[18:19], 0, s[14:15]
	global_load_dwordx4 v[112:115], v[18:19], off
	v_add_u32_e32 v14, 0xa0, v128
	ds_read2st64_b32 v[80:81], v14 offset1:4
	ds_read2st64_b32 v[82:83], v14 offset0:8 offset1:12
	ds_read2st64_b32 v[84:85], v14 offset0:16 offset1:20
	ds_read2st64_b32 v[86:87], v14 offset0:24 offset1:28
	ds_read2st64_b32 v[2:3], v14 offset0:32 offset1:36
	ds_read2st64_b32 v[4:5], v14 offset0:40 offset1:44
	ds_read2st64_b32 v[6:7], v14 offset0:48 offset1:52
	ds_read2st64_b32 v[8:9], v14 offset0:56 offset1:60
	ds_read2st64_b32 v[142:143], v14 offset0:64 offset1:68
	s_waitcnt vmcnt(11) lgkmcnt(9)
	v_pk_fma_f32 v[64:65], v[118:119], v[162:163], v[64:65] op_sel_hi:[1,0,1]
	v_pk_fma_f32 v[66:67], v[116:117], v[162:163], v[66:67] op_sel_hi:[1,0,1]
	v_pk_fma_f32 v[60:61], v[118:119], v[162:163], v[60:61] op_sel:[0,1,0]
	v_pk_fma_f32 v[62:63], v[116:117], v[162:163], v[62:63] op_sel:[0,1,0]
	v_pk_fma_f32 v[56:57], v[118:119], v[164:165], v[56:57] op_sel_hi:[1,0,1]
	v_pk_fma_f32 v[58:59], v[116:117], v[164:165], v[58:59] op_sel_hi:[1,0,1]
	v_pk_fma_f32 v[52:53], v[118:119], v[164:165], v[52:53] op_sel:[0,1,0]
	v_pk_fma_f32 v[54:55], v[116:117], v[164:165], v[54:55] op_sel:[0,1,0]
	v_pk_fma_f32 v[48:49], v[118:119], v[166:167], v[48:49] op_sel_hi:[1,0,1]
	v_pk_fma_f32 v[50:51], v[116:117], v[166:167], v[50:51] op_sel_hi:[1,0,1]
	v_pk_fma_f32 v[44:45], v[118:119], v[166:167], v[44:45] op_sel:[0,1,0]
	v_pk_fma_f32 v[46:47], v[116:117], v[166:167], v[46:47] op_sel:[0,1,0]
	v_pk_fma_f32 v[40:41], v[118:119], v[168:169], v[40:41] op_sel_hi:[1,0,1]
	v_pk_fma_f32 v[42:43], v[116:117], v[168:169], v[42:43] op_sel_hi:[1,0,1]
	v_pk_fma_f32 v[36:37], v[118:119], v[168:169], v[36:37] op_sel:[0,1,0]
	v_pk_fma_f32 v[38:39], v[116:117], v[168:169], v[38:39] op_sel:[0,1,0]
	v_pk_fma_f32 v[32:33], v[118:119], v[170:171], v[32:33] op_sel_hi:[1,0,1]
	v_pk_fma_f32 v[34:35], v[116:117], v[170:171], v[34:35] op_sel_hi:[1,0,1]
	v_pk_fma_f32 v[28:29], v[118:119], v[170:171], v[28:29] op_sel:[0,1,0]
	v_pk_fma_f32 v[30:31], v[116:117], v[170:171], v[30:31] op_sel:[0,1,0]
	v_pk_fma_f32 v[24:25], v[118:119], v[172:173], v[24:25] op_sel_hi:[1,0,1]
	v_pk_fma_f32 v[26:27], v[116:117], v[172:173], v[26:27] op_sel_hi:[1,0,1]
	v_pk_fma_f32 v[20:21], v[118:119], v[172:173], v[20:21] op_sel:[0,1,0]
	v_pk_fma_f32 v[22:23], v[116:117], v[172:173], v[22:23] op_sel:[0,1,0]
	v_pk_fma_f32 v[96:97], v[118:119], v[174:175], v[96:97] op_sel_hi:[1,0,1]
	v_pk_fma_f32 v[98:99], v[116:117], v[174:175], v[98:99] op_sel_hi:[1,0,1]
	v_pk_fma_f32 v[92:93], v[118:119], v[174:175], v[92:93] op_sel:[0,1,0]
	v_pk_fma_f32 v[94:95], v[116:117], v[174:175], v[94:95] op_sel:[0,1,0]
	v_pk_fma_f32 v[88:89], v[118:119], v[176:177], v[88:89] op_sel_hi:[1,0,1]
	v_pk_fma_f32 v[90:91], v[116:117], v[176:177], v[90:91] op_sel_hi:[1,0,1]
	v_pk_fma_f32 v[76:77], v[118:119], v[176:177], v[76:77] op_sel:[0,1,0]
	v_pk_fma_f32 v[78:79], v[116:117], v[176:177], v[78:79] op_sel:[0,1,0]
	v_pk_fma_f32 v[72:73], v[118:119], v[178:179], v[72:73] op_sel_hi:[1,0,1]
	v_pk_fma_f32 v[74:75], v[116:117], v[178:179], v[74:75] op_sel_hi:[1,0,1]
	v_pk_fma_f32 v[68:69], v[118:119], v[178:179], v[68:69] op_sel:[0,1,0]
	v_pk_fma_f32 v[70:71], v[116:117], v[178:179], v[70:71] op_sel:[0,1,0]
	v_lshl_add_u64 v[18:19], v[18:19], 0, s[14:15]
	global_load_dwordx4 v[116:119], v[18:19], off
	v_add_u32_e32 v14, 0xc0, v128
	ds_read2st64_b32 v[162:163], v14 offset1:4
	ds_read2st64_b32 v[164:165], v14 offset0:8 offset1:12
	ds_read2st64_b32 v[166:167], v14 offset0:16 offset1:20
	ds_read2st64_b32 v[168:169], v14 offset0:24 offset1:28
	ds_read2st64_b32 v[170:171], v14 offset0:32 offset1:36
	ds_read2st64_b32 v[172:173], v14 offset0:40 offset1:44
	ds_read2st64_b32 v[174:175], v14 offset0:48 offset1:52
	ds_read2st64_b32 v[176:177], v14 offset0:56 offset1:60
	ds_read2st64_b32 v[178:179], v14 offset0:64 offset1:68
	s_waitcnt vmcnt(11) lgkmcnt(9)
	v_pk_fma_f32 v[64:65], v[122:123], v[80:81], v[64:65] op_sel_hi:[1,0,1]
	v_pk_fma_f32 v[66:67], v[120:121], v[80:81], v[66:67] op_sel_hi:[1,0,1]
	v_pk_fma_f32 v[60:61], v[122:123], v[80:81], v[60:61] op_sel:[0,1,0]
	v_pk_fma_f32 v[62:63], v[120:121], v[80:81], v[62:63] op_sel:[0,1,0]
	v_pk_fma_f32 v[56:57], v[122:123], v[82:83], v[56:57] op_sel_hi:[1,0,1]
	v_pk_fma_f32 v[58:59], v[120:121], v[82:83], v[58:59] op_sel_hi:[1,0,1]
	v_pk_fma_f32 v[52:53], v[122:123], v[82:83], v[52:53] op_sel:[0,1,0]
	v_pk_fma_f32 v[54:55], v[120:121], v[82:83], v[54:55] op_sel:[0,1,0]
	v_pk_fma_f32 v[48:49], v[122:123], v[84:85], v[48:49] op_sel_hi:[1,0,1]
	v_pk_fma_f32 v[50:51], v[120:121], v[84:85], v[50:51] op_sel_hi:[1,0,1]
	v_pk_fma_f32 v[44:45], v[122:123], v[84:85], v[44:45] op_sel:[0,1,0]
	v_pk_fma_f32 v[46:47], v[120:121], v[84:85], v[46:47] op_sel:[0,1,0]
	v_pk_fma_f32 v[40:41], v[122:123], v[86:87], v[40:41] op_sel_hi:[1,0,1]
	v_pk_fma_f32 v[42:43], v[120:121], v[86:87], v[42:43] op_sel_hi:[1,0,1]
	v_pk_fma_f32 v[36:37], v[122:123], v[86:87], v[36:37] op_sel:[0,1,0]
	v_pk_fma_f32 v[38:39], v[120:121], v[86:87], v[38:39] op_sel:[0,1,0]
	v_pk_fma_f32 v[32:33], v[122:123], v[2:3], v[32:33] op_sel_hi:[1,0,1]
	v_pk_fma_f32 v[34:35], v[120:121], v[2:3], v[34:35] op_sel_hi:[1,0,1]
	v_pk_fma_f32 v[28:29], v[122:123], v[2:3], v[28:29] op_sel:[0,1,0]
	v_pk_fma_f32 v[30:31], v[120:121], v[2:3], v[30:31] op_sel:[0,1,0]
	v_pk_fma_f32 v[24:25], v[122:123], v[4:5], v[24:25] op_sel_hi:[1,0,1]
	v_pk_fma_f32 v[26:27], v[120:121], v[4:5], v[26:27] op_sel_hi:[1,0,1]
	v_pk_fma_f32 v[20:21], v[122:123], v[4:5], v[20:21] op_sel:[0,1,0]
	v_pk_fma_f32 v[22:23], v[120:121], v[4:5], v[22:23] op_sel:[0,1,0]
	v_pk_fma_f32 v[96:97], v[122:123], v[6:7], v[96:97] op_sel_hi:[1,0,1]
	v_pk_fma_f32 v[98:99], v[120:121], v[6:7], v[98:99] op_sel_hi:[1,0,1]
	v_pk_fma_f32 v[92:93], v[122:123], v[6:7], v[92:93] op_sel:[0,1,0]
	v_pk_fma_f32 v[94:95], v[120:121], v[6:7], v[94:95] op_sel:[0,1,0]
	v_pk_fma_f32 v[88:89], v[122:123], v[8:9], v[88:89] op_sel_hi:[1,0,1]
	v_pk_fma_f32 v[90:91], v[120:121], v[8:9], v[90:91] op_sel_hi:[1,0,1]
	v_pk_fma_f32 v[76:77], v[122:123], v[8:9], v[76:77] op_sel:[0,1,0]
	v_pk_fma_f32 v[78:79], v[120:121], v[8:9], v[78:79] op_sel:[0,1,0]
	v_pk_fma_f32 v[72:73], v[122:123], v[142:143], v[72:73] op_sel_hi:[1,0,1]
	v_pk_fma_f32 v[74:75], v[120:121], v[142:143], v[74:75] op_sel_hi:[1,0,1]
	v_pk_fma_f32 v[68:69], v[122:123], v[142:143], v[68:69] op_sel:[0,1,0]
	v_pk_fma_f32 v[70:71], v[120:121], v[142:143], v[70:71] op_sel:[0,1,0]
	v_lshl_add_u64 v[18:19], v[18:19], 0, s[14:15]
	global_load_dwordx4 v[120:123], v[18:19], off
	v_add_u32_e32 v14, 0xe0, v128
	ds_read2st64_b32 v[80:81], v14 offset1:4
	ds_read2st64_b32 v[82:83], v14 offset0:8 offset1:12
	ds_read2st64_b32 v[84:85], v14 offset0:16 offset1:20
	ds_read2st64_b32 v[86:87], v14 offset0:24 offset1:28
	ds_read2st64_b32 v[2:3], v14 offset0:32 offset1:36
	ds_read2st64_b32 v[4:5], v14 offset0:40 offset1:44
	ds_read2st64_b32 v[6:7], v14 offset0:48 offset1:52
	ds_read2st64_b32 v[8:9], v14 offset0:56 offset1:60
	ds_read2st64_b32 v[142:143], v14 offset0:64 offset1:68
	s_waitcnt vmcnt(11) lgkmcnt(9)
	v_pk_fma_f32 v[64:65], v[126:127], v[162:163], v[64:65] op_sel_hi:[1,0,1]
	v_pk_fma_f32 v[66:67], v[124:125], v[162:163], v[66:67] op_sel_hi:[1,0,1]
	v_pk_fma_f32 v[60:61], v[126:127], v[162:163], v[60:61] op_sel:[0,1,0]
	v_pk_fma_f32 v[62:63], v[124:125], v[162:163], v[62:63] op_sel:[0,1,0]
	v_pk_fma_f32 v[56:57], v[126:127], v[164:165], v[56:57] op_sel_hi:[1,0,1]
	v_pk_fma_f32 v[58:59], v[124:125], v[164:165], v[58:59] op_sel_hi:[1,0,1]
	v_pk_fma_f32 v[52:53], v[126:127], v[164:165], v[52:53] op_sel:[0,1,0]
	v_pk_fma_f32 v[54:55], v[124:125], v[164:165], v[54:55] op_sel:[0,1,0]
	v_pk_fma_f32 v[48:49], v[126:127], v[166:167], v[48:49] op_sel_hi:[1,0,1]
	v_pk_fma_f32 v[50:51], v[124:125], v[166:167], v[50:51] op_sel_hi:[1,0,1]
	v_pk_fma_f32 v[44:45], v[126:127], v[166:167], v[44:45] op_sel:[0,1,0]
	v_pk_fma_f32 v[46:47], v[124:125], v[166:167], v[46:47] op_sel:[0,1,0]
	v_pk_fma_f32 v[40:41], v[126:127], v[168:169], v[40:41] op_sel_hi:[1,0,1]
	v_pk_fma_f32 v[42:43], v[124:125], v[168:169], v[42:43] op_sel_hi:[1,0,1]
	v_pk_fma_f32 v[36:37], v[126:127], v[168:169], v[36:37] op_sel:[0,1,0]
	v_pk_fma_f32 v[38:39], v[124:125], v[168:169], v[38:39] op_sel:[0,1,0]
	v_pk_fma_f32 v[32:33], v[126:127], v[170:171], v[32:33] op_sel_hi:[1,0,1]
	v_pk_fma_f32 v[34:35], v[124:125], v[170:171], v[34:35] op_sel_hi:[1,0,1]
	v_pk_fma_f32 v[28:29], v[126:127], v[170:171], v[28:29] op_sel:[0,1,0]
	v_pk_fma_f32 v[30:31], v[124:125], v[170:171], v[30:31] op_sel:[0,1,0]
	v_pk_fma_f32 v[24:25], v[126:127], v[172:173], v[24:25] op_sel_hi:[1,0,1]
	v_pk_fma_f32 v[26:27], v[124:125], v[172:173], v[26:27] op_sel_hi:[1,0,1]
	v_pk_fma_f32 v[20:21], v[126:127], v[172:173], v[20:21] op_sel:[0,1,0]
	v_pk_fma_f32 v[22:23], v[124:125], v[172:173], v[22:23] op_sel:[0,1,0]
	v_pk_fma_f32 v[96:97], v[126:127], v[174:175], v[96:97] op_sel_hi:[1,0,1]
	v_pk_fma_f32 v[98:99], v[124:125], v[174:175], v[98:99] op_sel_hi:[1,0,1]
	v_pk_fma_f32 v[92:93], v[126:127], v[174:175], v[92:93] op_sel:[0,1,0]
	v_pk_fma_f32 v[94:95], v[124:125], v[174:175], v[94:95] op_sel:[0,1,0]
	v_pk_fma_f32 v[88:89], v[126:127], v[176:177], v[88:89] op_sel_hi:[1,0,1]
	v_pk_fma_f32 v[90:91], v[124:125], v[176:177], v[90:91] op_sel_hi:[1,0,1]
	v_pk_fma_f32 v[76:77], v[126:127], v[176:177], v[76:77] op_sel:[0,1,0]
	v_pk_fma_f32 v[78:79], v[124:125], v[176:177], v[78:79] op_sel:[0,1,0]
	v_pk_fma_f32 v[72:73], v[126:127], v[178:179], v[72:73] op_sel_hi:[1,0,1]
	v_pk_fma_f32 v[74:75], v[124:125], v[178:179], v[74:75] op_sel_hi:[1,0,1]
	v_pk_fma_f32 v[68:69], v[126:127], v[178:179], v[68:69] op_sel:[0,1,0]
	v_pk_fma_f32 v[70:71], v[124:125], v[178:179], v[70:71] op_sel:[0,1,0]
	v_lshl_add_u64 v[18:19], v[18:19], 0, s[14:15]
	global_load_dwordx4 v[124:127], v[18:19], off
	v_add_u32_e32 v14, 0x100, v128
	ds_read2st64_b32 v[162:163], v14 offset1:4
	ds_read2st64_b32 v[164:165], v14 offset0:8 offset1:12
	ds_read2st64_b32 v[166:167], v14 offset0:16 offset1:20
	ds_read2st64_b32 v[168:169], v14 offset0:24 offset1:28
	ds_read2st64_b32 v[170:171], v14 offset0:32 offset1:36
	ds_read2st64_b32 v[172:173], v14 offset0:40 offset1:44
	ds_read2st64_b32 v[174:175], v14 offset0:48 offset1:52
	ds_read2st64_b32 v[176:177], v14 offset0:56 offset1:60
	ds_read2st64_b32 v[178:179], v14 offset0:64 offset1:68
	s_waitcnt vmcnt(11) lgkmcnt(9)
	v_pk_fma_f32 v[64:65], v[132:133], v[80:81], v[64:65] op_sel_hi:[1,0,1]
	v_pk_fma_f32 v[66:67], v[130:131], v[80:81], v[66:67] op_sel_hi:[1,0,1]
	v_pk_fma_f32 v[60:61], v[132:133], v[80:81], v[60:61] op_sel:[0,1,0]
	v_pk_fma_f32 v[62:63], v[130:131], v[80:81], v[62:63] op_sel:[0,1,0]
	v_pk_fma_f32 v[56:57], v[132:133], v[82:83], v[56:57] op_sel_hi:[1,0,1]
	v_pk_fma_f32 v[58:59], v[130:131], v[82:83], v[58:59] op_sel_hi:[1,0,1]
	v_pk_fma_f32 v[52:53], v[132:133], v[82:83], v[52:53] op_sel:[0,1,0]
	v_pk_fma_f32 v[54:55], v[130:131], v[82:83], v[54:55] op_sel:[0,1,0]
	v_pk_fma_f32 v[48:49], v[132:133], v[84:85], v[48:49] op_sel_hi:[1,0,1]
	v_pk_fma_f32 v[50:51], v[130:131], v[84:85], v[50:51] op_sel_hi:[1,0,1]
	v_pk_fma_f32 v[44:45], v[132:133], v[84:85], v[44:45] op_sel:[0,1,0]
	v_pk_fma_f32 v[46:47], v[130:131], v[84:85], v[46:47] op_sel:[0,1,0]
	v_pk_fma_f32 v[40:41], v[132:133], v[86:87], v[40:41] op_sel_hi:[1,0,1]
	v_pk_fma_f32 v[42:43], v[130:131], v[86:87], v[42:43] op_sel_hi:[1,0,1]
	v_pk_fma_f32 v[36:37], v[132:133], v[86:87], v[36:37] op_sel:[0,1,0]
	v_pk_fma_f32 v[38:39], v[130:131], v[86:87], v[38:39] op_sel:[0,1,0]
	v_pk_fma_f32 v[32:33], v[132:133], v[2:3], v[32:33] op_sel_hi:[1,0,1]
	v_pk_fma_f32 v[34:35], v[130:131], v[2:3], v[34:35] op_sel_hi:[1,0,1]
	v_pk_fma_f32 v[28:29], v[132:133], v[2:3], v[28:29] op_sel:[0,1,0]
	v_pk_fma_f32 v[30:31], v[130:131], v[2:3], v[30:31] op_sel:[0,1,0]
	v_pk_fma_f32 v[24:25], v[132:133], v[4:5], v[24:25] op_sel_hi:[1,0,1]
	v_pk_fma_f32 v[26:27], v[130:131], v[4:5], v[26:27] op_sel_hi:[1,0,1]
	v_pk_fma_f32 v[20:21], v[132:133], v[4:5], v[20:21] op_sel:[0,1,0]
	v_pk_fma_f32 v[22:23], v[130:131], v[4:5], v[22:23] op_sel:[0,1,0]
	v_pk_fma_f32 v[96:97], v[132:133], v[6:7], v[96:97] op_sel_hi:[1,0,1]
	v_pk_fma_f32 v[98:99], v[130:131], v[6:7], v[98:99] op_sel_hi:[1,0,1]
	v_pk_fma_f32 v[92:93], v[132:133], v[6:7], v[92:93] op_sel:[0,1,0]
	v_pk_fma_f32 v[94:95], v[130:131], v[6:7], v[94:95] op_sel:[0,1,0]
	v_pk_fma_f32 v[88:89], v[132:133], v[8:9], v[88:89] op_sel_hi:[1,0,1]
	v_pk_fma_f32 v[90:91], v[130:131], v[8:9], v[90:91] op_sel_hi:[1,0,1]
	v_pk_fma_f32 v[76:77], v[132:133], v[8:9], v[76:77] op_sel:[0,1,0]
	v_pk_fma_f32 v[78:79], v[130:131], v[8:9], v[78:79] op_sel:[0,1,0]
	v_pk_fma_f32 v[72:73], v[132:133], v[142:143], v[72:73] op_sel_hi:[1,0,1]
	v_pk_fma_f32 v[74:75], v[130:131], v[142:143], v[74:75] op_sel_hi:[1,0,1]
	v_pk_fma_f32 v[68:69], v[132:133], v[142:143], v[68:69] op_sel:[0,1,0]
	v_pk_fma_f32 v[70:71], v[130:131], v[142:143], v[70:71] op_sel:[0,1,0]
	v_lshl_add_u64 v[18:19], v[18:19], 0, s[14:15]
	global_load_dwordx4 v[130:133], v[18:19], off
	v_add_u32_e32 v14, 0x120, v128
	ds_read2st64_b32 v[80:81], v14 offset1:4
	ds_read2st64_b32 v[82:83], v14 offset0:8 offset1:12
	ds_read2st64_b32 v[84:85], v14 offset0:16 offset1:20
	ds_read2st64_b32 v[86:87], v14 offset0:24 offset1:28
	ds_read2st64_b32 v[2:3], v14 offset0:32 offset1:36
	ds_read2st64_b32 v[4:5], v14 offset0:40 offset1:44
	ds_read2st64_b32 v[6:7], v14 offset0:48 offset1:52
	ds_read2st64_b32 v[8:9], v14 offset0:56 offset1:60
	ds_read2st64_b32 v[142:143], v14 offset0:64 offset1:68
	s_waitcnt vmcnt(11) lgkmcnt(9)
	v_pk_fma_f32 v[64:65], v[136:137], v[162:163], v[64:65] op_sel_hi:[1,0,1]
	v_pk_fma_f32 v[66:67], v[134:135], v[162:163], v[66:67] op_sel_hi:[1,0,1]
	v_pk_fma_f32 v[60:61], v[136:137], v[162:163], v[60:61] op_sel:[0,1,0]
	v_pk_fma_f32 v[62:63], v[134:135], v[162:163], v[62:63] op_sel:[0,1,0]
	v_pk_fma_f32 v[56:57], v[136:137], v[164:165], v[56:57] op_sel_hi:[1,0,1]
	v_pk_fma_f32 v[58:59], v[134:135], v[164:165], v[58:59] op_sel_hi:[1,0,1]
	v_pk_fma_f32 v[52:53], v[136:137], v[164:165], v[52:53] op_sel:[0,1,0]
	v_pk_fma_f32 v[54:55], v[134:135], v[164:165], v[54:55] op_sel:[0,1,0]
	v_pk_fma_f32 v[48:49], v[136:137], v[166:167], v[48:49] op_sel_hi:[1,0,1]
	v_pk_fma_f32 v[50:51], v[134:135], v[166:167], v[50:51] op_sel_hi:[1,0,1]
	v_pk_fma_f32 v[44:45], v[136:137], v[166:167], v[44:45] op_sel:[0,1,0]
	v_pk_fma_f32 v[46:47], v[134:135], v[166:167], v[46:47] op_sel:[0,1,0]
	v_pk_fma_f32 v[40:41], v[136:137], v[168:169], v[40:41] op_sel_hi:[1,0,1]
	v_pk_fma_f32 v[42:43], v[134:135], v[168:169], v[42:43] op_sel_hi:[1,0,1]
	v_pk_fma_f32 v[36:37], v[136:137], v[168:169], v[36:37] op_sel:[0,1,0]
	v_pk_fma_f32 v[38:39], v[134:135], v[168:169], v[38:39] op_sel:[0,1,0]
	v_pk_fma_f32 v[32:33], v[136:137], v[170:171], v[32:33] op_sel_hi:[1,0,1]
	v_pk_fma_f32 v[34:35], v[134:135], v[170:171], v[34:35] op_sel_hi:[1,0,1]
	v_pk_fma_f32 v[28:29], v[136:137], v[170:171], v[28:29] op_sel:[0,1,0]
	v_pk_fma_f32 v[30:31], v[134:135], v[170:171], v[30:31] op_sel:[0,1,0]
	v_pk_fma_f32 v[24:25], v[136:137], v[172:173], v[24:25] op_sel_hi:[1,0,1]
	v_pk_fma_f32 v[26:27], v[134:135], v[172:173], v[26:27] op_sel_hi:[1,0,1]
	v_pk_fma_f32 v[20:21], v[136:137], v[172:173], v[20:21] op_sel:[0,1,0]
	v_pk_fma_f32 v[22:23], v[134:135], v[172:173], v[22:23] op_sel:[0,1,0]
	v_pk_fma_f32 v[96:97], v[136:137], v[174:175], v[96:97] op_sel_hi:[1,0,1]
	v_pk_fma_f32 v[98:99], v[134:135], v[174:175], v[98:99] op_sel_hi:[1,0,1]
	v_pk_fma_f32 v[92:93], v[136:137], v[174:175], v[92:93] op_sel:[0,1,0]
	v_pk_fma_f32 v[94:95], v[134:135], v[174:175], v[94:95] op_sel:[0,1,0]
	v_pk_fma_f32 v[88:89], v[136:137], v[176:177], v[88:89] op_sel_hi:[1,0,1]
	v_pk_fma_f32 v[90:91], v[134:135], v[176:177], v[90:91] op_sel_hi:[1,0,1]
	v_pk_fma_f32 v[76:77], v[136:137], v[176:177], v[76:77] op_sel:[0,1,0]
	v_pk_fma_f32 v[78:79], v[134:135], v[176:177], v[78:79] op_sel:[0,1,0]
	v_pk_fma_f32 v[72:73], v[136:137], v[178:179], v[72:73] op_sel_hi:[1,0,1]
	v_pk_fma_f32 v[74:75], v[134:135], v[178:179], v[74:75] op_sel_hi:[1,0,1]
	v_pk_fma_f32 v[68:69], v[136:137], v[178:179], v[68:69] op_sel:[0,1,0]
	v_pk_fma_f32 v[70:71], v[134:135], v[178:179], v[70:71] op_sel:[0,1,0]
	v_lshl_add_u64 v[18:19], v[18:19], 0, s[14:15]
	global_load_dwordx4 v[134:137], v[18:19], off
	v_add_u32_e32 v14, 0x140, v128
	ds_read2st64_b32 v[162:163], v14 offset1:4
	ds_read2st64_b32 v[164:165], v14 offset0:8 offset1:12
	ds_read2st64_b32 v[166:167], v14 offset0:16 offset1:20
	ds_read2st64_b32 v[168:169], v14 offset0:24 offset1:28
	ds_read2st64_b32 v[170:171], v14 offset0:32 offset1:36
	ds_read2st64_b32 v[172:173], v14 offset0:40 offset1:44
	ds_read2st64_b32 v[174:175], v14 offset0:48 offset1:52
	ds_read2st64_b32 v[176:177], v14 offset0:56 offset1:60
	ds_read2st64_b32 v[178:179], v14 offset0:64 offset1:68
	s_waitcnt vmcnt(11) lgkmcnt(9)
	v_pk_fma_f32 v[64:65], v[140:141], v[80:81], v[64:65] op_sel_hi:[1,0,1]
	v_pk_fma_f32 v[66:67], v[138:139], v[80:81], v[66:67] op_sel_hi:[1,0,1]
	v_pk_fma_f32 v[60:61], v[140:141], v[80:81], v[60:61] op_sel:[0,1,0]
	v_pk_fma_f32 v[62:63], v[138:139], v[80:81], v[62:63] op_sel:[0,1,0]
	v_pk_fma_f32 v[56:57], v[140:141], v[82:83], v[56:57] op_sel_hi:[1,0,1]
	v_pk_fma_f32 v[58:59], v[138:139], v[82:83], v[58:59] op_sel_hi:[1,0,1]
	v_pk_fma_f32 v[52:53], v[140:141], v[82:83], v[52:53] op_sel:[0,1,0]
	v_pk_fma_f32 v[54:55], v[138:139], v[82:83], v[54:55] op_sel:[0,1,0]
	v_pk_fma_f32 v[48:49], v[140:141], v[84:85], v[48:49] op_sel_hi:[1,0,1]
	v_pk_fma_f32 v[50:51], v[138:139], v[84:85], v[50:51] op_sel_hi:[1,0,1]
	v_pk_fma_f32 v[44:45], v[140:141], v[84:85], v[44:45] op_sel:[0,1,0]
	v_pk_fma_f32 v[46:47], v[138:139], v[84:85], v[46:47] op_sel:[0,1,0]
	v_pk_fma_f32 v[40:41], v[140:141], v[86:87], v[40:41] op_sel_hi:[1,0,1]
	v_pk_fma_f32 v[42:43], v[138:139], v[86:87], v[42:43] op_sel_hi:[1,0,1]
	v_pk_fma_f32 v[36:37], v[140:141], v[86:87], v[36:37] op_sel:[0,1,0]
	v_pk_fma_f32 v[38:39], v[138:139], v[86:87], v[38:39] op_sel:[0,1,0]
	v_pk_fma_f32 v[32:33], v[140:141], v[2:3], v[32:33] op_sel_hi:[1,0,1]
	v_pk_fma_f32 v[34:35], v[138:139], v[2:3], v[34:35] op_sel_hi:[1,0,1]
	v_pk_fma_f32 v[28:29], v[140:141], v[2:3], v[28:29] op_sel:[0,1,0]
	v_pk_fma_f32 v[30:31], v[138:139], v[2:3], v[30:31] op_sel:[0,1,0]
	v_pk_fma_f32 v[24:25], v[140:141], v[4:5], v[24:25] op_sel_hi:[1,0,1]
	v_pk_fma_f32 v[26:27], v[138:139], v[4:5], v[26:27] op_sel_hi:[1,0,1]
	v_pk_fma_f32 v[20:21], v[140:141], v[4:5], v[20:21] op_sel:[0,1,0]
	v_pk_fma_f32 v[22:23], v[138:139], v[4:5], v[22:23] op_sel:[0,1,0]
	v_pk_fma_f32 v[96:97], v[140:141], v[6:7], v[96:97] op_sel_hi:[1,0,1]
	v_pk_fma_f32 v[98:99], v[138:139], v[6:7], v[98:99] op_sel_hi:[1,0,1]
	v_pk_fma_f32 v[92:93], v[140:141], v[6:7], v[92:93] op_sel:[0,1,0]
	v_pk_fma_f32 v[94:95], v[138:139], v[6:7], v[94:95] op_sel:[0,1,0]
	v_pk_fma_f32 v[88:89], v[140:141], v[8:9], v[88:89] op_sel_hi:[1,0,1]
	v_pk_fma_f32 v[90:91], v[138:139], v[8:9], v[90:91] op_sel_hi:[1,0,1]
	v_pk_fma_f32 v[76:77], v[140:141], v[8:9], v[76:77] op_sel:[0,1,0]
	v_pk_fma_f32 v[78:79], v[138:139], v[8:9], v[78:79] op_sel:[0,1,0]
	v_pk_fma_f32 v[72:73], v[140:141], v[142:143], v[72:73] op_sel_hi:[1,0,1]
	v_pk_fma_f32 v[74:75], v[138:139], v[142:143], v[74:75] op_sel_hi:[1,0,1]
	v_pk_fma_f32 v[68:69], v[140:141], v[142:143], v[68:69] op_sel:[0,1,0]
	v_pk_fma_f32 v[70:71], v[138:139], v[142:143], v[70:71] op_sel:[0,1,0]
	v_lshl_add_u64 v[18:19], v[18:19], 0, s[14:15]
	global_load_dwordx4 v[138:141], v[18:19], off
	v_add_u32_e32 v14, 0x160, v128
	ds_read2st64_b32 v[80:81], v14 offset1:4
	ds_read2st64_b32 v[82:83], v14 offset0:8 offset1:12
	ds_read2st64_b32 v[84:85], v14 offset0:16 offset1:20
	ds_read2st64_b32 v[86:87], v14 offset0:24 offset1:28
	ds_read2st64_b32 v[2:3], v14 offset0:32 offset1:36
	ds_read2st64_b32 v[4:5], v14 offset0:40 offset1:44
	ds_read2st64_b32 v[6:7], v14 offset0:48 offset1:52
	ds_read2st64_b32 v[8:9], v14 offset0:56 offset1:60
	ds_read2st64_b32 v[142:143], v14 offset0:64 offset1:68
	s_waitcnt vmcnt(11) lgkmcnt(9)
	v_pk_fma_f32 v[64:65], v[148:149], v[162:163], v[64:65] op_sel_hi:[1,0,1]
	v_pk_fma_f32 v[66:67], v[146:147], v[162:163], v[66:67] op_sel_hi:[1,0,1]
	v_pk_fma_f32 v[60:61], v[148:149], v[162:163], v[60:61] op_sel:[0,1,0]
	v_pk_fma_f32 v[62:63], v[146:147], v[162:163], v[62:63] op_sel:[0,1,0]
	v_pk_fma_f32 v[56:57], v[148:149], v[164:165], v[56:57] op_sel_hi:[1,0,1]
	v_pk_fma_f32 v[58:59], v[146:147], v[164:165], v[58:59] op_sel_hi:[1,0,1]
	v_pk_fma_f32 v[52:53], v[148:149], v[164:165], v[52:53] op_sel:[0,1,0]
	v_pk_fma_f32 v[54:55], v[146:147], v[164:165], v[54:55] op_sel:[0,1,0]
	v_pk_fma_f32 v[48:49], v[148:149], v[166:167], v[48:49] op_sel_hi:[1,0,1]
	v_pk_fma_f32 v[50:51], v[146:147], v[166:167], v[50:51] op_sel_hi:[1,0,1]
	v_pk_fma_f32 v[44:45], v[148:149], v[166:167], v[44:45] op_sel:[0,1,0]
	v_pk_fma_f32 v[46:47], v[146:147], v[166:167], v[46:47] op_sel:[0,1,0]
	v_pk_fma_f32 v[40:41], v[148:149], v[168:169], v[40:41] op_sel_hi:[1,0,1]
	v_pk_fma_f32 v[42:43], v[146:147], v[168:169], v[42:43] op_sel_hi:[1,0,1]
	v_pk_fma_f32 v[36:37], v[148:149], v[168:169], v[36:37] op_sel:[0,1,0]
	v_pk_fma_f32 v[38:39], v[146:147], v[168:169], v[38:39] op_sel:[0,1,0]
	v_pk_fma_f32 v[32:33], v[148:149], v[170:171], v[32:33] op_sel_hi:[1,0,1]
	v_pk_fma_f32 v[34:35], v[146:147], v[170:171], v[34:35] op_sel_hi:[1,0,1]
	v_pk_fma_f32 v[28:29], v[148:149], v[170:171], v[28:29] op_sel:[0,1,0]
	v_pk_fma_f32 v[30:31], v[146:147], v[170:171], v[30:31] op_sel:[0,1,0]
	v_pk_fma_f32 v[24:25], v[148:149], v[172:173], v[24:25] op_sel_hi:[1,0,1]
	v_pk_fma_f32 v[26:27], v[146:147], v[172:173], v[26:27] op_sel_hi:[1,0,1]
	v_pk_fma_f32 v[20:21], v[148:149], v[172:173], v[20:21] op_sel:[0,1,0]
	v_pk_fma_f32 v[22:23], v[146:147], v[172:173], v[22:23] op_sel:[0,1,0]
	v_pk_fma_f32 v[96:97], v[148:149], v[174:175], v[96:97] op_sel_hi:[1,0,1]
	v_pk_fma_f32 v[98:99], v[146:147], v[174:175], v[98:99] op_sel_hi:[1,0,1]
	v_pk_fma_f32 v[92:93], v[148:149], v[174:175], v[92:93] op_sel:[0,1,0]
	v_pk_fma_f32 v[94:95], v[146:147], v[174:175], v[94:95] op_sel:[0,1,0]
	v_pk_fma_f32 v[88:89], v[148:149], v[176:177], v[88:89] op_sel_hi:[1,0,1]
	v_pk_fma_f32 v[90:91], v[146:147], v[176:177], v[90:91] op_sel_hi:[1,0,1]
	v_pk_fma_f32 v[76:77], v[148:149], v[176:177], v[76:77] op_sel:[0,1,0]
	v_pk_fma_f32 v[78:79], v[146:147], v[176:177], v[78:79] op_sel:[0,1,0]
	v_pk_fma_f32 v[72:73], v[148:149], v[178:179], v[72:73] op_sel_hi:[1,0,1]
	v_pk_fma_f32 v[74:75], v[146:147], v[178:179], v[74:75] op_sel_hi:[1,0,1]
	v_pk_fma_f32 v[68:69], v[148:149], v[178:179], v[68:69] op_sel:[0,1,0]
	v_pk_fma_f32 v[70:71], v[146:147], v[178:179], v[70:71] op_sel:[0,1,0]
	v_lshl_add_u64 v[18:19], v[18:19], 0, s[14:15]
	global_load_dwordx4 v[146:149], v[18:19], off
	v_add_u32_e32 v14, 0x180, v128
	ds_read2st64_b32 v[162:163], v14 offset1:4
	ds_read2st64_b32 v[164:165], v14 offset0:8 offset1:12
	ds_read2st64_b32 v[166:167], v14 offset0:16 offset1:20
	ds_read2st64_b32 v[168:169], v14 offset0:24 offset1:28
	ds_read2st64_b32 v[170:171], v14 offset0:32 offset1:36
	ds_read2st64_b32 v[172:173], v14 offset0:40 offset1:44
	ds_read2st64_b32 v[174:175], v14 offset0:48 offset1:52
	ds_read2st64_b32 v[176:177], v14 offset0:56 offset1:60
	ds_read2st64_b32 v[178:179], v14 offset0:64 offset1:68
	s_waitcnt vmcnt(11) lgkmcnt(9)
	v_pk_fma_f32 v[64:65], v[152:153], v[80:81], v[64:65] op_sel_hi:[1,0,1]
	v_pk_fma_f32 v[66:67], v[150:151], v[80:81], v[66:67] op_sel_hi:[1,0,1]
	v_pk_fma_f32 v[60:61], v[152:153], v[80:81], v[60:61] op_sel:[0,1,0]
	v_pk_fma_f32 v[62:63], v[150:151], v[80:81], v[62:63] op_sel:[0,1,0]
	v_pk_fma_f32 v[56:57], v[152:153], v[82:83], v[56:57] op_sel_hi:[1,0,1]
	v_pk_fma_f32 v[58:59], v[150:151], v[82:83], v[58:59] op_sel_hi:[1,0,1]
	v_pk_fma_f32 v[52:53], v[152:153], v[82:83], v[52:53] op_sel:[0,1,0]
	v_pk_fma_f32 v[54:55], v[150:151], v[82:83], v[54:55] op_sel:[0,1,0]
	v_pk_fma_f32 v[48:49], v[152:153], v[84:85], v[48:49] op_sel_hi:[1,0,1]
	v_pk_fma_f32 v[50:51], v[150:151], v[84:85], v[50:51] op_sel_hi:[1,0,1]
	v_pk_fma_f32 v[44:45], v[152:153], v[84:85], v[44:45] op_sel:[0,1,0]
	v_pk_fma_f32 v[46:47], v[150:151], v[84:85], v[46:47] op_sel:[0,1,0]
	v_pk_fma_f32 v[40:41], v[152:153], v[86:87], v[40:41] op_sel_hi:[1,0,1]
	v_pk_fma_f32 v[42:43], v[150:151], v[86:87], v[42:43] op_sel_hi:[1,0,1]
	v_pk_fma_f32 v[36:37], v[152:153], v[86:87], v[36:37] op_sel:[0,1,0]
	v_pk_fma_f32 v[38:39], v[150:151], v[86:87], v[38:39] op_sel:[0,1,0]
	v_pk_fma_f32 v[32:33], v[152:153], v[2:3], v[32:33] op_sel_hi:[1,0,1]
	v_pk_fma_f32 v[34:35], v[150:151], v[2:3], v[34:35] op_sel_hi:[1,0,1]
	v_pk_fma_f32 v[28:29], v[152:153], v[2:3], v[28:29] op_sel:[0,1,0]
	v_pk_fma_f32 v[30:31], v[150:151], v[2:3], v[30:31] op_sel:[0,1,0]
	v_pk_fma_f32 v[24:25], v[152:153], v[4:5], v[24:25] op_sel_hi:[1,0,1]
	v_pk_fma_f32 v[26:27], v[150:151], v[4:5], v[26:27] op_sel_hi:[1,0,1]
	v_pk_fma_f32 v[20:21], v[152:153], v[4:5], v[20:21] op_sel:[0,1,0]
	v_pk_fma_f32 v[22:23], v[150:151], v[4:5], v[22:23] op_sel:[0,1,0]
	v_pk_fma_f32 v[96:97], v[152:153], v[6:7], v[96:97] op_sel_hi:[1,0,1]
	v_pk_fma_f32 v[98:99], v[150:151], v[6:7], v[98:99] op_sel_hi:[1,0,1]
	v_pk_fma_f32 v[92:93], v[152:153], v[6:7], v[92:93] op_sel:[0,1,0]
	v_pk_fma_f32 v[94:95], v[150:151], v[6:7], v[94:95] op_sel:[0,1,0]
	v_pk_fma_f32 v[88:89], v[152:153], v[8:9], v[88:89] op_sel_hi:[1,0,1]
	v_pk_fma_f32 v[90:91], v[150:151], v[8:9], v[90:91] op_sel_hi:[1,0,1]
	v_pk_fma_f32 v[76:77], v[152:153], v[8:9], v[76:77] op_sel:[0,1,0]
	v_pk_fma_f32 v[78:79], v[150:151], v[8:9], v[78:79] op_sel:[0,1,0]
	v_pk_fma_f32 v[72:73], v[152:153], v[142:143], v[72:73] op_sel_hi:[1,0,1]
	v_pk_fma_f32 v[74:75], v[150:151], v[142:143], v[74:75] op_sel_hi:[1,0,1]
	v_pk_fma_f32 v[68:69], v[152:153], v[142:143], v[68:69] op_sel:[0,1,0]
	v_pk_fma_f32 v[70:71], v[150:151], v[142:143], v[70:71] op_sel:[0,1,0]
	v_lshl_add_u64 v[18:19], v[18:19], 0, s[14:15]
	global_load_dwordx4 v[150:153], v[18:19], off
	v_add_u32_e32 v14, 0x1a0, v128
	ds_read2st64_b32 v[80:81], v14 offset1:4
	ds_read2st64_b32 v[82:83], v14 offset0:8 offset1:12
	ds_read2st64_b32 v[84:85], v14 offset0:16 offset1:20
	ds_read2st64_b32 v[86:87], v14 offset0:24 offset1:28
	ds_read2st64_b32 v[2:3], v14 offset0:32 offset1:36
	ds_read2st64_b32 v[4:5], v14 offset0:40 offset1:44
	ds_read2st64_b32 v[6:7], v14 offset0:48 offset1:52
	ds_read2st64_b32 v[8:9], v14 offset0:56 offset1:60
	ds_read2st64_b32 v[142:143], v14 offset0:64 offset1:68
	s_waitcnt vmcnt(11) lgkmcnt(9)
	v_pk_fma_f32 v[64:65], v[102:103], v[162:163], v[64:65] op_sel_hi:[1,0,1]
	v_pk_fma_f32 v[66:67], v[100:101], v[162:163], v[66:67] op_sel_hi:[1,0,1]
	v_pk_fma_f32 v[60:61], v[102:103], v[162:163], v[60:61] op_sel:[0,1,0]
	v_pk_fma_f32 v[62:63], v[100:101], v[162:163], v[62:63] op_sel:[0,1,0]
	v_pk_fma_f32 v[56:57], v[102:103], v[164:165], v[56:57] op_sel_hi:[1,0,1]
	v_pk_fma_f32 v[58:59], v[100:101], v[164:165], v[58:59] op_sel_hi:[1,0,1]
	v_pk_fma_f32 v[52:53], v[102:103], v[164:165], v[52:53] op_sel:[0,1,0]
	v_pk_fma_f32 v[54:55], v[100:101], v[164:165], v[54:55] op_sel:[0,1,0]
	v_pk_fma_f32 v[48:49], v[102:103], v[166:167], v[48:49] op_sel_hi:[1,0,1]
	v_pk_fma_f32 v[50:51], v[100:101], v[166:167], v[50:51] op_sel_hi:[1,0,1]
	v_pk_fma_f32 v[44:45], v[102:103], v[166:167], v[44:45] op_sel:[0,1,0]
	v_pk_fma_f32 v[46:47], v[100:101], v[166:167], v[46:47] op_sel:[0,1,0]
	v_pk_fma_f32 v[40:41], v[102:103], v[168:169], v[40:41] op_sel_hi:[1,0,1]
	v_pk_fma_f32 v[42:43], v[100:101], v[168:169], v[42:43] op_sel_hi:[1,0,1]
	v_pk_fma_f32 v[36:37], v[102:103], v[168:169], v[36:37] op_sel:[0,1,0]
	v_pk_fma_f32 v[38:39], v[100:101], v[168:169], v[38:39] op_sel:[0,1,0]
	v_pk_fma_f32 v[32:33], v[102:103], v[170:171], v[32:33] op_sel_hi:[1,0,1]
	v_pk_fma_f32 v[34:35], v[100:101], v[170:171], v[34:35] op_sel_hi:[1,0,1]
	v_pk_fma_f32 v[28:29], v[102:103], v[170:171], v[28:29] op_sel:[0,1,0]
	v_pk_fma_f32 v[30:31], v[100:101], v[170:171], v[30:31] op_sel:[0,1,0]
	v_pk_fma_f32 v[24:25], v[102:103], v[172:173], v[24:25] op_sel_hi:[1,0,1]
	v_pk_fma_f32 v[26:27], v[100:101], v[172:173], v[26:27] op_sel_hi:[1,0,1]
	v_pk_fma_f32 v[20:21], v[102:103], v[172:173], v[20:21] op_sel:[0,1,0]
	v_pk_fma_f32 v[22:23], v[100:101], v[172:173], v[22:23] op_sel:[0,1,0]
	v_pk_fma_f32 v[96:97], v[102:103], v[174:175], v[96:97] op_sel_hi:[1,0,1]
	v_pk_fma_f32 v[98:99], v[100:101], v[174:175], v[98:99] op_sel_hi:[1,0,1]
	v_pk_fma_f32 v[92:93], v[102:103], v[174:175], v[92:93] op_sel:[0,1,0]
	v_pk_fma_f32 v[94:95], v[100:101], v[174:175], v[94:95] op_sel:[0,1,0]
	v_pk_fma_f32 v[88:89], v[102:103], v[176:177], v[88:89] op_sel_hi:[1,0,1]
	v_pk_fma_f32 v[90:91], v[100:101], v[176:177], v[90:91] op_sel_hi:[1,0,1]
	v_pk_fma_f32 v[76:77], v[102:103], v[176:177], v[76:77] op_sel:[0,1,0]
	v_pk_fma_f32 v[78:79], v[100:101], v[176:177], v[78:79] op_sel:[0,1,0]
	v_pk_fma_f32 v[72:73], v[102:103], v[178:179], v[72:73] op_sel_hi:[1,0,1]
	v_pk_fma_f32 v[74:75], v[100:101], v[178:179], v[74:75] op_sel_hi:[1,0,1]
	v_pk_fma_f32 v[68:69], v[102:103], v[178:179], v[68:69] op_sel:[0,1,0]
	v_pk_fma_f32 v[70:71], v[100:101], v[178:179], v[70:71] op_sel:[0,1,0]
	v_lshl_add_u64 v[18:19], v[18:19], 0, s[14:15]
	global_load_dwordx4 v[100:103], v[18:19], off
	v_add_u32_e32 v14, 0x1c0, v128
	ds_read2st64_b32 v[162:163], v14 offset1:4
	ds_read2st64_b32 v[164:165], v14 offset0:8 offset1:12
	ds_read2st64_b32 v[166:167], v14 offset0:16 offset1:20
	ds_read2st64_b32 v[168:169], v14 offset0:24 offset1:28
	ds_read2st64_b32 v[170:171], v14 offset0:32 offset1:36
	ds_read2st64_b32 v[172:173], v14 offset0:40 offset1:44
	ds_read2st64_b32 v[174:175], v14 offset0:48 offset1:52
	ds_read2st64_b32 v[176:177], v14 offset0:56 offset1:60
	ds_read2st64_b32 v[178:179], v14 offset0:64 offset1:68
	s_waitcnt vmcnt(11) lgkmcnt(9)
	v_pk_fma_f32 v[64:65], v[106:107], v[80:81], v[64:65] op_sel_hi:[1,0,1]
	v_pk_fma_f32 v[66:67], v[104:105], v[80:81], v[66:67] op_sel_hi:[1,0,1]
	v_pk_fma_f32 v[60:61], v[106:107], v[80:81], v[60:61] op_sel:[0,1,0]
	v_pk_fma_f32 v[62:63], v[104:105], v[80:81], v[62:63] op_sel:[0,1,0]
	v_pk_fma_f32 v[56:57], v[106:107], v[82:83], v[56:57] op_sel_hi:[1,0,1]
	v_pk_fma_f32 v[58:59], v[104:105], v[82:83], v[58:59] op_sel_hi:[1,0,1]
	v_pk_fma_f32 v[52:53], v[106:107], v[82:83], v[52:53] op_sel:[0,1,0]
	v_pk_fma_f32 v[54:55], v[104:105], v[82:83], v[54:55] op_sel:[0,1,0]
	v_pk_fma_f32 v[48:49], v[106:107], v[84:85], v[48:49] op_sel_hi:[1,0,1]
	v_pk_fma_f32 v[50:51], v[104:105], v[84:85], v[50:51] op_sel_hi:[1,0,1]
	v_pk_fma_f32 v[44:45], v[106:107], v[84:85], v[44:45] op_sel:[0,1,0]
	v_pk_fma_f32 v[46:47], v[104:105], v[84:85], v[46:47] op_sel:[0,1,0]
	v_pk_fma_f32 v[40:41], v[106:107], v[86:87], v[40:41] op_sel_hi:[1,0,1]
	v_pk_fma_f32 v[42:43], v[104:105], v[86:87], v[42:43] op_sel_hi:[1,0,1]
	v_pk_fma_f32 v[36:37], v[106:107], v[86:87], v[36:37] op_sel:[0,1,0]
	v_pk_fma_f32 v[38:39], v[104:105], v[86:87], v[38:39] op_sel:[0,1,0]
	v_pk_fma_f32 v[32:33], v[106:107], v[2:3], v[32:33] op_sel_hi:[1,0,1]
	v_pk_fma_f32 v[34:35], v[104:105], v[2:3], v[34:35] op_sel_hi:[1,0,1]
	v_pk_fma_f32 v[28:29], v[106:107], v[2:3], v[28:29] op_sel:[0,1,0]
	v_pk_fma_f32 v[30:31], v[104:105], v[2:3], v[30:31] op_sel:[0,1,0]
	v_pk_fma_f32 v[24:25], v[106:107], v[4:5], v[24:25] op_sel_hi:[1,0,1]
	v_pk_fma_f32 v[26:27], v[104:105], v[4:5], v[26:27] op_sel_hi:[1,0,1]
	v_pk_fma_f32 v[20:21], v[106:107], v[4:5], v[20:21] op_sel:[0,1,0]
	v_pk_fma_f32 v[22:23], v[104:105], v[4:5], v[22:23] op_sel:[0,1,0]
	v_pk_fma_f32 v[96:97], v[106:107], v[6:7], v[96:97] op_sel_hi:[1,0,1]
	v_pk_fma_f32 v[98:99], v[104:105], v[6:7], v[98:99] op_sel_hi:[1,0,1]
	v_pk_fma_f32 v[92:93], v[106:107], v[6:7], v[92:93] op_sel:[0,1,0]
	v_pk_fma_f32 v[94:95], v[104:105], v[6:7], v[94:95] op_sel:[0,1,0]
	v_pk_fma_f32 v[88:89], v[106:107], v[8:9], v[88:89] op_sel_hi:[1,0,1]
	v_pk_fma_f32 v[90:91], v[104:105], v[8:9], v[90:91] op_sel_hi:[1,0,1]
	v_pk_fma_f32 v[76:77], v[106:107], v[8:9], v[76:77] op_sel:[0,1,0]
	v_pk_fma_f32 v[78:79], v[104:105], v[8:9], v[78:79] op_sel:[0,1,0]
	v_pk_fma_f32 v[72:73], v[106:107], v[142:143], v[72:73] op_sel_hi:[1,0,1]
	v_pk_fma_f32 v[74:75], v[104:105], v[142:143], v[74:75] op_sel_hi:[1,0,1]
	v_pk_fma_f32 v[68:69], v[106:107], v[142:143], v[68:69] op_sel:[0,1,0]
	v_pk_fma_f32 v[70:71], v[104:105], v[142:143], v[70:71] op_sel:[0,1,0]
	v_lshl_add_u64 v[18:19], v[18:19], 0, s[14:15]
	global_load_dwordx4 v[104:107], v[18:19], off
	v_add_u32_e32 v14, 0x1e0, v128
	ds_read2st64_b32 v[80:81], v14 offset1:4
	ds_read2st64_b32 v[82:83], v14 offset0:8 offset1:12
	ds_read2st64_b32 v[84:85], v14 offset0:16 offset1:20
	ds_read2st64_b32 v[86:87], v14 offset0:24 offset1:28
	ds_read2st64_b32 v[2:3], v14 offset0:32 offset1:36
	ds_read2st64_b32 v[4:5], v14 offset0:40 offset1:44
	ds_read2st64_b32 v[6:7], v14 offset0:48 offset1:52
	ds_read2st64_b32 v[8:9], v14 offset0:56 offset1:60
	ds_read2st64_b32 v[142:143], v14 offset0:64 offset1:68
	s_waitcnt vmcnt(11) lgkmcnt(9)
	v_pk_fma_f32 v[64:65], v[110:111], v[162:163], v[64:65] op_sel_hi:[1,0,1]
	v_pk_fma_f32 v[66:67], v[108:109], v[162:163], v[66:67] op_sel_hi:[1,0,1]
	v_pk_fma_f32 v[60:61], v[110:111], v[162:163], v[60:61] op_sel:[0,1,0]
	v_pk_fma_f32 v[62:63], v[108:109], v[162:163], v[62:63] op_sel:[0,1,0]
	v_pk_fma_f32 v[56:57], v[110:111], v[164:165], v[56:57] op_sel_hi:[1,0,1]
	v_pk_fma_f32 v[58:59], v[108:109], v[164:165], v[58:59] op_sel_hi:[1,0,1]
	v_pk_fma_f32 v[52:53], v[110:111], v[164:165], v[52:53] op_sel:[0,1,0]
	v_pk_fma_f32 v[54:55], v[108:109], v[164:165], v[54:55] op_sel:[0,1,0]
	v_pk_fma_f32 v[48:49], v[110:111], v[166:167], v[48:49] op_sel_hi:[1,0,1]
	v_pk_fma_f32 v[50:51], v[108:109], v[166:167], v[50:51] op_sel_hi:[1,0,1]
	v_pk_fma_f32 v[44:45], v[110:111], v[166:167], v[44:45] op_sel:[0,1,0]
	v_pk_fma_f32 v[46:47], v[108:109], v[166:167], v[46:47] op_sel:[0,1,0]
	v_pk_fma_f32 v[40:41], v[110:111], v[168:169], v[40:41] op_sel_hi:[1,0,1]
	v_pk_fma_f32 v[42:43], v[108:109], v[168:169], v[42:43] op_sel_hi:[1,0,1]
	v_pk_fma_f32 v[36:37], v[110:111], v[168:169], v[36:37] op_sel:[0,1,0]
	v_pk_fma_f32 v[38:39], v[108:109], v[168:169], v[38:39] op_sel:[0,1,0]
	v_pk_fma_f32 v[32:33], v[110:111], v[170:171], v[32:33] op_sel_hi:[1,0,1]
	v_pk_fma_f32 v[34:35], v[108:109], v[170:171], v[34:35] op_sel_hi:[1,0,1]
	v_pk_fma_f32 v[28:29], v[110:111], v[170:171], v[28:29] op_sel:[0,1,0]
	v_pk_fma_f32 v[30:31], v[108:109], v[170:171], v[30:31] op_sel:[0,1,0]
	v_pk_fma_f32 v[24:25], v[110:111], v[172:173], v[24:25] op_sel_hi:[1,0,1]
	v_pk_fma_f32 v[26:27], v[108:109], v[172:173], v[26:27] op_sel_hi:[1,0,1]
	v_pk_fma_f32 v[20:21], v[110:111], v[172:173], v[20:21] op_sel:[0,1,0]
	v_pk_fma_f32 v[22:23], v[108:109], v[172:173], v[22:23] op_sel:[0,1,0]
	v_pk_fma_f32 v[96:97], v[110:111], v[174:175], v[96:97] op_sel_hi:[1,0,1]
	v_pk_fma_f32 v[98:99], v[108:109], v[174:175], v[98:99] op_sel_hi:[1,0,1]
	v_pk_fma_f32 v[92:93], v[110:111], v[174:175], v[92:93] op_sel:[0,1,0]
	v_pk_fma_f32 v[94:95], v[108:109], v[174:175], v[94:95] op_sel:[0,1,0]
	v_pk_fma_f32 v[88:89], v[110:111], v[176:177], v[88:89] op_sel_hi:[1,0,1]
	v_pk_fma_f32 v[90:91], v[108:109], v[176:177], v[90:91] op_sel_hi:[1,0,1]
	v_pk_fma_f32 v[76:77], v[110:111], v[176:177], v[76:77] op_sel:[0,1,0]
	v_pk_fma_f32 v[78:79], v[108:109], v[176:177], v[78:79] op_sel:[0,1,0]
	v_pk_fma_f32 v[72:73], v[110:111], v[178:179], v[72:73] op_sel_hi:[1,0,1]
	v_pk_fma_f32 v[74:75], v[108:109], v[178:179], v[74:75] op_sel_hi:[1,0,1]
	v_pk_fma_f32 v[68:69], v[110:111], v[178:179], v[68:69] op_sel:[0,1,0]
	v_pk_fma_f32 v[70:71], v[108:109], v[178:179], v[70:71] op_sel:[0,1,0]
	v_lshl_add_u64 v[18:19], v[18:19], 0, s[14:15]
	global_load_dwordx4 v[108:111], v[18:19], off
	v_add_u32_e32 v14, 0x200, v128
	ds_read2st64_b32 v[162:163], v14 offset1:4
	ds_read2st64_b32 v[164:165], v14 offset0:8 offset1:12
	ds_read2st64_b32 v[166:167], v14 offset0:16 offset1:20
	ds_read2st64_b32 v[168:169], v14 offset0:24 offset1:28
	ds_read2st64_b32 v[170:171], v14 offset0:32 offset1:36
	ds_read2st64_b32 v[172:173], v14 offset0:40 offset1:44
	ds_read2st64_b32 v[174:175], v14 offset0:48 offset1:52
	ds_read2st64_b32 v[176:177], v14 offset0:56 offset1:60
	ds_read2st64_b32 v[178:179], v14 offset0:64 offset1:68
	s_waitcnt vmcnt(11) lgkmcnt(9)
	v_pk_fma_f32 v[64:65], v[114:115], v[80:81], v[64:65] op_sel_hi:[1,0,1]
	v_pk_fma_f32 v[66:67], v[112:113], v[80:81], v[66:67] op_sel_hi:[1,0,1]
	v_pk_fma_f32 v[60:61], v[114:115], v[80:81], v[60:61] op_sel:[0,1,0]
	v_pk_fma_f32 v[62:63], v[112:113], v[80:81], v[62:63] op_sel:[0,1,0]
	v_pk_fma_f32 v[56:57], v[114:115], v[82:83], v[56:57] op_sel_hi:[1,0,1]
	v_pk_fma_f32 v[58:59], v[112:113], v[82:83], v[58:59] op_sel_hi:[1,0,1]
	v_pk_fma_f32 v[52:53], v[114:115], v[82:83], v[52:53] op_sel:[0,1,0]
	v_pk_fma_f32 v[54:55], v[112:113], v[82:83], v[54:55] op_sel:[0,1,0]
	v_pk_fma_f32 v[48:49], v[114:115], v[84:85], v[48:49] op_sel_hi:[1,0,1]
	v_pk_fma_f32 v[50:51], v[112:113], v[84:85], v[50:51] op_sel_hi:[1,0,1]
	v_pk_fma_f32 v[44:45], v[114:115], v[84:85], v[44:45] op_sel:[0,1,0]
	v_pk_fma_f32 v[46:47], v[112:113], v[84:85], v[46:47] op_sel:[0,1,0]
	v_pk_fma_f32 v[40:41], v[114:115], v[86:87], v[40:41] op_sel_hi:[1,0,1]
	v_pk_fma_f32 v[42:43], v[112:113], v[86:87], v[42:43] op_sel_hi:[1,0,1]
	v_pk_fma_f32 v[36:37], v[114:115], v[86:87], v[36:37] op_sel:[0,1,0]
	v_pk_fma_f32 v[38:39], v[112:113], v[86:87], v[38:39] op_sel:[0,1,0]
	v_pk_fma_f32 v[32:33], v[114:115], v[2:3], v[32:33] op_sel_hi:[1,0,1]
	v_pk_fma_f32 v[34:35], v[112:113], v[2:3], v[34:35] op_sel_hi:[1,0,1]
	v_pk_fma_f32 v[28:29], v[114:115], v[2:3], v[28:29] op_sel:[0,1,0]
	v_pk_fma_f32 v[30:31], v[112:113], v[2:3], v[30:31] op_sel:[0,1,0]
	v_pk_fma_f32 v[24:25], v[114:115], v[4:5], v[24:25] op_sel_hi:[1,0,1]
	v_pk_fma_f32 v[26:27], v[112:113], v[4:5], v[26:27] op_sel_hi:[1,0,1]
	v_pk_fma_f32 v[20:21], v[114:115], v[4:5], v[20:21] op_sel:[0,1,0]
	v_pk_fma_f32 v[22:23], v[112:113], v[4:5], v[22:23] op_sel:[0,1,0]
	v_pk_fma_f32 v[96:97], v[114:115], v[6:7], v[96:97] op_sel_hi:[1,0,1]
	v_pk_fma_f32 v[98:99], v[112:113], v[6:7], v[98:99] op_sel_hi:[1,0,1]
	v_pk_fma_f32 v[92:93], v[114:115], v[6:7], v[92:93] op_sel:[0,1,0]
	v_pk_fma_f32 v[94:95], v[112:113], v[6:7], v[94:95] op_sel:[0,1,0]
	v_pk_fma_f32 v[88:89], v[114:115], v[8:9], v[88:89] op_sel_hi:[1,0,1]
	v_pk_fma_f32 v[90:91], v[112:113], v[8:9], v[90:91] op_sel_hi:[1,0,1]
	v_pk_fma_f32 v[76:77], v[114:115], v[8:9], v[76:77] op_sel:[0,1,0]
	v_pk_fma_f32 v[78:79], v[112:113], v[8:9], v[78:79] op_sel:[0,1,0]
	v_pk_fma_f32 v[72:73], v[114:115], v[142:143], v[72:73] op_sel_hi:[1,0,1]
	v_pk_fma_f32 v[74:75], v[112:113], v[142:143], v[74:75] op_sel_hi:[1,0,1]
	v_pk_fma_f32 v[68:69], v[114:115], v[142:143], v[68:69] op_sel:[0,1,0]
	v_pk_fma_f32 v[70:71], v[112:113], v[142:143], v[70:71] op_sel:[0,1,0]
	v_lshl_add_u64 v[18:19], v[18:19], 0, s[14:15]
	global_load_dwordx4 v[112:115], v[18:19], off
	v_add_u32_e32 v14, 0x220, v128
	ds_read2st64_b32 v[80:81], v14 offset1:4
	ds_read2st64_b32 v[82:83], v14 offset0:8 offset1:12
	ds_read2st64_b32 v[84:85], v14 offset0:16 offset1:20
	ds_read2st64_b32 v[86:87], v14 offset0:24 offset1:28
	ds_read2st64_b32 v[2:3], v14 offset0:32 offset1:36
	ds_read2st64_b32 v[4:5], v14 offset0:40 offset1:44
	ds_read2st64_b32 v[6:7], v14 offset0:48 offset1:52
	ds_read2st64_b32 v[8:9], v14 offset0:56 offset1:60
	ds_read2st64_b32 v[142:143], v14 offset0:64 offset1:68
	s_waitcnt vmcnt(11) lgkmcnt(9)
	v_pk_fma_f32 v[64:65], v[118:119], v[162:163], v[64:65] op_sel_hi:[1,0,1]
	v_pk_fma_f32 v[66:67], v[116:117], v[162:163], v[66:67] op_sel_hi:[1,0,1]
	v_pk_fma_f32 v[60:61], v[118:119], v[162:163], v[60:61] op_sel:[0,1,0]
	v_pk_fma_f32 v[62:63], v[116:117], v[162:163], v[62:63] op_sel:[0,1,0]
	v_pk_fma_f32 v[56:57], v[118:119], v[164:165], v[56:57] op_sel_hi:[1,0,1]
	v_pk_fma_f32 v[58:59], v[116:117], v[164:165], v[58:59] op_sel_hi:[1,0,1]
	v_pk_fma_f32 v[52:53], v[118:119], v[164:165], v[52:53] op_sel:[0,1,0]
	v_pk_fma_f32 v[54:55], v[116:117], v[164:165], v[54:55] op_sel:[0,1,0]
	v_pk_fma_f32 v[48:49], v[118:119], v[166:167], v[48:49] op_sel_hi:[1,0,1]
	v_pk_fma_f32 v[50:51], v[116:117], v[166:167], v[50:51] op_sel_hi:[1,0,1]
	v_pk_fma_f32 v[44:45], v[118:119], v[166:167], v[44:45] op_sel:[0,1,0]
	v_pk_fma_f32 v[46:47], v[116:117], v[166:167], v[46:47] op_sel:[0,1,0]
	v_pk_fma_f32 v[40:41], v[118:119], v[168:169], v[40:41] op_sel_hi:[1,0,1]
	v_pk_fma_f32 v[42:43], v[116:117], v[168:169], v[42:43] op_sel_hi:[1,0,1]
	v_pk_fma_f32 v[36:37], v[118:119], v[168:169], v[36:37] op_sel:[0,1,0]
	v_pk_fma_f32 v[38:39], v[116:117], v[168:169], v[38:39] op_sel:[0,1,0]
	v_pk_fma_f32 v[32:33], v[118:119], v[170:171], v[32:33] op_sel_hi:[1,0,1]
	v_pk_fma_f32 v[34:35], v[116:117], v[170:171], v[34:35] op_sel_hi:[1,0,1]
	v_pk_fma_f32 v[28:29], v[118:119], v[170:171], v[28:29] op_sel:[0,1,0]
	v_pk_fma_f32 v[30:31], v[116:117], v[170:171], v[30:31] op_sel:[0,1,0]
	v_pk_fma_f32 v[24:25], v[118:119], v[172:173], v[24:25] op_sel_hi:[1,0,1]
	v_pk_fma_f32 v[26:27], v[116:117], v[172:173], v[26:27] op_sel_hi:[1,0,1]
	v_pk_fma_f32 v[20:21], v[118:119], v[172:173], v[20:21] op_sel:[0,1,0]
	v_pk_fma_f32 v[22:23], v[116:117], v[172:173], v[22:23] op_sel:[0,1,0]
	v_pk_fma_f32 v[96:97], v[118:119], v[174:175], v[96:97] op_sel_hi:[1,0,1]
	v_pk_fma_f32 v[98:99], v[116:117], v[174:175], v[98:99] op_sel_hi:[1,0,1]
	v_pk_fma_f32 v[92:93], v[118:119], v[174:175], v[92:93] op_sel:[0,1,0]
	v_pk_fma_f32 v[94:95], v[116:117], v[174:175], v[94:95] op_sel:[0,1,0]
	v_pk_fma_f32 v[88:89], v[118:119], v[176:177], v[88:89] op_sel_hi:[1,0,1]
	v_pk_fma_f32 v[90:91], v[116:117], v[176:177], v[90:91] op_sel_hi:[1,0,1]
	v_pk_fma_f32 v[76:77], v[118:119], v[176:177], v[76:77] op_sel:[0,1,0]
	v_pk_fma_f32 v[78:79], v[116:117], v[176:177], v[78:79] op_sel:[0,1,0]
	v_pk_fma_f32 v[72:73], v[118:119], v[178:179], v[72:73] op_sel_hi:[1,0,1]
	v_pk_fma_f32 v[74:75], v[116:117], v[178:179], v[74:75] op_sel_hi:[1,0,1]
	v_pk_fma_f32 v[68:69], v[118:119], v[178:179], v[68:69] op_sel:[0,1,0]
	v_pk_fma_f32 v[70:71], v[116:117], v[178:179], v[70:71] op_sel:[0,1,0]
	v_lshl_add_u64 v[18:19], v[18:19], 0, s[14:15]
	global_load_dwordx4 v[116:119], v[18:19], off
	v_add_u32_e32 v14, 0x240, v128
	ds_read2st64_b32 v[162:163], v14 offset1:4
	ds_read2st64_b32 v[164:165], v14 offset0:8 offset1:12
	ds_read2st64_b32 v[166:167], v14 offset0:16 offset1:20
	ds_read2st64_b32 v[168:169], v14 offset0:24 offset1:28
	ds_read2st64_b32 v[170:171], v14 offset0:32 offset1:36
	ds_read2st64_b32 v[172:173], v14 offset0:40 offset1:44
	ds_read2st64_b32 v[174:175], v14 offset0:48 offset1:52
	ds_read2st64_b32 v[176:177], v14 offset0:56 offset1:60
	ds_read2st64_b32 v[178:179], v14 offset0:64 offset1:68
	s_waitcnt vmcnt(11) lgkmcnt(9)
	v_pk_fma_f32 v[64:65], v[122:123], v[80:81], v[64:65] op_sel_hi:[1,0,1]
	v_pk_fma_f32 v[66:67], v[120:121], v[80:81], v[66:67] op_sel_hi:[1,0,1]
	v_pk_fma_f32 v[60:61], v[122:123], v[80:81], v[60:61] op_sel:[0,1,0]
	v_pk_fma_f32 v[62:63], v[120:121], v[80:81], v[62:63] op_sel:[0,1,0]
	v_pk_fma_f32 v[56:57], v[122:123], v[82:83], v[56:57] op_sel_hi:[1,0,1]
	v_pk_fma_f32 v[58:59], v[120:121], v[82:83], v[58:59] op_sel_hi:[1,0,1]
	v_pk_fma_f32 v[52:53], v[122:123], v[82:83], v[52:53] op_sel:[0,1,0]
	v_pk_fma_f32 v[54:55], v[120:121], v[82:83], v[54:55] op_sel:[0,1,0]
	v_pk_fma_f32 v[48:49], v[122:123], v[84:85], v[48:49] op_sel_hi:[1,0,1]
	v_pk_fma_f32 v[50:51], v[120:121], v[84:85], v[50:51] op_sel_hi:[1,0,1]
	v_pk_fma_f32 v[44:45], v[122:123], v[84:85], v[44:45] op_sel:[0,1,0]
	v_pk_fma_f32 v[46:47], v[120:121], v[84:85], v[46:47] op_sel:[0,1,0]
	v_pk_fma_f32 v[40:41], v[122:123], v[86:87], v[40:41] op_sel_hi:[1,0,1]
	v_pk_fma_f32 v[42:43], v[120:121], v[86:87], v[42:43] op_sel_hi:[1,0,1]
	v_pk_fma_f32 v[36:37], v[122:123], v[86:87], v[36:37] op_sel:[0,1,0]
	v_pk_fma_f32 v[38:39], v[120:121], v[86:87], v[38:39] op_sel:[0,1,0]
	v_pk_fma_f32 v[32:33], v[122:123], v[2:3], v[32:33] op_sel_hi:[1,0,1]
	v_pk_fma_f32 v[34:35], v[120:121], v[2:3], v[34:35] op_sel_hi:[1,0,1]
	v_pk_fma_f32 v[28:29], v[122:123], v[2:3], v[28:29] op_sel:[0,1,0]
	v_pk_fma_f32 v[30:31], v[120:121], v[2:3], v[30:31] op_sel:[0,1,0]
	v_pk_fma_f32 v[24:25], v[122:123], v[4:5], v[24:25] op_sel_hi:[1,0,1]
	v_pk_fma_f32 v[26:27], v[120:121], v[4:5], v[26:27] op_sel_hi:[1,0,1]
	v_pk_fma_f32 v[20:21], v[122:123], v[4:5], v[20:21] op_sel:[0,1,0]
	v_pk_fma_f32 v[22:23], v[120:121], v[4:5], v[22:23] op_sel:[0,1,0]
	v_pk_fma_f32 v[96:97], v[122:123], v[6:7], v[96:97] op_sel_hi:[1,0,1]
	v_pk_fma_f32 v[98:99], v[120:121], v[6:7], v[98:99] op_sel_hi:[1,0,1]
	v_pk_fma_f32 v[92:93], v[122:123], v[6:7], v[92:93] op_sel:[0,1,0]
	v_pk_fma_f32 v[94:95], v[120:121], v[6:7], v[94:95] op_sel:[0,1,0]
	v_pk_fma_f32 v[88:89], v[122:123], v[8:9], v[88:89] op_sel_hi:[1,0,1]
	v_pk_fma_f32 v[90:91], v[120:121], v[8:9], v[90:91] op_sel_hi:[1,0,1]
	v_pk_fma_f32 v[76:77], v[122:123], v[8:9], v[76:77] op_sel:[0,1,0]
	v_pk_fma_f32 v[78:79], v[120:121], v[8:9], v[78:79] op_sel:[0,1,0]
	v_pk_fma_f32 v[72:73], v[122:123], v[142:143], v[72:73] op_sel_hi:[1,0,1]
	v_pk_fma_f32 v[74:75], v[120:121], v[142:143], v[74:75] op_sel_hi:[1,0,1]
	v_pk_fma_f32 v[68:69], v[122:123], v[142:143], v[68:69] op_sel:[0,1,0]
	v_pk_fma_f32 v[70:71], v[120:121], v[142:143], v[70:71] op_sel:[0,1,0]
	v_lshl_add_u64 v[18:19], v[18:19], 0, s[14:15]
	global_load_dwordx4 v[120:123], v[18:19], off
	v_add_u32_e32 v14, 0x260, v128
	ds_read2st64_b32 v[80:81], v14 offset1:4
	ds_read2st64_b32 v[82:83], v14 offset0:8 offset1:12
	ds_read2st64_b32 v[84:85], v14 offset0:16 offset1:20
	ds_read2st64_b32 v[86:87], v14 offset0:24 offset1:28
	ds_read2st64_b32 v[2:3], v14 offset0:32 offset1:36
	ds_read2st64_b32 v[4:5], v14 offset0:40 offset1:44
	ds_read2st64_b32 v[6:7], v14 offset0:48 offset1:52
	ds_read2st64_b32 v[8:9], v14 offset0:56 offset1:60
	ds_read2st64_b32 v[142:143], v14 offset0:64 offset1:68
	s_waitcnt vmcnt(11) lgkmcnt(9)
	v_pk_fma_f32 v[64:65], v[126:127], v[162:163], v[64:65] op_sel_hi:[1,0,1]
	v_pk_fma_f32 v[66:67], v[124:125], v[162:163], v[66:67] op_sel_hi:[1,0,1]
	v_pk_fma_f32 v[60:61], v[126:127], v[162:163], v[60:61] op_sel:[0,1,0]
	v_pk_fma_f32 v[62:63], v[124:125], v[162:163], v[62:63] op_sel:[0,1,0]
	v_pk_fma_f32 v[56:57], v[126:127], v[164:165], v[56:57] op_sel_hi:[1,0,1]
	v_pk_fma_f32 v[58:59], v[124:125], v[164:165], v[58:59] op_sel_hi:[1,0,1]
	v_pk_fma_f32 v[52:53], v[126:127], v[164:165], v[52:53] op_sel:[0,1,0]
	v_pk_fma_f32 v[54:55], v[124:125], v[164:165], v[54:55] op_sel:[0,1,0]
	v_pk_fma_f32 v[48:49], v[126:127], v[166:167], v[48:49] op_sel_hi:[1,0,1]
	v_pk_fma_f32 v[50:51], v[124:125], v[166:167], v[50:51] op_sel_hi:[1,0,1]
	v_pk_fma_f32 v[44:45], v[126:127], v[166:167], v[44:45] op_sel:[0,1,0]
	v_pk_fma_f32 v[46:47], v[124:125], v[166:167], v[46:47] op_sel:[0,1,0]
	v_pk_fma_f32 v[40:41], v[126:127], v[168:169], v[40:41] op_sel_hi:[1,0,1]
	v_pk_fma_f32 v[42:43], v[124:125], v[168:169], v[42:43] op_sel_hi:[1,0,1]
	v_pk_fma_f32 v[36:37], v[126:127], v[168:169], v[36:37] op_sel:[0,1,0]
	v_pk_fma_f32 v[38:39], v[124:125], v[168:169], v[38:39] op_sel:[0,1,0]
	v_pk_fma_f32 v[32:33], v[126:127], v[170:171], v[32:33] op_sel_hi:[1,0,1]
	v_pk_fma_f32 v[34:35], v[124:125], v[170:171], v[34:35] op_sel_hi:[1,0,1]
	v_pk_fma_f32 v[28:29], v[126:127], v[170:171], v[28:29] op_sel:[0,1,0]
	v_pk_fma_f32 v[30:31], v[124:125], v[170:171], v[30:31] op_sel:[0,1,0]
	v_pk_fma_f32 v[24:25], v[126:127], v[172:173], v[24:25] op_sel_hi:[1,0,1]
	v_pk_fma_f32 v[26:27], v[124:125], v[172:173], v[26:27] op_sel_hi:[1,0,1]
	v_pk_fma_f32 v[20:21], v[126:127], v[172:173], v[20:21] op_sel:[0,1,0]
	v_pk_fma_f32 v[22:23], v[124:125], v[172:173], v[22:23] op_sel:[0,1,0]
	v_pk_fma_f32 v[96:97], v[126:127], v[174:175], v[96:97] op_sel_hi:[1,0,1]
	v_pk_fma_f32 v[98:99], v[124:125], v[174:175], v[98:99] op_sel_hi:[1,0,1]
	v_pk_fma_f32 v[92:93], v[126:127], v[174:175], v[92:93] op_sel:[0,1,0]
	v_pk_fma_f32 v[94:95], v[124:125], v[174:175], v[94:95] op_sel:[0,1,0]
	v_pk_fma_f32 v[88:89], v[126:127], v[176:177], v[88:89] op_sel_hi:[1,0,1]
	v_pk_fma_f32 v[90:91], v[124:125], v[176:177], v[90:91] op_sel_hi:[1,0,1]
	v_pk_fma_f32 v[76:77], v[126:127], v[176:177], v[76:77] op_sel:[0,1,0]
	v_pk_fma_f32 v[78:79], v[124:125], v[176:177], v[78:79] op_sel:[0,1,0]
	v_pk_fma_f32 v[72:73], v[126:127], v[178:179], v[72:73] op_sel_hi:[1,0,1]
	v_pk_fma_f32 v[74:75], v[124:125], v[178:179], v[74:75] op_sel_hi:[1,0,1]
	v_pk_fma_f32 v[68:69], v[126:127], v[178:179], v[68:69] op_sel:[0,1,0]
	v_pk_fma_f32 v[70:71], v[124:125], v[178:179], v[70:71] op_sel:[0,1,0]
	v_lshl_add_u64 v[18:19], v[18:19], 0, s[14:15]
	global_load_dwordx4 v[124:127], v[18:19], off
	v_add_u32_e32 v14, 0x280, v128
	ds_read2st64_b32 v[162:163], v14 offset1:4
	ds_read2st64_b32 v[164:165], v14 offset0:8 offset1:12
	ds_read2st64_b32 v[166:167], v14 offset0:16 offset1:20
	ds_read2st64_b32 v[168:169], v14 offset0:24 offset1:28
	ds_read2st64_b32 v[170:171], v14 offset0:32 offset1:36
	ds_read2st64_b32 v[172:173], v14 offset0:40 offset1:44
	ds_read2st64_b32 v[174:175], v14 offset0:48 offset1:52
	ds_read2st64_b32 v[176:177], v14 offset0:56 offset1:60
	ds_read2st64_b32 v[178:179], v14 offset0:64 offset1:68
	s_waitcnt vmcnt(11) lgkmcnt(9)
	v_pk_fma_f32 v[64:65], v[132:133], v[80:81], v[64:65] op_sel_hi:[1,0,1]
	v_pk_fma_f32 v[66:67], v[130:131], v[80:81], v[66:67] op_sel_hi:[1,0,1]
	v_pk_fma_f32 v[60:61], v[132:133], v[80:81], v[60:61] op_sel:[0,1,0]
	v_pk_fma_f32 v[62:63], v[130:131], v[80:81], v[62:63] op_sel:[0,1,0]
	v_pk_fma_f32 v[56:57], v[132:133], v[82:83], v[56:57] op_sel_hi:[1,0,1]
	v_pk_fma_f32 v[58:59], v[130:131], v[82:83], v[58:59] op_sel_hi:[1,0,1]
	v_pk_fma_f32 v[52:53], v[132:133], v[82:83], v[52:53] op_sel:[0,1,0]
	v_pk_fma_f32 v[54:55], v[130:131], v[82:83], v[54:55] op_sel:[0,1,0]
	v_pk_fma_f32 v[48:49], v[132:133], v[84:85], v[48:49] op_sel_hi:[1,0,1]
	v_pk_fma_f32 v[50:51], v[130:131], v[84:85], v[50:51] op_sel_hi:[1,0,1]
	v_pk_fma_f32 v[44:45], v[132:133], v[84:85], v[44:45] op_sel:[0,1,0]
	v_pk_fma_f32 v[46:47], v[130:131], v[84:85], v[46:47] op_sel:[0,1,0]
	v_pk_fma_f32 v[40:41], v[132:133], v[86:87], v[40:41] op_sel_hi:[1,0,1]
	v_pk_fma_f32 v[42:43], v[130:131], v[86:87], v[42:43] op_sel_hi:[1,0,1]
	v_pk_fma_f32 v[36:37], v[132:133], v[86:87], v[36:37] op_sel:[0,1,0]
	v_pk_fma_f32 v[38:39], v[130:131], v[86:87], v[38:39] op_sel:[0,1,0]
	v_pk_fma_f32 v[32:33], v[132:133], v[2:3], v[32:33] op_sel_hi:[1,0,1]
	v_pk_fma_f32 v[34:35], v[130:131], v[2:3], v[34:35] op_sel_hi:[1,0,1]
	v_pk_fma_f32 v[28:29], v[132:133], v[2:3], v[28:29] op_sel:[0,1,0]
	v_pk_fma_f32 v[30:31], v[130:131], v[2:3], v[30:31] op_sel:[0,1,0]
	v_pk_fma_f32 v[24:25], v[132:133], v[4:5], v[24:25] op_sel_hi:[1,0,1]
	v_pk_fma_f32 v[26:27], v[130:131], v[4:5], v[26:27] op_sel_hi:[1,0,1]
	v_pk_fma_f32 v[20:21], v[132:133], v[4:5], v[20:21] op_sel:[0,1,0]
	v_pk_fma_f32 v[22:23], v[130:131], v[4:5], v[22:23] op_sel:[0,1,0]
	v_pk_fma_f32 v[96:97], v[132:133], v[6:7], v[96:97] op_sel_hi:[1,0,1]
	v_pk_fma_f32 v[98:99], v[130:131], v[6:7], v[98:99] op_sel_hi:[1,0,1]
	v_pk_fma_f32 v[92:93], v[132:133], v[6:7], v[92:93] op_sel:[0,1,0]
	v_pk_fma_f32 v[94:95], v[130:131], v[6:7], v[94:95] op_sel:[0,1,0]
	v_pk_fma_f32 v[88:89], v[132:133], v[8:9], v[88:89] op_sel_hi:[1,0,1]
	v_pk_fma_f32 v[90:91], v[130:131], v[8:9], v[90:91] op_sel_hi:[1,0,1]
	v_pk_fma_f32 v[76:77], v[132:133], v[8:9], v[76:77] op_sel:[0,1,0]
	v_pk_fma_f32 v[78:79], v[130:131], v[8:9], v[78:79] op_sel:[0,1,0]
	v_pk_fma_f32 v[72:73], v[132:133], v[142:143], v[72:73] op_sel_hi:[1,0,1]
	v_pk_fma_f32 v[74:75], v[130:131], v[142:143], v[74:75] op_sel_hi:[1,0,1]
	v_pk_fma_f32 v[68:69], v[132:133], v[142:143], v[68:69] op_sel:[0,1,0]
	v_pk_fma_f32 v[70:71], v[130:131], v[142:143], v[70:71] op_sel:[0,1,0]
	v_lshl_add_u64 v[18:19], v[18:19], 0, s[14:15]
	global_load_dwordx4 v[130:133], v[18:19], off
	v_add_u32_e32 v14, 0x2a0, v128
	ds_read2st64_b32 v[80:81], v14 offset1:4
	ds_read2st64_b32 v[82:83], v14 offset0:8 offset1:12
	ds_read2st64_b32 v[84:85], v14 offset0:16 offset1:20
	ds_read2st64_b32 v[86:87], v14 offset0:24 offset1:28
	ds_read2st64_b32 v[2:3], v14 offset0:32 offset1:36
	ds_read2st64_b32 v[4:5], v14 offset0:40 offset1:44
	ds_read2st64_b32 v[6:7], v14 offset0:48 offset1:52
	ds_read2st64_b32 v[8:9], v14 offset0:56 offset1:60
	ds_read2st64_b32 v[142:143], v14 offset0:64 offset1:68
	s_waitcnt vmcnt(11) lgkmcnt(9)
	v_pk_fma_f32 v[64:65], v[136:137], v[162:163], v[64:65] op_sel_hi:[1,0,1]
	v_pk_fma_f32 v[66:67], v[134:135], v[162:163], v[66:67] op_sel_hi:[1,0,1]
	v_pk_fma_f32 v[60:61], v[136:137], v[162:163], v[60:61] op_sel:[0,1,0]
	v_pk_fma_f32 v[62:63], v[134:135], v[162:163], v[62:63] op_sel:[0,1,0]
	v_pk_fma_f32 v[56:57], v[136:137], v[164:165], v[56:57] op_sel_hi:[1,0,1]
	v_pk_fma_f32 v[58:59], v[134:135], v[164:165], v[58:59] op_sel_hi:[1,0,1]
	v_pk_fma_f32 v[52:53], v[136:137], v[164:165], v[52:53] op_sel:[0,1,0]
	v_pk_fma_f32 v[54:55], v[134:135], v[164:165], v[54:55] op_sel:[0,1,0]
	v_pk_fma_f32 v[48:49], v[136:137], v[166:167], v[48:49] op_sel_hi:[1,0,1]
	v_pk_fma_f32 v[50:51], v[134:135], v[166:167], v[50:51] op_sel_hi:[1,0,1]
	v_pk_fma_f32 v[44:45], v[136:137], v[166:167], v[44:45] op_sel:[0,1,0]
	v_pk_fma_f32 v[46:47], v[134:135], v[166:167], v[46:47] op_sel:[0,1,0]
	v_pk_fma_f32 v[40:41], v[136:137], v[168:169], v[40:41] op_sel_hi:[1,0,1]
	v_pk_fma_f32 v[42:43], v[134:135], v[168:169], v[42:43] op_sel_hi:[1,0,1]
	v_pk_fma_f32 v[36:37], v[136:137], v[168:169], v[36:37] op_sel:[0,1,0]
	v_pk_fma_f32 v[38:39], v[134:135], v[168:169], v[38:39] op_sel:[0,1,0]
	v_pk_fma_f32 v[32:33], v[136:137], v[170:171], v[32:33] op_sel_hi:[1,0,1]
	v_pk_fma_f32 v[34:35], v[134:135], v[170:171], v[34:35] op_sel_hi:[1,0,1]
	v_pk_fma_f32 v[28:29], v[136:137], v[170:171], v[28:29] op_sel:[0,1,0]
	v_pk_fma_f32 v[30:31], v[134:135], v[170:171], v[30:31] op_sel:[0,1,0]
	v_pk_fma_f32 v[24:25], v[136:137], v[172:173], v[24:25] op_sel_hi:[1,0,1]
	v_pk_fma_f32 v[26:27], v[134:135], v[172:173], v[26:27] op_sel_hi:[1,0,1]
	v_pk_fma_f32 v[20:21], v[136:137], v[172:173], v[20:21] op_sel:[0,1,0]
	v_pk_fma_f32 v[22:23], v[134:135], v[172:173], v[22:23] op_sel:[0,1,0]
	v_pk_fma_f32 v[96:97], v[136:137], v[174:175], v[96:97] op_sel_hi:[1,0,1]
	v_pk_fma_f32 v[98:99], v[134:135], v[174:175], v[98:99] op_sel_hi:[1,0,1]
	v_pk_fma_f32 v[92:93], v[136:137], v[174:175], v[92:93] op_sel:[0,1,0]
	v_pk_fma_f32 v[94:95], v[134:135], v[174:175], v[94:95] op_sel:[0,1,0]
	v_pk_fma_f32 v[88:89], v[136:137], v[176:177], v[88:89] op_sel_hi:[1,0,1]
	v_pk_fma_f32 v[90:91], v[134:135], v[176:177], v[90:91] op_sel_hi:[1,0,1]
	v_pk_fma_f32 v[76:77], v[136:137], v[176:177], v[76:77] op_sel:[0,1,0]
	v_pk_fma_f32 v[78:79], v[134:135], v[176:177], v[78:79] op_sel:[0,1,0]
	v_pk_fma_f32 v[72:73], v[136:137], v[178:179], v[72:73] op_sel_hi:[1,0,1]
	v_pk_fma_f32 v[74:75], v[134:135], v[178:179], v[74:75] op_sel_hi:[1,0,1]
	v_pk_fma_f32 v[68:69], v[136:137], v[178:179], v[68:69] op_sel:[0,1,0]
	v_pk_fma_f32 v[70:71], v[134:135], v[178:179], v[70:71] op_sel:[0,1,0]
	v_add_u32_e32 v14, 0x2c0, v128
	ds_read2st64_b32 v[162:163], v14 offset1:4
	ds_read2st64_b32 v[164:165], v14 offset0:8 offset1:12
	ds_read2st64_b32 v[166:167], v14 offset0:16 offset1:20
	ds_read2st64_b32 v[168:169], v14 offset0:24 offset1:28
	ds_read2st64_b32 v[170:171], v14 offset0:32 offset1:36
	ds_read2st64_b32 v[172:173], v14 offset0:40 offset1:44
	ds_read2st64_b32 v[174:175], v14 offset0:48 offset1:52
	ds_read2st64_b32 v[176:177], v14 offset0:56 offset1:60
	ds_read2st64_b32 v[178:179], v14 offset0:64 offset1:68
	s_waitcnt vmcnt(10) lgkmcnt(9)
	v_pk_fma_f32 v[64:65], v[140:141], v[80:81], v[64:65] op_sel_hi:[1,0,1]
	v_pk_fma_f32 v[66:67], v[138:139], v[80:81], v[66:67] op_sel_hi:[1,0,1]
	v_pk_fma_f32 v[60:61], v[140:141], v[80:81], v[60:61] op_sel:[0,1,0]
	v_pk_fma_f32 v[62:63], v[138:139], v[80:81], v[62:63] op_sel:[0,1,0]
	v_pk_fma_f32 v[56:57], v[140:141], v[82:83], v[56:57] op_sel_hi:[1,0,1]
	v_pk_fma_f32 v[58:59], v[138:139], v[82:83], v[58:59] op_sel_hi:[1,0,1]
	v_pk_fma_f32 v[52:53], v[140:141], v[82:83], v[52:53] op_sel:[0,1,0]
	v_pk_fma_f32 v[54:55], v[138:139], v[82:83], v[54:55] op_sel:[0,1,0]
	v_pk_fma_f32 v[48:49], v[140:141], v[84:85], v[48:49] op_sel_hi:[1,0,1]
	v_pk_fma_f32 v[50:51], v[138:139], v[84:85], v[50:51] op_sel_hi:[1,0,1]
	v_pk_fma_f32 v[44:45], v[140:141], v[84:85], v[44:45] op_sel:[0,1,0]
	v_pk_fma_f32 v[46:47], v[138:139], v[84:85], v[46:47] op_sel:[0,1,0]
	v_pk_fma_f32 v[40:41], v[140:141], v[86:87], v[40:41] op_sel_hi:[1,0,1]
	v_pk_fma_f32 v[42:43], v[138:139], v[86:87], v[42:43] op_sel_hi:[1,0,1]
	v_pk_fma_f32 v[36:37], v[140:141], v[86:87], v[36:37] op_sel:[0,1,0]
	v_pk_fma_f32 v[38:39], v[138:139], v[86:87], v[38:39] op_sel:[0,1,0]
	v_pk_fma_f32 v[32:33], v[140:141], v[2:3], v[32:33] op_sel_hi:[1,0,1]
	v_pk_fma_f32 v[34:35], v[138:139], v[2:3], v[34:35] op_sel_hi:[1,0,1]
	v_pk_fma_f32 v[28:29], v[140:141], v[2:3], v[28:29] op_sel:[0,1,0]
	v_pk_fma_f32 v[30:31], v[138:139], v[2:3], v[30:31] op_sel:[0,1,0]
	v_pk_fma_f32 v[24:25], v[140:141], v[4:5], v[24:25] op_sel_hi:[1,0,1]
	v_pk_fma_f32 v[26:27], v[138:139], v[4:5], v[26:27] op_sel_hi:[1,0,1]
	v_pk_fma_f32 v[20:21], v[140:141], v[4:5], v[20:21] op_sel:[0,1,0]
	v_pk_fma_f32 v[22:23], v[138:139], v[4:5], v[22:23] op_sel:[0,1,0]
	v_pk_fma_f32 v[96:97], v[140:141], v[6:7], v[96:97] op_sel_hi:[1,0,1]
	v_pk_fma_f32 v[98:99], v[138:139], v[6:7], v[98:99] op_sel_hi:[1,0,1]
	v_pk_fma_f32 v[92:93], v[140:141], v[6:7], v[92:93] op_sel:[0,1,0]
	v_pk_fma_f32 v[94:95], v[138:139], v[6:7], v[94:95] op_sel:[0,1,0]
	v_pk_fma_f32 v[88:89], v[140:141], v[8:9], v[88:89] op_sel_hi:[1,0,1]
	v_pk_fma_f32 v[90:91], v[138:139], v[8:9], v[90:91] op_sel_hi:[1,0,1]
	v_pk_fma_f32 v[76:77], v[140:141], v[8:9], v[76:77] op_sel:[0,1,0]
	v_pk_fma_f32 v[78:79], v[138:139], v[8:9], v[78:79] op_sel:[0,1,0]
	v_pk_fma_f32 v[72:73], v[140:141], v[142:143], v[72:73] op_sel_hi:[1,0,1]
	v_pk_fma_f32 v[74:75], v[138:139], v[142:143], v[74:75] op_sel_hi:[1,0,1]
	v_pk_fma_f32 v[68:69], v[140:141], v[142:143], v[68:69] op_sel:[0,1,0]
	v_pk_fma_f32 v[70:71], v[138:139], v[142:143], v[70:71] op_sel:[0,1,0]
	v_add_u32_e32 v14, 0x2e0, v128
	ds_read2st64_b32 v[80:81], v14 offset1:4
	ds_read2st64_b32 v[82:83], v14 offset0:8 offset1:12
	ds_read2st64_b32 v[84:85], v14 offset0:16 offset1:20
	ds_read2st64_b32 v[86:87], v14 offset0:24 offset1:28
	ds_read2st64_b32 v[2:3], v14 offset0:32 offset1:36
	ds_read2st64_b32 v[4:5], v14 offset0:40 offset1:44
	ds_read2st64_b32 v[6:7], v14 offset0:48 offset1:52
	ds_read2st64_b32 v[8:9], v14 offset0:56 offset1:60
	ds_read2st64_b32 v[142:143], v14 offset0:64 offset1:68
	s_waitcnt vmcnt(9) lgkmcnt(9)
	v_pk_fma_f32 v[64:65], v[148:149], v[162:163], v[64:65] op_sel_hi:[1,0,1]
	v_pk_fma_f32 v[66:67], v[146:147], v[162:163], v[66:67] op_sel_hi:[1,0,1]
	v_pk_fma_f32 v[60:61], v[148:149], v[162:163], v[60:61] op_sel:[0,1,0]
	v_pk_fma_f32 v[62:63], v[146:147], v[162:163], v[62:63] op_sel:[0,1,0]
	v_pk_fma_f32 v[56:57], v[148:149], v[164:165], v[56:57] op_sel_hi:[1,0,1]
	v_pk_fma_f32 v[58:59], v[146:147], v[164:165], v[58:59] op_sel_hi:[1,0,1]
	v_pk_fma_f32 v[52:53], v[148:149], v[164:165], v[52:53] op_sel:[0,1,0]
	v_pk_fma_f32 v[54:55], v[146:147], v[164:165], v[54:55] op_sel:[0,1,0]
	v_pk_fma_f32 v[48:49], v[148:149], v[166:167], v[48:49] op_sel_hi:[1,0,1]
	v_pk_fma_f32 v[50:51], v[146:147], v[166:167], v[50:51] op_sel_hi:[1,0,1]
	v_pk_fma_f32 v[44:45], v[148:149], v[166:167], v[44:45] op_sel:[0,1,0]
	v_pk_fma_f32 v[46:47], v[146:147], v[166:167], v[46:47] op_sel:[0,1,0]
	v_pk_fma_f32 v[40:41], v[148:149], v[168:169], v[40:41] op_sel_hi:[1,0,1]
	v_pk_fma_f32 v[42:43], v[146:147], v[168:169], v[42:43] op_sel_hi:[1,0,1]
	v_pk_fma_f32 v[36:37], v[148:149], v[168:169], v[36:37] op_sel:[0,1,0]
	v_pk_fma_f32 v[38:39], v[146:147], v[168:169], v[38:39] op_sel:[0,1,0]
	v_pk_fma_f32 v[32:33], v[148:149], v[170:171], v[32:33] op_sel_hi:[1,0,1]
	v_pk_fma_f32 v[34:35], v[146:147], v[170:171], v[34:35] op_sel_hi:[1,0,1]
	v_pk_fma_f32 v[28:29], v[148:149], v[170:171], v[28:29] op_sel:[0,1,0]
	v_pk_fma_f32 v[30:31], v[146:147], v[170:171], v[30:31] op_sel:[0,1,0]
	v_pk_fma_f32 v[24:25], v[148:149], v[172:173], v[24:25] op_sel_hi:[1,0,1]
	v_pk_fma_f32 v[26:27], v[146:147], v[172:173], v[26:27] op_sel_hi:[1,0,1]
	v_pk_fma_f32 v[20:21], v[148:149], v[172:173], v[20:21] op_sel:[0,1,0]
	v_pk_fma_f32 v[22:23], v[146:147], v[172:173], v[22:23] op_sel:[0,1,0]
	v_pk_fma_f32 v[96:97], v[148:149], v[174:175], v[96:97] op_sel_hi:[1,0,1]
	v_pk_fma_f32 v[98:99], v[146:147], v[174:175], v[98:99] op_sel_hi:[1,0,1]
	v_pk_fma_f32 v[92:93], v[148:149], v[174:175], v[92:93] op_sel:[0,1,0]
	v_pk_fma_f32 v[94:95], v[146:147], v[174:175], v[94:95] op_sel:[0,1,0]
	v_pk_fma_f32 v[88:89], v[148:149], v[176:177], v[88:89] op_sel_hi:[1,0,1]
	v_pk_fma_f32 v[90:91], v[146:147], v[176:177], v[90:91] op_sel_hi:[1,0,1]
	v_pk_fma_f32 v[76:77], v[148:149], v[176:177], v[76:77] op_sel:[0,1,0]
	v_pk_fma_f32 v[78:79], v[146:147], v[176:177], v[78:79] op_sel:[0,1,0]
	v_pk_fma_f32 v[72:73], v[148:149], v[178:179], v[72:73] op_sel_hi:[1,0,1]
	v_pk_fma_f32 v[74:75], v[146:147], v[178:179], v[74:75] op_sel_hi:[1,0,1]
	v_pk_fma_f32 v[68:69], v[148:149], v[178:179], v[68:69] op_sel:[0,1,0]
	v_pk_fma_f32 v[70:71], v[146:147], v[178:179], v[70:71] op_sel:[0,1,0]
	v_add_u32_e32 v14, 0x300, v128
	ds_read2st64_b32 v[162:163], v14 offset1:4
	ds_read2st64_b32 v[164:165], v14 offset0:8 offset1:12
	ds_read2st64_b32 v[166:167], v14 offset0:16 offset1:20
	ds_read2st64_b32 v[168:169], v14 offset0:24 offset1:28
	ds_read2st64_b32 v[170:171], v14 offset0:32 offset1:36
	ds_read2st64_b32 v[172:173], v14 offset0:40 offset1:44
	ds_read2st64_b32 v[174:175], v14 offset0:48 offset1:52
	ds_read2st64_b32 v[176:177], v14 offset0:56 offset1:60
	ds_read2st64_b32 v[178:179], v14 offset0:64 offset1:68
	s_waitcnt vmcnt(8) lgkmcnt(9)
	v_pk_fma_f32 v[64:65], v[152:153], v[80:81], v[64:65] op_sel_hi:[1,0,1]
	v_pk_fma_f32 v[66:67], v[150:151], v[80:81], v[66:67] op_sel_hi:[1,0,1]
	v_pk_fma_f32 v[60:61], v[152:153], v[80:81], v[60:61] op_sel:[0,1,0]
	v_pk_fma_f32 v[62:63], v[150:151], v[80:81], v[62:63] op_sel:[0,1,0]
	v_pk_fma_f32 v[56:57], v[152:153], v[82:83], v[56:57] op_sel_hi:[1,0,1]
	v_pk_fma_f32 v[58:59], v[150:151], v[82:83], v[58:59] op_sel_hi:[1,0,1]
	v_pk_fma_f32 v[52:53], v[152:153], v[82:83], v[52:53] op_sel:[0,1,0]
	v_pk_fma_f32 v[54:55], v[150:151], v[82:83], v[54:55] op_sel:[0,1,0]
	v_pk_fma_f32 v[48:49], v[152:153], v[84:85], v[48:49] op_sel_hi:[1,0,1]
	v_pk_fma_f32 v[50:51], v[150:151], v[84:85], v[50:51] op_sel_hi:[1,0,1]
	v_pk_fma_f32 v[44:45], v[152:153], v[84:85], v[44:45] op_sel:[0,1,0]
	v_pk_fma_f32 v[46:47], v[150:151], v[84:85], v[46:47] op_sel:[0,1,0]
	v_pk_fma_f32 v[40:41], v[152:153], v[86:87], v[40:41] op_sel_hi:[1,0,1]
	v_pk_fma_f32 v[42:43], v[150:151], v[86:87], v[42:43] op_sel_hi:[1,0,1]
	v_pk_fma_f32 v[36:37], v[152:153], v[86:87], v[36:37] op_sel:[0,1,0]
	v_pk_fma_f32 v[38:39], v[150:151], v[86:87], v[38:39] op_sel:[0,1,0]
	v_pk_fma_f32 v[32:33], v[152:153], v[2:3], v[32:33] op_sel_hi:[1,0,1]
	v_pk_fma_f32 v[34:35], v[150:151], v[2:3], v[34:35] op_sel_hi:[1,0,1]
	v_pk_fma_f32 v[28:29], v[152:153], v[2:3], v[28:29] op_sel:[0,1,0]
	v_pk_fma_f32 v[30:31], v[150:151], v[2:3], v[30:31] op_sel:[0,1,0]
	v_pk_fma_f32 v[24:25], v[152:153], v[4:5], v[24:25] op_sel_hi:[1,0,1]
	v_pk_fma_f32 v[26:27], v[150:151], v[4:5], v[26:27] op_sel_hi:[1,0,1]
	v_pk_fma_f32 v[20:21], v[152:153], v[4:5], v[20:21] op_sel:[0,1,0]
	v_pk_fma_f32 v[22:23], v[150:151], v[4:5], v[22:23] op_sel:[0,1,0]
	v_pk_fma_f32 v[96:97], v[152:153], v[6:7], v[96:97] op_sel_hi:[1,0,1]
	v_pk_fma_f32 v[98:99], v[150:151], v[6:7], v[98:99] op_sel_hi:[1,0,1]
	v_pk_fma_f32 v[92:93], v[152:153], v[6:7], v[92:93] op_sel:[0,1,0]
	v_pk_fma_f32 v[94:95], v[150:151], v[6:7], v[94:95] op_sel:[0,1,0]
	v_pk_fma_f32 v[88:89], v[152:153], v[8:9], v[88:89] op_sel_hi:[1,0,1]
	v_pk_fma_f32 v[90:91], v[150:151], v[8:9], v[90:91] op_sel_hi:[1,0,1]
	v_pk_fma_f32 v[76:77], v[152:153], v[8:9], v[76:77] op_sel:[0,1,0]
	v_pk_fma_f32 v[78:79], v[150:151], v[8:9], v[78:79] op_sel:[0,1,0]
	v_pk_fma_f32 v[72:73], v[152:153], v[142:143], v[72:73] op_sel_hi:[1,0,1]
	v_pk_fma_f32 v[74:75], v[150:151], v[142:143], v[74:75] op_sel_hi:[1,0,1]
	v_pk_fma_f32 v[68:69], v[152:153], v[142:143], v[68:69] op_sel:[0,1,0]
	v_pk_fma_f32 v[70:71], v[150:151], v[142:143], v[70:71] op_sel:[0,1,0]
	v_add_u32_e32 v14, 0x320, v128
	ds_read2st64_b32 v[80:81], v14 offset1:4
	ds_read2st64_b32 v[82:83], v14 offset0:8 offset1:12
	ds_read2st64_b32 v[84:85], v14 offset0:16 offset1:20
	ds_read2st64_b32 v[86:87], v14 offset0:24 offset1:28
	ds_read2st64_b32 v[2:3], v14 offset0:32 offset1:36
	ds_read2st64_b32 v[4:5], v14 offset0:40 offset1:44
	ds_read2st64_b32 v[6:7], v14 offset0:48 offset1:52
	ds_read2st64_b32 v[8:9], v14 offset0:56 offset1:60
	ds_read2st64_b32 v[142:143], v14 offset0:64 offset1:68
	s_waitcnt vmcnt(7) lgkmcnt(9)
	v_pk_fma_f32 v[64:65], v[102:103], v[162:163], v[64:65] op_sel_hi:[1,0,1]
	v_pk_fma_f32 v[66:67], v[100:101], v[162:163], v[66:67] op_sel_hi:[1,0,1]
	v_pk_fma_f32 v[60:61], v[102:103], v[162:163], v[60:61] op_sel:[0,1,0]
	v_pk_fma_f32 v[62:63], v[100:101], v[162:163], v[62:63] op_sel:[0,1,0]
	v_pk_fma_f32 v[56:57], v[102:103], v[164:165], v[56:57] op_sel_hi:[1,0,1]
	v_pk_fma_f32 v[58:59], v[100:101], v[164:165], v[58:59] op_sel_hi:[1,0,1]
	v_pk_fma_f32 v[52:53], v[102:103], v[164:165], v[52:53] op_sel:[0,1,0]
	v_pk_fma_f32 v[54:55], v[100:101], v[164:165], v[54:55] op_sel:[0,1,0]
	v_pk_fma_f32 v[48:49], v[102:103], v[166:167], v[48:49] op_sel_hi:[1,0,1]
	v_pk_fma_f32 v[50:51], v[100:101], v[166:167], v[50:51] op_sel_hi:[1,0,1]
	v_pk_fma_f32 v[44:45], v[102:103], v[166:167], v[44:45] op_sel:[0,1,0]
	v_pk_fma_f32 v[46:47], v[100:101], v[166:167], v[46:47] op_sel:[0,1,0]
	v_pk_fma_f32 v[40:41], v[102:103], v[168:169], v[40:41] op_sel_hi:[1,0,1]
	v_pk_fma_f32 v[42:43], v[100:101], v[168:169], v[42:43] op_sel_hi:[1,0,1]
	v_pk_fma_f32 v[36:37], v[102:103], v[168:169], v[36:37] op_sel:[0,1,0]
	v_pk_fma_f32 v[38:39], v[100:101], v[168:169], v[38:39] op_sel:[0,1,0]
	v_pk_fma_f32 v[32:33], v[102:103], v[170:171], v[32:33] op_sel_hi:[1,0,1]
	v_pk_fma_f32 v[34:35], v[100:101], v[170:171], v[34:35] op_sel_hi:[1,0,1]
	v_pk_fma_f32 v[28:29], v[102:103], v[170:171], v[28:29] op_sel:[0,1,0]
	v_pk_fma_f32 v[30:31], v[100:101], v[170:171], v[30:31] op_sel:[0,1,0]
	v_pk_fma_f32 v[24:25], v[102:103], v[172:173], v[24:25] op_sel_hi:[1,0,1]
	v_pk_fma_f32 v[26:27], v[100:101], v[172:173], v[26:27] op_sel_hi:[1,0,1]
	v_pk_fma_f32 v[20:21], v[102:103], v[172:173], v[20:21] op_sel:[0,1,0]
	v_pk_fma_f32 v[22:23], v[100:101], v[172:173], v[22:23] op_sel:[0,1,0]
	v_pk_fma_f32 v[96:97], v[102:103], v[174:175], v[96:97] op_sel_hi:[1,0,1]
	v_pk_fma_f32 v[98:99], v[100:101], v[174:175], v[98:99] op_sel_hi:[1,0,1]
	v_pk_fma_f32 v[92:93], v[102:103], v[174:175], v[92:93] op_sel:[0,1,0]
	v_pk_fma_f32 v[94:95], v[100:101], v[174:175], v[94:95] op_sel:[0,1,0]
	v_pk_fma_f32 v[88:89], v[102:103], v[176:177], v[88:89] op_sel_hi:[1,0,1]
	v_pk_fma_f32 v[90:91], v[100:101], v[176:177], v[90:91] op_sel_hi:[1,0,1]
	v_pk_fma_f32 v[76:77], v[102:103], v[176:177], v[76:77] op_sel:[0,1,0]
	v_pk_fma_f32 v[78:79], v[100:101], v[176:177], v[78:79] op_sel:[0,1,0]
	v_pk_fma_f32 v[72:73], v[102:103], v[178:179], v[72:73] op_sel_hi:[1,0,1]
	v_pk_fma_f32 v[74:75], v[100:101], v[178:179], v[74:75] op_sel_hi:[1,0,1]
	v_pk_fma_f32 v[68:69], v[102:103], v[178:179], v[68:69] op_sel:[0,1,0]
	v_pk_fma_f32 v[70:71], v[100:101], v[178:179], v[70:71] op_sel:[0,1,0]
	v_add_u32_e32 v14, 0x340, v128
	ds_read2st64_b32 v[162:163], v14 offset1:4
	ds_read2st64_b32 v[164:165], v14 offset0:8 offset1:12
	ds_read2st64_b32 v[166:167], v14 offset0:16 offset1:20
	ds_read2st64_b32 v[168:169], v14 offset0:24 offset1:28
	ds_read2st64_b32 v[170:171], v14 offset0:32 offset1:36
	ds_read2st64_b32 v[172:173], v14 offset0:40 offset1:44
	ds_read2st64_b32 v[174:175], v14 offset0:48 offset1:52
	ds_read2st64_b32 v[176:177], v14 offset0:56 offset1:60
	ds_read2st64_b32 v[178:179], v14 offset0:64 offset1:68
	s_waitcnt vmcnt(6) lgkmcnt(9)
	v_pk_fma_f32 v[64:65], v[106:107], v[80:81], v[64:65] op_sel_hi:[1,0,1]
	v_pk_fma_f32 v[66:67], v[104:105], v[80:81], v[66:67] op_sel_hi:[1,0,1]
	v_pk_fma_f32 v[60:61], v[106:107], v[80:81], v[60:61] op_sel:[0,1,0]
	v_pk_fma_f32 v[62:63], v[104:105], v[80:81], v[62:63] op_sel:[0,1,0]
	v_pk_fma_f32 v[56:57], v[106:107], v[82:83], v[56:57] op_sel_hi:[1,0,1]
	v_pk_fma_f32 v[58:59], v[104:105], v[82:83], v[58:59] op_sel_hi:[1,0,1]
	v_pk_fma_f32 v[52:53], v[106:107], v[82:83], v[52:53] op_sel:[0,1,0]
	v_pk_fma_f32 v[54:55], v[104:105], v[82:83], v[54:55] op_sel:[0,1,0]
	v_pk_fma_f32 v[48:49], v[106:107], v[84:85], v[48:49] op_sel_hi:[1,0,1]
	v_pk_fma_f32 v[50:51], v[104:105], v[84:85], v[50:51] op_sel_hi:[1,0,1]
	v_pk_fma_f32 v[44:45], v[106:107], v[84:85], v[44:45] op_sel:[0,1,0]
	v_pk_fma_f32 v[46:47], v[104:105], v[84:85], v[46:47] op_sel:[0,1,0]
	v_pk_fma_f32 v[40:41], v[106:107], v[86:87], v[40:41] op_sel_hi:[1,0,1]
	v_pk_fma_f32 v[42:43], v[104:105], v[86:87], v[42:43] op_sel_hi:[1,0,1]
	v_pk_fma_f32 v[36:37], v[106:107], v[86:87], v[36:37] op_sel:[0,1,0]
	v_pk_fma_f32 v[38:39], v[104:105], v[86:87], v[38:39] op_sel:[0,1,0]
	v_pk_fma_f32 v[32:33], v[106:107], v[2:3], v[32:33] op_sel_hi:[1,0,1]
	v_pk_fma_f32 v[34:35], v[104:105], v[2:3], v[34:35] op_sel_hi:[1,0,1]
	v_pk_fma_f32 v[28:29], v[106:107], v[2:3], v[28:29] op_sel:[0,1,0]
	v_pk_fma_f32 v[30:31], v[104:105], v[2:3], v[30:31] op_sel:[0,1,0]
	v_pk_fma_f32 v[24:25], v[106:107], v[4:5], v[24:25] op_sel_hi:[1,0,1]
	v_pk_fma_f32 v[26:27], v[104:105], v[4:5], v[26:27] op_sel_hi:[1,0,1]
	v_pk_fma_f32 v[20:21], v[106:107], v[4:5], v[20:21] op_sel:[0,1,0]
	v_pk_fma_f32 v[22:23], v[104:105], v[4:5], v[22:23] op_sel:[0,1,0]
	v_pk_fma_f32 v[96:97], v[106:107], v[6:7], v[96:97] op_sel_hi:[1,0,1]
	v_pk_fma_f32 v[98:99], v[104:105], v[6:7], v[98:99] op_sel_hi:[1,0,1]
	v_pk_fma_f32 v[92:93], v[106:107], v[6:7], v[92:93] op_sel:[0,1,0]
	v_pk_fma_f32 v[94:95], v[104:105], v[6:7], v[94:95] op_sel:[0,1,0]
	v_pk_fma_f32 v[88:89], v[106:107], v[8:9], v[88:89] op_sel_hi:[1,0,1]
	v_pk_fma_f32 v[90:91], v[104:105], v[8:9], v[90:91] op_sel_hi:[1,0,1]
	v_pk_fma_f32 v[76:77], v[106:107], v[8:9], v[76:77] op_sel:[0,1,0]
	v_pk_fma_f32 v[78:79], v[104:105], v[8:9], v[78:79] op_sel:[0,1,0]
	v_pk_fma_f32 v[72:73], v[106:107], v[142:143], v[72:73] op_sel_hi:[1,0,1]
	v_pk_fma_f32 v[74:75], v[104:105], v[142:143], v[74:75] op_sel_hi:[1,0,1]
	v_pk_fma_f32 v[68:69], v[106:107], v[142:143], v[68:69] op_sel:[0,1,0]
	v_pk_fma_f32 v[70:71], v[104:105], v[142:143], v[70:71] op_sel:[0,1,0]
	v_add_u32_e32 v14, 0x360, v128
	ds_read2st64_b32 v[80:81], v14 offset1:4
	ds_read2st64_b32 v[82:83], v14 offset0:8 offset1:12
	ds_read2st64_b32 v[84:85], v14 offset0:16 offset1:20
	ds_read2st64_b32 v[86:87], v14 offset0:24 offset1:28
	ds_read2st64_b32 v[2:3], v14 offset0:32 offset1:36
	ds_read2st64_b32 v[4:5], v14 offset0:40 offset1:44
	ds_read2st64_b32 v[6:7], v14 offset0:48 offset1:52
	ds_read2st64_b32 v[8:9], v14 offset0:56 offset1:60
	ds_read2st64_b32 v[142:143], v14 offset0:64 offset1:68
	s_waitcnt vmcnt(5) lgkmcnt(9)
	v_pk_fma_f32 v[64:65], v[110:111], v[162:163], v[64:65] op_sel_hi:[1,0,1]
	v_pk_fma_f32 v[66:67], v[108:109], v[162:163], v[66:67] op_sel_hi:[1,0,1]
	v_pk_fma_f32 v[60:61], v[110:111], v[162:163], v[60:61] op_sel:[0,1,0]
	v_pk_fma_f32 v[62:63], v[108:109], v[162:163], v[62:63] op_sel:[0,1,0]
	v_pk_fma_f32 v[56:57], v[110:111], v[164:165], v[56:57] op_sel_hi:[1,0,1]
	v_pk_fma_f32 v[58:59], v[108:109], v[164:165], v[58:59] op_sel_hi:[1,0,1]
	v_pk_fma_f32 v[52:53], v[110:111], v[164:165], v[52:53] op_sel:[0,1,0]
	v_pk_fma_f32 v[54:55], v[108:109], v[164:165], v[54:55] op_sel:[0,1,0]
	v_pk_fma_f32 v[48:49], v[110:111], v[166:167], v[48:49] op_sel_hi:[1,0,1]
	v_pk_fma_f32 v[50:51], v[108:109], v[166:167], v[50:51] op_sel_hi:[1,0,1]
	v_pk_fma_f32 v[44:45], v[110:111], v[166:167], v[44:45] op_sel:[0,1,0]
	v_pk_fma_f32 v[46:47], v[108:109], v[166:167], v[46:47] op_sel:[0,1,0]
	v_pk_fma_f32 v[40:41], v[110:111], v[168:169], v[40:41] op_sel_hi:[1,0,1]
	v_pk_fma_f32 v[42:43], v[108:109], v[168:169], v[42:43] op_sel_hi:[1,0,1]
	v_pk_fma_f32 v[36:37], v[110:111], v[168:169], v[36:37] op_sel:[0,1,0]
	v_pk_fma_f32 v[38:39], v[108:109], v[168:169], v[38:39] op_sel:[0,1,0]
	v_pk_fma_f32 v[32:33], v[110:111], v[170:171], v[32:33] op_sel_hi:[1,0,1]
	v_pk_fma_f32 v[34:35], v[108:109], v[170:171], v[34:35] op_sel_hi:[1,0,1]
	v_pk_fma_f32 v[28:29], v[110:111], v[170:171], v[28:29] op_sel:[0,1,0]
	v_pk_fma_f32 v[30:31], v[108:109], v[170:171], v[30:31] op_sel:[0,1,0]
	v_pk_fma_f32 v[24:25], v[110:111], v[172:173], v[24:25] op_sel_hi:[1,0,1]
	v_pk_fma_f32 v[26:27], v[108:109], v[172:173], v[26:27] op_sel_hi:[1,0,1]
	v_pk_fma_f32 v[20:21], v[110:111], v[172:173], v[20:21] op_sel:[0,1,0]
	v_pk_fma_f32 v[22:23], v[108:109], v[172:173], v[22:23] op_sel:[0,1,0]
	v_pk_fma_f32 v[96:97], v[110:111], v[174:175], v[96:97] op_sel_hi:[1,0,1]
	v_pk_fma_f32 v[98:99], v[108:109], v[174:175], v[98:99] op_sel_hi:[1,0,1]
	v_pk_fma_f32 v[92:93], v[110:111], v[174:175], v[92:93] op_sel:[0,1,0]
	v_pk_fma_f32 v[94:95], v[108:109], v[174:175], v[94:95] op_sel:[0,1,0]
	v_pk_fma_f32 v[88:89], v[110:111], v[176:177], v[88:89] op_sel_hi:[1,0,1]
	v_pk_fma_f32 v[90:91], v[108:109], v[176:177], v[90:91] op_sel_hi:[1,0,1]
	v_pk_fma_f32 v[76:77], v[110:111], v[176:177], v[76:77] op_sel:[0,1,0]
	v_pk_fma_f32 v[78:79], v[108:109], v[176:177], v[78:79] op_sel:[0,1,0]
	v_pk_fma_f32 v[72:73], v[110:111], v[178:179], v[72:73] op_sel_hi:[1,0,1]
	v_pk_fma_f32 v[74:75], v[108:109], v[178:179], v[74:75] op_sel_hi:[1,0,1]
	v_pk_fma_f32 v[68:69], v[110:111], v[178:179], v[68:69] op_sel:[0,1,0]
	v_pk_fma_f32 v[70:71], v[108:109], v[178:179], v[70:71] op_sel:[0,1,0]
	v_add_u32_e32 v14, 0x380, v128
	ds_read2st64_b32 v[162:163], v14 offset1:4
	ds_read2st64_b32 v[164:165], v14 offset0:8 offset1:12
	ds_read2st64_b32 v[166:167], v14 offset0:16 offset1:20
	ds_read2st64_b32 v[168:169], v14 offset0:24 offset1:28
	ds_read2st64_b32 v[170:171], v14 offset0:32 offset1:36
	ds_read2st64_b32 v[172:173], v14 offset0:40 offset1:44
	ds_read2st64_b32 v[174:175], v14 offset0:48 offset1:52
	ds_read2st64_b32 v[176:177], v14 offset0:56 offset1:60
	ds_read2st64_b32 v[178:179], v14 offset0:64 offset1:68
	s_waitcnt vmcnt(4) lgkmcnt(9)
	v_pk_fma_f32 v[64:65], v[114:115], v[80:81], v[64:65] op_sel_hi:[1,0,1]
	v_pk_fma_f32 v[66:67], v[112:113], v[80:81], v[66:67] op_sel_hi:[1,0,1]
	v_pk_fma_f32 v[60:61], v[114:115], v[80:81], v[60:61] op_sel:[0,1,0]
	v_pk_fma_f32 v[62:63], v[112:113], v[80:81], v[62:63] op_sel:[0,1,0]
	v_pk_fma_f32 v[56:57], v[114:115], v[82:83], v[56:57] op_sel_hi:[1,0,1]
	v_pk_fma_f32 v[58:59], v[112:113], v[82:83], v[58:59] op_sel_hi:[1,0,1]
	v_pk_fma_f32 v[52:53], v[114:115], v[82:83], v[52:53] op_sel:[0,1,0]
	v_pk_fma_f32 v[54:55], v[112:113], v[82:83], v[54:55] op_sel:[0,1,0]
	v_pk_fma_f32 v[48:49], v[114:115], v[84:85], v[48:49] op_sel_hi:[1,0,1]
	v_pk_fma_f32 v[50:51], v[112:113], v[84:85], v[50:51] op_sel_hi:[1,0,1]
	v_pk_fma_f32 v[44:45], v[114:115], v[84:85], v[44:45] op_sel:[0,1,0]
	v_pk_fma_f32 v[46:47], v[112:113], v[84:85], v[46:47] op_sel:[0,1,0]
	v_pk_fma_f32 v[40:41], v[114:115], v[86:87], v[40:41] op_sel_hi:[1,0,1]
	v_pk_fma_f32 v[42:43], v[112:113], v[86:87], v[42:43] op_sel_hi:[1,0,1]
	v_pk_fma_f32 v[36:37], v[114:115], v[86:87], v[36:37] op_sel:[0,1,0]
	v_pk_fma_f32 v[38:39], v[112:113], v[86:87], v[38:39] op_sel:[0,1,0]
	v_pk_fma_f32 v[32:33], v[114:115], v[2:3], v[32:33] op_sel_hi:[1,0,1]
	v_pk_fma_f32 v[34:35], v[112:113], v[2:3], v[34:35] op_sel_hi:[1,0,1]
	v_pk_fma_f32 v[28:29], v[114:115], v[2:3], v[28:29] op_sel:[0,1,0]
	v_pk_fma_f32 v[30:31], v[112:113], v[2:3], v[30:31] op_sel:[0,1,0]
	v_pk_fma_f32 v[24:25], v[114:115], v[4:5], v[24:25] op_sel_hi:[1,0,1]
	v_pk_fma_f32 v[26:27], v[112:113], v[4:5], v[26:27] op_sel_hi:[1,0,1]
	v_pk_fma_f32 v[20:21], v[114:115], v[4:5], v[20:21] op_sel:[0,1,0]
	v_pk_fma_f32 v[22:23], v[112:113], v[4:5], v[22:23] op_sel:[0,1,0]
	v_pk_fma_f32 v[96:97], v[114:115], v[6:7], v[96:97] op_sel_hi:[1,0,1]
	v_pk_fma_f32 v[98:99], v[112:113], v[6:7], v[98:99] op_sel_hi:[1,0,1]
	v_pk_fma_f32 v[92:93], v[114:115], v[6:7], v[92:93] op_sel:[0,1,0]
	v_pk_fma_f32 v[94:95], v[112:113], v[6:7], v[94:95] op_sel:[0,1,0]
	v_pk_fma_f32 v[88:89], v[114:115], v[8:9], v[88:89] op_sel_hi:[1,0,1]
	v_pk_fma_f32 v[90:91], v[112:113], v[8:9], v[90:91] op_sel_hi:[1,0,1]
	v_pk_fma_f32 v[76:77], v[114:115], v[8:9], v[76:77] op_sel:[0,1,0]
	v_pk_fma_f32 v[78:79], v[112:113], v[8:9], v[78:79] op_sel:[0,1,0]
	v_pk_fma_f32 v[72:73], v[114:115], v[142:143], v[72:73] op_sel_hi:[1,0,1]
	v_pk_fma_f32 v[74:75], v[112:113], v[142:143], v[74:75] op_sel_hi:[1,0,1]
	v_pk_fma_f32 v[68:69], v[114:115], v[142:143], v[68:69] op_sel:[0,1,0]
	v_pk_fma_f32 v[70:71], v[112:113], v[142:143], v[70:71] op_sel:[0,1,0]
	v_add_u32_e32 v14, 0x3a0, v128
	ds_read2st64_b32 v[80:81], v14 offset1:4
	ds_read2st64_b32 v[82:83], v14 offset0:8 offset1:12
	ds_read2st64_b32 v[84:85], v14 offset0:16 offset1:20
	ds_read2st64_b32 v[86:87], v14 offset0:24 offset1:28
	ds_read2st64_b32 v[2:3], v14 offset0:32 offset1:36
	ds_read2st64_b32 v[4:5], v14 offset0:40 offset1:44
	ds_read2st64_b32 v[6:7], v14 offset0:48 offset1:52
	ds_read2st64_b32 v[8:9], v14 offset0:56 offset1:60
	ds_read2st64_b32 v[142:143], v14 offset0:64 offset1:68
	s_waitcnt vmcnt(3) lgkmcnt(9)
	v_pk_fma_f32 v[64:65], v[118:119], v[162:163], v[64:65] op_sel_hi:[1,0,1]
	v_pk_fma_f32 v[66:67], v[116:117], v[162:163], v[66:67] op_sel_hi:[1,0,1]
	v_pk_fma_f32 v[60:61], v[118:119], v[162:163], v[60:61] op_sel:[0,1,0]
	v_pk_fma_f32 v[62:63], v[116:117], v[162:163], v[62:63] op_sel:[0,1,0]
	v_pk_fma_f32 v[56:57], v[118:119], v[164:165], v[56:57] op_sel_hi:[1,0,1]
	v_pk_fma_f32 v[58:59], v[116:117], v[164:165], v[58:59] op_sel_hi:[1,0,1]
	v_pk_fma_f32 v[52:53], v[118:119], v[164:165], v[52:53] op_sel:[0,1,0]
	v_pk_fma_f32 v[54:55], v[116:117], v[164:165], v[54:55] op_sel:[0,1,0]
	v_pk_fma_f32 v[48:49], v[118:119], v[166:167], v[48:49] op_sel_hi:[1,0,1]
	v_pk_fma_f32 v[50:51], v[116:117], v[166:167], v[50:51] op_sel_hi:[1,0,1]
	v_pk_fma_f32 v[44:45], v[118:119], v[166:167], v[44:45] op_sel:[0,1,0]
	v_pk_fma_f32 v[46:47], v[116:117], v[166:167], v[46:47] op_sel:[0,1,0]
	v_pk_fma_f32 v[40:41], v[118:119], v[168:169], v[40:41] op_sel_hi:[1,0,1]
	v_pk_fma_f32 v[42:43], v[116:117], v[168:169], v[42:43] op_sel_hi:[1,0,1]
	v_pk_fma_f32 v[36:37], v[118:119], v[168:169], v[36:37] op_sel:[0,1,0]
	v_pk_fma_f32 v[38:39], v[116:117], v[168:169], v[38:39] op_sel:[0,1,0]
	v_pk_fma_f32 v[32:33], v[118:119], v[170:171], v[32:33] op_sel_hi:[1,0,1]
	v_pk_fma_f32 v[34:35], v[116:117], v[170:171], v[34:35] op_sel_hi:[1,0,1]
	v_pk_fma_f32 v[28:29], v[118:119], v[170:171], v[28:29] op_sel:[0,1,0]
	v_pk_fma_f32 v[30:31], v[116:117], v[170:171], v[30:31] op_sel:[0,1,0]
	v_pk_fma_f32 v[24:25], v[118:119], v[172:173], v[24:25] op_sel_hi:[1,0,1]
	v_pk_fma_f32 v[26:27], v[116:117], v[172:173], v[26:27] op_sel_hi:[1,0,1]
	v_pk_fma_f32 v[20:21], v[118:119], v[172:173], v[20:21] op_sel:[0,1,0]
	v_pk_fma_f32 v[22:23], v[116:117], v[172:173], v[22:23] op_sel:[0,1,0]
	v_pk_fma_f32 v[96:97], v[118:119], v[174:175], v[96:97] op_sel_hi:[1,0,1]
	v_pk_fma_f32 v[98:99], v[116:117], v[174:175], v[98:99] op_sel_hi:[1,0,1]
	v_pk_fma_f32 v[92:93], v[118:119], v[174:175], v[92:93] op_sel:[0,1,0]
	v_pk_fma_f32 v[94:95], v[116:117], v[174:175], v[94:95] op_sel:[0,1,0]
	v_pk_fma_f32 v[88:89], v[118:119], v[176:177], v[88:89] op_sel_hi:[1,0,1]
	v_pk_fma_f32 v[90:91], v[116:117], v[176:177], v[90:91] op_sel_hi:[1,0,1]
	v_pk_fma_f32 v[76:77], v[118:119], v[176:177], v[76:77] op_sel:[0,1,0]
	v_pk_fma_f32 v[78:79], v[116:117], v[176:177], v[78:79] op_sel:[0,1,0]
	v_pk_fma_f32 v[72:73], v[118:119], v[178:179], v[72:73] op_sel_hi:[1,0,1]
	v_pk_fma_f32 v[74:75], v[116:117], v[178:179], v[74:75] op_sel_hi:[1,0,1]
	v_pk_fma_f32 v[68:69], v[118:119], v[178:179], v[68:69] op_sel:[0,1,0]
	v_pk_fma_f32 v[70:71], v[116:117], v[178:179], v[70:71] op_sel:[0,1,0]
	v_add_u32_e32 v14, 0x3c0, v128
	ds_read2st64_b32 v[162:163], v14 offset1:4
	ds_read2st64_b32 v[164:165], v14 offset0:8 offset1:12
	ds_read2st64_b32 v[166:167], v14 offset0:16 offset1:20
	ds_read2st64_b32 v[168:169], v14 offset0:24 offset1:28
	ds_read2st64_b32 v[170:171], v14 offset0:32 offset1:36
	ds_read2st64_b32 v[172:173], v14 offset0:40 offset1:44
	ds_read2st64_b32 v[174:175], v14 offset0:48 offset1:52
	ds_read2st64_b32 v[176:177], v14 offset0:56 offset1:60
	ds_read2st64_b32 v[178:179], v14 offset0:64 offset1:68
	s_waitcnt vmcnt(2) lgkmcnt(9)
	v_pk_fma_f32 v[64:65], v[122:123], v[80:81], v[64:65] op_sel_hi:[1,0,1]
	v_pk_fma_f32 v[66:67], v[120:121], v[80:81], v[66:67] op_sel_hi:[1,0,1]
	v_pk_fma_f32 v[60:61], v[122:123], v[80:81], v[60:61] op_sel:[0,1,0]
	v_pk_fma_f32 v[62:63], v[120:121], v[80:81], v[62:63] op_sel:[0,1,0]
	v_pk_fma_f32 v[56:57], v[122:123], v[82:83], v[56:57] op_sel_hi:[1,0,1]
	v_pk_fma_f32 v[58:59], v[120:121], v[82:83], v[58:59] op_sel_hi:[1,0,1]
	v_pk_fma_f32 v[52:53], v[122:123], v[82:83], v[52:53] op_sel:[0,1,0]
	v_pk_fma_f32 v[54:55], v[120:121], v[82:83], v[54:55] op_sel:[0,1,0]
	v_pk_fma_f32 v[48:49], v[122:123], v[84:85], v[48:49] op_sel_hi:[1,0,1]
	v_pk_fma_f32 v[50:51], v[120:121], v[84:85], v[50:51] op_sel_hi:[1,0,1]
	v_pk_fma_f32 v[44:45], v[122:123], v[84:85], v[44:45] op_sel:[0,1,0]
	v_pk_fma_f32 v[46:47], v[120:121], v[84:85], v[46:47] op_sel:[0,1,0]
	v_pk_fma_f32 v[40:41], v[122:123], v[86:87], v[40:41] op_sel_hi:[1,0,1]
	v_pk_fma_f32 v[42:43], v[120:121], v[86:87], v[42:43] op_sel_hi:[1,0,1]
	v_pk_fma_f32 v[36:37], v[122:123], v[86:87], v[36:37] op_sel:[0,1,0]
	v_pk_fma_f32 v[38:39], v[120:121], v[86:87], v[38:39] op_sel:[0,1,0]
	v_pk_fma_f32 v[32:33], v[122:123], v[2:3], v[32:33] op_sel_hi:[1,0,1]
	v_pk_fma_f32 v[34:35], v[120:121], v[2:3], v[34:35] op_sel_hi:[1,0,1]
	v_pk_fma_f32 v[28:29], v[122:123], v[2:3], v[28:29] op_sel:[0,1,0]
	v_pk_fma_f32 v[30:31], v[120:121], v[2:3], v[30:31] op_sel:[0,1,0]
	v_pk_fma_f32 v[24:25], v[122:123], v[4:5], v[24:25] op_sel_hi:[1,0,1]
	v_pk_fma_f32 v[26:27], v[120:121], v[4:5], v[26:27] op_sel_hi:[1,0,1]
	v_pk_fma_f32 v[20:21], v[122:123], v[4:5], v[20:21] op_sel:[0,1,0]
	v_pk_fma_f32 v[22:23], v[120:121], v[4:5], v[22:23] op_sel:[0,1,0]
	v_pk_fma_f32 v[96:97], v[122:123], v[6:7], v[96:97] op_sel_hi:[1,0,1]
	v_pk_fma_f32 v[98:99], v[120:121], v[6:7], v[98:99] op_sel_hi:[1,0,1]
	v_pk_fma_f32 v[92:93], v[122:123], v[6:7], v[92:93] op_sel:[0,1,0]
	v_pk_fma_f32 v[94:95], v[120:121], v[6:7], v[94:95] op_sel:[0,1,0]
	v_pk_fma_f32 v[88:89], v[122:123], v[8:9], v[88:89] op_sel_hi:[1,0,1]
	v_pk_fma_f32 v[90:91], v[120:121], v[8:9], v[90:91] op_sel_hi:[1,0,1]
	v_pk_fma_f32 v[76:77], v[122:123], v[8:9], v[76:77] op_sel:[0,1,0]
	v_pk_fma_f32 v[78:79], v[120:121], v[8:9], v[78:79] op_sel:[0,1,0]
	v_pk_fma_f32 v[72:73], v[122:123], v[142:143], v[72:73] op_sel_hi:[1,0,1]
	v_pk_fma_f32 v[74:75], v[120:121], v[142:143], v[74:75] op_sel_hi:[1,0,1]
	v_pk_fma_f32 v[68:69], v[122:123], v[142:143], v[68:69] op_sel:[0,1,0]
	v_pk_fma_f32 v[70:71], v[120:121], v[142:143], v[70:71] op_sel:[0,1,0]
	v_add_u32_e32 v14, 0x3e0, v128
	ds_read2st64_b32 v[80:81], v14 offset1:4
	ds_read2st64_b32 v[82:83], v14 offset0:8 offset1:12
	ds_read2st64_b32 v[84:85], v14 offset0:16 offset1:20
	ds_read2st64_b32 v[86:87], v14 offset0:24 offset1:28
	ds_read2st64_b32 v[2:3], v14 offset0:32 offset1:36
	ds_read2st64_b32 v[4:5], v14 offset0:40 offset1:44
	ds_read2st64_b32 v[6:7], v14 offset0:48 offset1:52
	ds_read2st64_b32 v[8:9], v14 offset0:56 offset1:60
	ds_read2st64_b32 v[142:143], v14 offset0:64 offset1:68
	s_waitcnt vmcnt(1) lgkmcnt(9)
	v_pk_fma_f32 v[64:65], v[126:127], v[162:163], v[64:65] op_sel_hi:[1,0,1]
	v_pk_fma_f32 v[66:67], v[124:125], v[162:163], v[66:67] op_sel_hi:[1,0,1]
	v_pk_fma_f32 v[60:61], v[126:127], v[162:163], v[60:61] op_sel:[0,1,0]
	v_pk_fma_f32 v[62:63], v[124:125], v[162:163], v[62:63] op_sel:[0,1,0]
	v_pk_fma_f32 v[56:57], v[126:127], v[164:165], v[56:57] op_sel_hi:[1,0,1]
	v_pk_fma_f32 v[58:59], v[124:125], v[164:165], v[58:59] op_sel_hi:[1,0,1]
	v_pk_fma_f32 v[52:53], v[126:127], v[164:165], v[52:53] op_sel:[0,1,0]
	v_pk_fma_f32 v[54:55], v[124:125], v[164:165], v[54:55] op_sel:[0,1,0]
	v_pk_fma_f32 v[48:49], v[126:127], v[166:167], v[48:49] op_sel_hi:[1,0,1]
	v_pk_fma_f32 v[50:51], v[124:125], v[166:167], v[50:51] op_sel_hi:[1,0,1]
	v_pk_fma_f32 v[44:45], v[126:127], v[166:167], v[44:45] op_sel:[0,1,0]
	v_pk_fma_f32 v[46:47], v[124:125], v[166:167], v[46:47] op_sel:[0,1,0]
	v_pk_fma_f32 v[40:41], v[126:127], v[168:169], v[40:41] op_sel_hi:[1,0,1]
	v_pk_fma_f32 v[42:43], v[124:125], v[168:169], v[42:43] op_sel_hi:[1,0,1]
	v_pk_fma_f32 v[36:37], v[126:127], v[168:169], v[36:37] op_sel:[0,1,0]
	v_pk_fma_f32 v[38:39], v[124:125], v[168:169], v[38:39] op_sel:[0,1,0]
	v_pk_fma_f32 v[32:33], v[126:127], v[170:171], v[32:33] op_sel_hi:[1,0,1]
	v_pk_fma_f32 v[34:35], v[124:125], v[170:171], v[34:35] op_sel_hi:[1,0,1]
	v_pk_fma_f32 v[28:29], v[126:127], v[170:171], v[28:29] op_sel:[0,1,0]
	v_pk_fma_f32 v[30:31], v[124:125], v[170:171], v[30:31] op_sel:[0,1,0]
	v_pk_fma_f32 v[24:25], v[126:127], v[172:173], v[24:25] op_sel_hi:[1,0,1]
	v_pk_fma_f32 v[26:27], v[124:125], v[172:173], v[26:27] op_sel_hi:[1,0,1]
	v_pk_fma_f32 v[20:21], v[126:127], v[172:173], v[20:21] op_sel:[0,1,0]
	v_pk_fma_f32 v[22:23], v[124:125], v[172:173], v[22:23] op_sel:[0,1,0]
	v_pk_fma_f32 v[96:97], v[126:127], v[174:175], v[96:97] op_sel_hi:[1,0,1]
	v_pk_fma_f32 v[98:99], v[124:125], v[174:175], v[98:99] op_sel_hi:[1,0,1]
	v_pk_fma_f32 v[92:93], v[126:127], v[174:175], v[92:93] op_sel:[0,1,0]
	v_pk_fma_f32 v[94:95], v[124:125], v[174:175], v[94:95] op_sel:[0,1,0]
	v_pk_fma_f32 v[88:89], v[126:127], v[176:177], v[88:89] op_sel_hi:[1,0,1]
	v_pk_fma_f32 v[90:91], v[124:125], v[176:177], v[90:91] op_sel_hi:[1,0,1]
	v_pk_fma_f32 v[76:77], v[126:127], v[176:177], v[76:77] op_sel:[0,1,0]
	v_pk_fma_f32 v[78:79], v[124:125], v[176:177], v[78:79] op_sel:[0,1,0]
	v_pk_fma_f32 v[72:73], v[126:127], v[178:179], v[72:73] op_sel_hi:[1,0,1]
	v_pk_fma_f32 v[74:75], v[124:125], v[178:179], v[74:75] op_sel_hi:[1,0,1]
	v_pk_fma_f32 v[68:69], v[126:127], v[178:179], v[68:69] op_sel:[0,1,0]
	v_pk_fma_f32 v[70:71], v[124:125], v[178:179], v[70:71] op_sel:[0,1,0]
	s_waitcnt vmcnt(0) lgkmcnt(0)
	v_pk_fma_f32 v[64:65], v[132:133], v[80:81], v[64:65] op_sel_hi:[1,0,1]
	v_pk_fma_f32 v[66:67], v[130:131], v[80:81], v[66:67] op_sel_hi:[1,0,1]
	v_pk_fma_f32 v[60:61], v[132:133], v[80:81], v[60:61] op_sel:[0,1,0]
	v_pk_fma_f32 v[62:63], v[130:131], v[80:81], v[62:63] op_sel:[0,1,0]
	v_pk_fma_f32 v[56:57], v[132:133], v[82:83], v[56:57] op_sel_hi:[1,0,1]
	v_pk_fma_f32 v[58:59], v[130:131], v[82:83], v[58:59] op_sel_hi:[1,0,1]
	v_pk_fma_f32 v[52:53], v[132:133], v[82:83], v[52:53] op_sel:[0,1,0]
	v_pk_fma_f32 v[54:55], v[130:131], v[82:83], v[54:55] op_sel:[0,1,0]
	v_pk_fma_f32 v[48:49], v[132:133], v[84:85], v[48:49] op_sel_hi:[1,0,1]
	v_pk_fma_f32 v[50:51], v[130:131], v[84:85], v[50:51] op_sel_hi:[1,0,1]
	v_pk_fma_f32 v[44:45], v[132:133], v[84:85], v[44:45] op_sel:[0,1,0]
	v_pk_fma_f32 v[46:47], v[130:131], v[84:85], v[46:47] op_sel:[0,1,0]
	v_pk_fma_f32 v[40:41], v[132:133], v[86:87], v[40:41] op_sel_hi:[1,0,1]
	v_pk_fma_f32 v[42:43], v[130:131], v[86:87], v[42:43] op_sel_hi:[1,0,1]
	v_pk_fma_f32 v[36:37], v[132:133], v[86:87], v[36:37] op_sel:[0,1,0]
	v_pk_fma_f32 v[38:39], v[130:131], v[86:87], v[38:39] op_sel:[0,1,0]
	v_pk_fma_f32 v[32:33], v[132:133], v[2:3], v[32:33] op_sel_hi:[1,0,1]
	v_pk_fma_f32 v[34:35], v[130:131], v[2:3], v[34:35] op_sel_hi:[1,0,1]
	v_pk_fma_f32 v[28:29], v[132:133], v[2:3], v[28:29] op_sel:[0,1,0]
	v_pk_fma_f32 v[30:31], v[130:131], v[2:3], v[30:31] op_sel:[0,1,0]
	v_pk_fma_f32 v[24:25], v[132:133], v[4:5], v[24:25] op_sel_hi:[1,0,1]
	v_pk_fma_f32 v[26:27], v[130:131], v[4:5], v[26:27] op_sel_hi:[1,0,1]
	v_pk_fma_f32 v[20:21], v[132:133], v[4:5], v[20:21] op_sel:[0,1,0]
	v_pk_fma_f32 v[22:23], v[130:131], v[4:5], v[22:23] op_sel:[0,1,0]
	v_pk_fma_f32 v[96:97], v[132:133], v[6:7], v[96:97] op_sel_hi:[1,0,1]
	v_pk_fma_f32 v[98:99], v[130:131], v[6:7], v[98:99] op_sel_hi:[1,0,1]
	v_pk_fma_f32 v[92:93], v[132:133], v[6:7], v[92:93] op_sel:[0,1,0]
	v_pk_fma_f32 v[94:95], v[130:131], v[6:7], v[94:95] op_sel:[0,1,0]
	v_pk_fma_f32 v[88:89], v[132:133], v[8:9], v[88:89] op_sel_hi:[1,0,1]
	v_pk_fma_f32 v[90:91], v[130:131], v[8:9], v[90:91] op_sel_hi:[1,0,1]
	v_pk_fma_f32 v[76:77], v[132:133], v[8:9], v[76:77] op_sel:[0,1,0]
	v_pk_fma_f32 v[78:79], v[130:131], v[8:9], v[78:79] op_sel:[0,1,0]
	v_pk_fma_f32 v[72:73], v[132:133], v[142:143], v[72:73] op_sel_hi:[1,0,1]
	v_pk_fma_f32 v[74:75], v[130:131], v[142:143], v[74:75] op_sel_hi:[1,0,1]
	v_pk_fma_f32 v[68:69], v[132:133], v[142:143], v[68:69] op_sel:[0,1,0]
	v_pk_fma_f32 v[70:71], v[130:131], v[142:143], v[70:71] op_sel:[0,1,0]
	ds_bpermute_b32 v2, v156, v66
	ds_bpermute_b32 v3, v156, v67
	ds_bpermute_b32 v4, v156, v64
	ds_bpermute_b32 v5, v156, v65
	ds_bpermute_b32 v8, v156, v62
	ds_bpermute_b32 v9, v156, v63
	s_waitcnt lgkmcnt(4)
	v_pk_add_f32 v[2:3], v[66:67], v[2:3]
	ds_bpermute_b32 v6, v157, v2
	ds_bpermute_b32 v7, v157, v3
	s_waitcnt lgkmcnt(4)
	v_pk_add_f32 v[4:5], v[64:65], v[4:5]
	ds_bpermute_b32 v82, v156, v60
	ds_bpermute_b32 v83, v156, v61
	ds_bpermute_b32 v104, v156, v50
	s_waitcnt lgkmcnt(3)
	v_pk_add_f32 v[18:19], v[2:3], v[6:7]
	ds_bpermute_b32 v2, v157, v4
	ds_bpermute_b32 v3, v157, v5
	v_pk_add_f32 v[6:7], v[62:63], v[8:9]
	ds_bpermute_b32 v8, v157, v6
	ds_bpermute_b32 v9, v157, v7
	ds_bpermute_b32 v105, v156, v51
	s_waitcnt lgkmcnt(3)
	v_pk_add_f32 v[62:63], v[4:5], v[2:3]
	v_pk_add_f32 v[2:3], v[60:61], v[82:83]
	ds_bpermute_b32 v4, v157, v2
	ds_bpermute_b32 v5, v157, v3
	s_waitcnt lgkmcnt(3)
	v_pk_add_f32 v[80:81], v[6:7], v[8:9]
	ds_bpermute_b32 v6, v156, v58
	ds_bpermute_b32 v7, v156, v59
	ds_bpermute_b32 v114, v156, v40
	s_waitcnt lgkmcnt(3)
	v_pk_add_f32 v[82:83], v[2:3], v[4:5]
	ds_bpermute_b32 v2, v156, v56
	ds_bpermute_b32 v3, v156, v57
	s_waitcnt lgkmcnt(3)
	v_pk_add_f32 v[4:5], v[58:59], v[6:7]
	ds_bpermute_b32 v6, v157, v4
	ds_bpermute_b32 v7, v157, v5
	ds_bpermute_b32 v115, v156, v41
	s_waitcnt lgkmcnt(3)
	v_pk_add_f32 v[2:3], v[56:57], v[2:3]
	ds_bpermute_b32 v8, v157, v2
	ds_bpermute_b32 v9, v157, v3
	s_waitcnt lgkmcnt(3)
	v_pk_add_f32 v[56:57], v[4:5], v[6:7]
	ds_bpermute_b32 v4, v156, v52
	ds_bpermute_b32 v5, v156, v53
	ds_bpermute_b32 v124, v156, v30
	s_waitcnt lgkmcnt(3)
	v_pk_add_f32 v[86:87], v[2:3], v[8:9]
	ds_bpermute_b32 v2, v156, v54
	ds_bpermute_b32 v3, v156, v55
	s_waitcnt lgkmcnt(3)
	v_pk_add_f32 v[4:5], v[52:53], v[4:5]
	ds_bpermute_b32 v8, v157, v4
	ds_bpermute_b32 v9, v157, v5
	ds_bpermute_b32 v125, v156, v31
	s_waitcnt lgkmcnt(3)
	v_pk_add_f32 v[2:3], v[54:55], v[2:3]
	ds_bpermute_b32 v6, v157, v2
	ds_bpermute_b32 v7, v157, v3
	s_waitcnt lgkmcnt(3)
	v_pk_add_f32 v[102:103], v[4:5], v[8:9]
	ds_bpermute_b32 v134, v156, v20
	ds_bpermute_b32 v135, v156, v21
	ds_bpermute_b32 v144, v156, v90
	s_waitcnt lgkmcnt(3)
	v_pk_add_f32 v[52:53], v[2:3], v[6:7]
	v_pk_add_f32 v[2:3], v[50:51], v[104:105]
	ds_bpermute_b32 v4, v157, v2
	ds_bpermute_b32 v5, v157, v3
	ds_bpermute_b32 v6, v156, v48
	ds_bpermute_b32 v7, v156, v49
	ds_bpermute_b32 v145, v156, v91
	ds_bpermute_b32 v152, v156, v72
	s_waitcnt lgkmcnt(4)
	v_pk_add_f32 v[104:105], v[2:3], v[4:5]
	ds_bpermute_b32 v2, v156, v46
	ds_bpermute_b32 v3, v156, v47
	s_waitcnt lgkmcnt(4)
	v_pk_add_f32 v[4:5], v[48:49], v[6:7]
	ds_bpermute_b32 v6, v157, v4
	ds_bpermute_b32 v7, v157, v5
	ds_bpermute_b32 v153, v156, v73
	s_waitcnt lgkmcnt(3)
	v_pk_add_f32 v[2:3], v[46:47], v[2:3]
	ds_bpermute_b32 v8, v157, v2
	ds_bpermute_b32 v9, v157, v3
	s_waitcnt lgkmcnt(3)
	v_pk_add_f32 v[46:47], v[4:5], v[6:7]
	ds_bpermute_b32 v4, v156, v42
	ds_bpermute_b32 v5, v156, v43
	ds_bpermute_b32 v162, v156, v70
	s_waitcnt lgkmcnt(3)
	v_pk_add_f32 v[108:109], v[2:3], v[8:9]
	ds_bpermute_b32 v2, v156, v44
	ds_bpermute_b32 v3, v156, v45
	s_waitcnt lgkmcnt(3)
	v_pk_add_f32 v[4:5], v[42:43], v[4:5]
	ds_bpermute_b32 v8, v157, v4
	ds_bpermute_b32 v9, v157, v5
	ds_bpermute_b32 v163, v156, v71
	s_waitcnt lgkmcnt(3)
	v_pk_add_f32 v[2:3], v[44:45], v[2:3]
	ds_bpermute_b32 v6, v157, v2
	ds_bpermute_b32 v7, v157, v3
	s_waitcnt lgkmcnt(3)
	v_pk_add_f32 v[112:113], v[4:5], v[8:9]
	ds_bpermute_b32 v64, v158, v18
	ds_bpermute_b32 v65, v158, v19
	ds_bpermute_b32 v66, v158, v62
	s_waitcnt lgkmcnt(3)
	v_pk_add_f32 v[42:43], v[2:3], v[6:7]
	v_pk_add_f32 v[2:3], v[40:41], v[114:115]
	ds_bpermute_b32 v4, v157, v2
	ds_bpermute_b32 v5, v157, v3
	ds_bpermute_b32 v6, v156, v38
	ds_bpermute_b32 v7, v156, v39
	ds_bpermute_b32 v67, v158, v63
	ds_bpermute_b32 v60, v158, v80
	s_waitcnt lgkmcnt(4)
	v_pk_add_f32 v[114:115], v[2:3], v[4:5]
	ds_bpermute_b32 v2, v156, v36
	ds_bpermute_b32 v3, v156, v37
	s_waitcnt lgkmcnt(4)
	v_pk_add_f32 v[4:5], v[38:39], v[6:7]
	ds_bpermute_b32 v6, v157, v4
	ds_bpermute_b32 v7, v157, v5
	ds_bpermute_b32 v61, v158, v81
	s_waitcnt lgkmcnt(3)
	v_pk_add_f32 v[2:3], v[36:37], v[2:3]
	ds_bpermute_b32 v8, v157, v2
	ds_bpermute_b32 v9, v157, v3
	s_waitcnt lgkmcnt(3)
	v_pk_add_f32 v[36:37], v[4:5], v[6:7]
	ds_bpermute_b32 v4, v156, v32
	ds_bpermute_b32 v5, v156, v33
	ds_bpermute_b32 v84, v158, v82
	s_waitcnt lgkmcnt(3)
	v_pk_add_f32 v[118:119], v[2:3], v[8:9]
	ds_bpermute_b32 v2, v156, v34
	ds_bpermute_b32 v3, v156, v35
	s_waitcnt lgkmcnt(3)
	v_pk_add_f32 v[4:5], v[32:33], v[4:5]
	ds_bpermute_b32 v8, v157, v4
	ds_bpermute_b32 v9, v157, v5
	ds_bpermute_b32 v85, v158, v83
	s_waitcnt lgkmcnt(3)
	v_pk_add_f32 v[2:3], v[34:35], v[2:3]
	ds_bpermute_b32 v6, v157, v2
	ds_bpermute_b32 v7, v157, v3
	s_waitcnt lgkmcnt(3)
	v_pk_add_f32 v[122:123], v[4:5], v[8:9]
	ds_bpermute_b32 v58, v158, v56
	ds_bpermute_b32 v59, v158, v57
	ds_bpermute_b32 v100, v158, v86
	s_waitcnt lgkmcnt(3)
	v_pk_add_f32 v[32:33], v[2:3], v[6:7]
	v_pk_add_f32 v[2:3], v[30:31], v[124:125]
	ds_bpermute_b32 v4, v157, v2
	ds_bpermute_b32 v5, v157, v3
	ds_bpermute_b32 v6, v156, v28
	ds_bpermute_b32 v7, v156, v29
	ds_bpermute_b32 v101, v158, v87
	ds_bpermute_b32 v54, v158, v52
	s_waitcnt lgkmcnt(4)
	v_pk_add_f32 v[124:125], v[2:3], v[4:5]
	ds_bpermute_b32 v2, v156, v26
	ds_bpermute_b32 v3, v156, v27
	s_waitcnt lgkmcnt(4)
	v_pk_add_f32 v[4:5], v[28:29], v[6:7]
	ds_bpermute_b32 v6, v157, v4
	ds_bpermute_b32 v7, v157, v5
	ds_bpermute_b32 v55, v158, v53
	s_waitcnt lgkmcnt(3)
	v_pk_add_f32 v[2:3], v[26:27], v[2:3]
	ds_bpermute_b32 v8, v157, v2
	ds_bpermute_b32 v9, v157, v3
	s_waitcnt lgkmcnt(3)
	v_pk_add_f32 v[26:27], v[4:5], v[6:7]
	ds_bpermute_b32 v4, v156, v22
	ds_bpermute_b32 v5, v156, v23
	ds_bpermute_b32 v50, v158, v102
	s_waitcnt lgkmcnt(3)
	v_pk_add_f32 v[128:129], v[2:3], v[8:9]
	ds_bpermute_b32 v2, v156, v24
	ds_bpermute_b32 v3, v156, v25
	s_waitcnt lgkmcnt(3)
	v_pk_add_f32 v[4:5], v[22:23], v[4:5]
	ds_bpermute_b32 v8, v157, v4
	ds_bpermute_b32 v9, v157, v5
	ds_bpermute_b32 v51, v158, v103
	s_waitcnt lgkmcnt(3)
	v_pk_add_f32 v[2:3], v[24:25], v[2:3]
	ds_bpermute_b32 v6, v157, v2
	ds_bpermute_b32 v7, v157, v3
	s_waitcnt lgkmcnt(3)
	v_pk_add_f32 v[132:133], v[4:5], v[8:9]
	ds_bpermute_b32 v106, v158, v104
	ds_bpermute_b32 v107, v158, v105
	ds_bpermute_b32 v48, v158, v46
	s_waitcnt lgkmcnt(3)
	v_pk_add_f32 v[22:23], v[2:3], v[6:7]
	v_pk_add_f32 v[2:3], v[20:21], v[134:135]
	ds_bpermute_b32 v4, v157, v2
	ds_bpermute_b32 v5, v157, v3
	ds_bpermute_b32 v6, v156, v98
	ds_bpermute_b32 v7, v156, v99
	ds_bpermute_b32 v49, v158, v47
	ds_bpermute_b32 v110, v158, v108
	s_waitcnt lgkmcnt(4)
	v_pk_add_f32 v[134:135], v[2:3], v[4:5]
	ds_bpermute_b32 v2, v156, v96
	ds_bpermute_b32 v3, v156, v97
	s_waitcnt lgkmcnt(4)
	v_pk_add_f32 v[4:5], v[98:99], v[6:7]
	ds_bpermute_b32 v6, v157, v4
	ds_bpermute_b32 v7, v157, v5
	ds_bpermute_b32 v111, v158, v109
	s_waitcnt lgkmcnt(3)
	v_pk_add_f32 v[2:3], v[96:97], v[2:3]
	ds_bpermute_b32 v8, v157, v2
	ds_bpermute_b32 v9, v157, v3
	s_waitcnt lgkmcnt(3)
	v_pk_add_f32 v[96:97], v[4:5], v[6:7]
	ds_bpermute_b32 v4, v156, v92
	ds_bpermute_b32 v5, v156, v93
	ds_bpermute_b32 v44, v158, v42
	s_waitcnt lgkmcnt(3)
	v_pk_add_f32 v[138:139], v[2:3], v[8:9]
	ds_bpermute_b32 v2, v156, v94
	ds_bpermute_b32 v3, v156, v95
	s_waitcnt lgkmcnt(3)
	v_pk_add_f32 v[4:5], v[92:93], v[4:5]
	ds_bpermute_b32 v8, v157, v4
	ds_bpermute_b32 v9, v157, v5
	ds_bpermute_b32 v45, v158, v43
	s_waitcnt lgkmcnt(3)
	v_pk_add_f32 v[2:3], v[94:95], v[2:3]
	ds_bpermute_b32 v6, v157, v2
	ds_bpermute_b32 v7, v157, v3
	s_waitcnt lgkmcnt(3)
	v_pk_add_f32 v[142:143], v[4:5], v[8:9]
	ds_bpermute_b32 v40, v158, v112
	ds_bpermute_b32 v41, v158, v113
	ds_bpermute_b32 v116, v158, v114
	s_waitcnt lgkmcnt(3)
	v_pk_add_f32 v[92:93], v[2:3], v[6:7]
	v_pk_add_f32 v[2:3], v[90:91], v[144:145]
	ds_bpermute_b32 v4, v157, v2
	ds_bpermute_b32 v5, v157, v3
	ds_bpermute_b32 v6, v156, v88
	ds_bpermute_b32 v7, v156, v89
	ds_bpermute_b32 v117, v158, v115
	ds_bpermute_b32 v38, v158, v36
	s_waitcnt lgkmcnt(4)
	v_pk_add_f32 v[144:145], v[2:3], v[4:5]
	ds_bpermute_b32 v2, v156, v78
	ds_bpermute_b32 v3, v156, v79
	s_waitcnt lgkmcnt(4)
	v_pk_add_f32 v[4:5], v[88:89], v[6:7]
	ds_bpermute_b32 v6, v157, v4
	ds_bpermute_b32 v7, v157, v5
	ds_bpermute_b32 v39, v158, v37
	s_waitcnt lgkmcnt(3)
	v_pk_add_f32 v[2:3], v[78:79], v[2:3]
	ds_bpermute_b32 v8, v157, v2
	ds_bpermute_b32 v9, v157, v3
	s_waitcnt lgkmcnt(3)
	v_pk_add_f32 v[78:79], v[4:5], v[6:7]
	ds_bpermute_b32 v4, v156, v74
	ds_bpermute_b32 v5, v156, v75
	ds_bpermute_b32 v120, v158, v118
	s_waitcnt lgkmcnt(3)
	v_pk_add_f32 v[148:149], v[2:3], v[8:9]
	ds_bpermute_b32 v2, v156, v76
	ds_bpermute_b32 v3, v156, v77
	s_waitcnt lgkmcnt(3)
	v_pk_add_f32 v[4:5], v[74:75], v[4:5]
	ds_bpermute_b32 v8, v157, v4
	ds_bpermute_b32 v9, v157, v5
	ds_bpermute_b32 v121, v158, v119
	s_waitcnt lgkmcnt(3)
	v_pk_add_f32 v[2:3], v[76:77], v[2:3]
	ds_bpermute_b32 v6, v157, v2
	ds_bpermute_b32 v7, v157, v3
	ds_bpermute_b32 v34, v158, v32
	ds_bpermute_b32 v35, v158, v33
	ds_bpermute_b32 v30, v158, v122
	ds_bpermute_b32 v31, v158, v123
	s_waitcnt lgkmcnt(4)
	v_pk_add_f32 v[74:75], v[2:3], v[6:7]
	v_pk_add_f32 v[2:3], v[72:73], v[152:153]
	v_pk_add_f32 v[6:7], v[4:5], v[8:9]
	ds_bpermute_b32 v4, v157, v2
	ds_bpermute_b32 v5, v157, v3
	ds_bpermute_b32 v126, v158, v124
	ds_bpermute_b32 v127, v158, v125
	ds_bpermute_b32 v28, v158, v26
	ds_bpermute_b32 v29, v158, v27
	s_waitcnt lgkmcnt(4)
	v_pk_add_f32 v[8:9], v[2:3], v[4:5]
	ds_bpermute_b32 v2, v156, v68
	ds_bpermute_b32 v3, v156, v69
	v_pk_add_f32 v[4:5], v[70:71], v[162:163]
	ds_bpermute_b32 v70, v157, v4
	ds_bpermute_b32 v71, v157, v5
	ds_bpermute_b32 v130, v158, v128
	s_waitcnt lgkmcnt(3)
	v_pk_add_f32 v[162:163], v[68:69], v[2:3]
	ds_bpermute_b32 v164, v157, v162
	ds_bpermute_b32 v165, v157, v163
	s_waitcnt lgkmcnt(3)
	v_pk_add_f32 v[2:3], v[4:5], v[70:71]
	ds_bpermute_b32 v131, v158, v129
	ds_bpermute_b32 v24, v158, v22
	ds_bpermute_b32 v25, v158, v23
	s_waitcnt lgkmcnt(3)
	v_pk_add_f32 v[4:5], v[162:163], v[164:165]
	ds_bpermute_b32 v20, v158, v132
	ds_bpermute_b32 v21, v158, v133
	ds_bpermute_b32 v136, v158, v134
	ds_bpermute_b32 v137, v158, v135
	ds_bpermute_b32 v98, v158, v96
	ds_bpermute_b32 v99, v158, v97
	ds_bpermute_b32 v140, v158, v138
	ds_bpermute_b32 v141, v158, v139
	ds_bpermute_b32 v94, v158, v92
	ds_bpermute_b32 v95, v158, v93
	ds_bpermute_b32 v90, v158, v142
	ds_bpermute_b32 v91, v158, v143
	ds_bpermute_b32 v146, v158, v144
	ds_bpermute_b32 v147, v158, v145
	ds_bpermute_b32 v88, v158, v78
	ds_bpermute_b32 v89, v158, v79
	ds_bpermute_b32 v150, v158, v148
	ds_bpermute_b32 v151, v158, v149
	ds_bpermute_b32 v76, v158, v74
	ds_bpermute_b32 v77, v158, v75
	ds_bpermute_b32 v72, v158, v6
	ds_bpermute_b32 v73, v158, v7
	ds_bpermute_b32 v152, v158, v8
	ds_bpermute_b32 v153, v158, v9
	ds_bpermute_b32 v68, v158, v2
	ds_bpermute_b32 v69, v158, v3
	ds_bpermute_b32 v70, v158, v4
	ds_bpermute_b32 v71, v158, v5
	s_and_saveexec_b64 s[14:15], s[6:7]
	s_cbranch_execz .LBB0_16
	s_lshl_b32 s13, s27, 1
	s_add_i32 s13, s13, s12
	v_lshl_add_u64 v[16:17], v[16:17], 2, s[10:11]
	v_mad_i64_i32 v[16:17], s[12:13], s13, v160, v[16:17]
	v_pk_add_f32 v[46:47], v[46:47], v[48:49]
	v_pk_add_f32 v[48:49], v[52:53], v[54:55]
	v_pk_add_f32 v[52:53], v[56:57], v[58:59]
	v_pk_add_f32 v[56:57], v[80:81], v[60:61]
	v_pk_add_f32 v[60:61], v[18:19], v[64:65]
	v_add_co_u32_e32 v18, vcc, s2, v16
	v_pk_add_f32 v[58:59], v[82:83], v[84:85]
	s_nop 0
	v_addc_co_u32_e32 v19, vcc, 0, v17, vcc
	s_mov_b32 s12, 0xc000
	global_store_dwordx4 v[18:19], v[56:59], off
	v_add_co_u32_e32 v18, vcc, s12, v16
	v_pk_add_f32 v[54:55], v[86:87], v[100:101]
	s_nop 0
	v_addc_co_u32_e32 v19, vcc, 0, v17, vcc
	s_mov_b32 s12, 0x12000
	global_store_dwordx4 v[18:19], v[52:55], off
	v_add_co_u32_e32 v18, vcc, s12, v16
	v_pk_add_f32 v[50:51], v[102:103], v[50:51]
	s_nop 0
	v_addc_co_u32_e32 v19, vcc, 0, v17, vcc
	s_mov_b32 s12, 0x18000
	global_store_dwordx4 v[18:19], v[48:51], off
	v_add_co_u32_e32 v18, vcc, s12, v16
	v_pk_add_f32 v[42:43], v[42:43], v[44:45]
	v_pk_add_f32 v[44:45], v[104:105], v[106:107]
	v_addc_co_u32_e32 v19, vcc, 0, v17, vcc
	s_mov_b32 s12, 0x1e000
	global_store_dwordx4 v[18:19], v[44:47], off
	v_add_co_u32_e32 v18, vcc, s12, v16
	v_pk_add_f32 v[26:27], v[26:27], v[28:29]
	v_pk_add_f32 v[28:29], v[32:33], v[34:35]
	v_pk_add_f32 v[32:33], v[36:37], v[38:39]
	v_pk_add_f32 v[36:37], v[112:113], v[40:41]
	v_pk_add_f32 v[40:41], v[108:109], v[110:111]
	v_addc_co_u32_e32 v19, vcc, 0, v17, vcc
	s_mov_b32 s12, 0x24000
	global_store_dwordx4 v[18:19], v[40:43], off
	v_add_co_u32_e32 v18, vcc, s12, v16
	v_pk_add_f32 v[38:39], v[114:115], v[116:117]
	s_nop 0
	v_addc_co_u32_e32 v19, vcc, 0, v17, vcc
	global_store_dwordx4 v[18:19], v[36:39], off
	v_add_co_u32_e32 v18, vcc, s20, v16
	v_pk_add_f32 v[34:35], v[118:119], v[120:121]
	s_nop 0
	v_addc_co_u32_e32 v19, vcc, 0, v17, vcc
	global_store_dwordx4 v[18:19], v[32:35], off
	v_add_co_u32_e32 v18, vcc, s3, v16
	v_pk_add_f32 v[30:31], v[122:123], v[30:31]
	s_nop 0
	v_addc_co_u32_e32 v19, vcc, 0, v17, vcc
	global_store_dwordx4 v[18:19], v[28:31], off
	v_add_co_u32_e32 v18, vcc, s21, v16
	s_waitcnt lgkmcnt(14)
	v_pk_add_f32 v[22:23], v[22:23], v[24:25]
	v_pk_add_f32 v[24:25], v[124:125], v[126:127]
	v_addc_co_u32_e32 v19, vcc, 0, v17, vcc
	global_store_dwordx4 v[18:19], v[24:27], off
	v_add_co_u32_e32 v18, vcc, s22, v16
	s_waitcnt lgkmcnt(0)
	v_pk_add_f32 v[4:5], v[4:5], v[70:71]
	v_pk_add_f32 v[70:71], v[74:75], v[76:77]
	v_pk_add_f32 v[76:77], v[92:93], v[94:95]
	v_pk_add_f32 v[92:93], v[132:133], v[20:21]
	v_pk_add_f32 v[20:21], v[128:129], v[130:131]
	v_addc_co_u32_e32 v19, vcc, 0, v17, vcc
	global_store_dwordx4 v[18:19], v[20:23], off
	v_add_co_u32_e32 v18, vcc, s23, v16
	v_pk_add_f32 v[94:95], v[134:135], v[136:137]
	s_nop 0
	v_addc_co_u32_e32 v19, vcc, 0, v17, vcc
	global_store_dwordx4 v[18:19], v[92:95], off
	v_add_co_u32_e32 v18, vcc, s24, v16
	v_pk_add_f32 v[74:75], v[78:79], v[88:89]
	v_pk_add_f32 v[78:79], v[142:143], v[90:91]
	v_pk_add_f32 v[90:91], v[138:139], v[140:141]
	v_pk_add_f32 v[88:89], v[96:97], v[98:99]
	v_addc_co_u32_e32 v19, vcc, 0, v17, vcc
	global_store_dwordx4 v[18:19], v[88:91], off
	v_add_co_u32_e32 v18, vcc, s25, v16
	v_pk_add_f32 v[6:7], v[6:7], v[72:73]
	s_nop 0
	v_addc_co_u32_e32 v19, vcc, 0, v17, vcc
	global_store_dwordx4 v[18:19], v[76:79], off
	v_add_co_u32_e32 v18, vcc, 0x54000, v16
	v_pk_add_f32 v[72:73], v[144:145], v[146:147]
	s_nop 0
	v_addc_co_u32_e32 v19, vcc, 0, v17, vcc
	global_store_dwordx4 v[18:19], v[72:75], off
	v_add_co_u32_e32 v18, vcc, 0x5a000, v16
	v_pk_add_f32 v[2:3], v[2:3], v[68:69]
	v_pk_add_f32 v[68:69], v[148:149], v[150:151]
	v_addc_co_u32_e32 v19, vcc, 0, v17, vcc
	global_store_dwordx4 v[18:19], v[68:71], off
	v_add_co_u32_e32 v18, vcc, 0x60000, v16
	v_pk_add_f32 v[8:9], v[8:9], v[152:153]
	s_nop 0
	v_addc_co_u32_e32 v19, vcc, 0, v17, vcc
	global_store_dwordx4 v[18:19], v[6:9], off
	v_pk_add_f32 v[62:63], v[62:63], v[66:67]
	global_store_dwordx4 v[16:17], v[60:63], off
	v_add_co_u32_e32 v6, vcc, 0x66000, v16
	s_nop 1
	v_addc_co_u32_e32 v7, vcc, 0, v17, vcc
	global_store_dwordx4 v[6:7], v[2:5], off
	s_branch .LBB0_16

.LBB0_2028:
	v_lshl_or_b32 v129, s23, 6, v129
	s_or_b32 s24, s24, s44
	v_lshl_or_b32 v135, v128, 2, s45
	v_lshl_add_u32 v149, s22, 8, v129
	s_ashr_i32 s25, s24, 31
	s_lshl_b64 s[22:23], s[24:25], 2
	s_add_u32 s22, s42, s22
	s_addc_u32 s23, s43, s23
	v_or_b32_e32 v132, s24, v135
	v_lshlrev_b32_e32 v129, 2, v135
	v_lshl_add_u32 v130, v149, 11, v132
	v_lshlrev_b32_e32 v130, 1, v130
	global_load_dwordx4 v[140:143], v129, s[22:23]
	global_load_dwordx4 v[144:147], v129, s[22:23] offset:64
	global_load_dwordx4 v[150:153], v129, s[22:23] offset:512
	global_load_dwordx4 v[154:157], v129, s[22:23] offset:576
	v_add_u32_e32 v131, 0x10000, v130
	v_add_u32_e32 v132, 0x20000, v130
	v_add_u32_e32 v133, 0x30000, v130
	v_add_u32_e32 v135, 0x80000, v130
	v_add_u32_e32 v138, 0x90000, v130
	v_add_u32_e32 v139, 0xa0000, v130
	v_add_u32_e32 v148, 0xb0000, v130
	global_load_dwordx2 v[158:159], v130, s[38:39]
	global_load_dwordx2 v[160:161], v130, s[38:39] offset:32
	global_load_dwordx2 v[162:163], v130, s[38:39] offset:256
	global_load_dwordx2 v[164:165], v130, s[38:39] offset:288
	global_load_dwordx2 v[166:167], v131, s[38:39]
	global_load_dwordx2 v[168:169], v131, s[38:39] offset:32
	global_load_dwordx2 v[170:171], v131, s[38:39] offset:256
	global_load_dwordx2 v[178:179], v131, s[38:39] offset:288
	global_load_dwordx2 v[180:181], v132, s[38:39]
	global_load_dwordx2 v[182:183], v132, s[38:39] offset:32
	global_load_dwordx2 v[184:185], v132, s[38:39] offset:256
	global_load_dwordx2 v[186:187], v132, s[38:39] offset:288
	global_load_dwordx2 v[188:189], v133, s[38:39]
	global_load_dwordx2 v[190:191], v133, s[38:39] offset:32
	global_load_dwordx2 v[192:193], v133, s[38:39] offset:256
	global_load_dwordx2 v[194:195], v133, s[38:39] offset:288
	global_load_dwordx2 v[196:197], v135, s[38:39]
	global_load_dwordx2 v[198:199], v135, s[38:39] offset:32
	global_load_dwordx2 v[200:201], v135, s[38:39] offset:256
	global_load_dwordx2 v[202:203], v135, s[38:39] offset:288
	global_load_dwordx2 v[204:205], v138, s[38:39]
	global_load_dwordx2 v[206:207], v138, s[38:39] offset:32
	global_load_dwordx2 v[208:209], v138, s[38:39] offset:256
	global_load_dwordx2 v[210:211], v138, s[38:39] offset:288
	global_load_dwordx2 v[212:213], v139, s[38:39]
	global_load_dwordx2 v[214:215], v139, s[38:39] offset:32
	global_load_dwordx2 v[216:217], v139, s[38:39] offset:256
	global_load_dwordx2 v[218:219], v139, s[38:39] offset:288
	global_load_dwordx2 v[220:221], v148, s[38:39]
	global_load_dwordx2 v[222:223], v148, s[38:39] offset:32
	global_load_dwordx2 v[224:225], v148, s[38:39] offset:256
	global_load_dwordx2 v[226:227], v148, s[38:39] offset:288
	v_and_b32_e32 v136, 1, v128
	v_mul_u32_u24_e32 v136, 40, v136
	v_sub_u32_e32 v136, 32, v136
	v_add_u32_e32 v130, v130, v136
	v_add_u32_e32 v131, v131, v136
	v_add_u32_e32 v132, v132, v136
	v_add_u32_e32 v133, v133, v136
	v_add_u32_e32 v135, v135, v136
	v_add_u32_e32 v138, v138, v136
	v_add_u32_e32 v139, v139, v136
	v_add_u32_e32 v148, v148, v136
	s_waitcnt vmcnt(31)
	v_lshlrev_b32_e32 v136, 16, v158
	v_and_b32_e32 v137, 0xffff0000, v158
	v_lshlrev_b32_e32 v158, 16, v159
	v_and_b32_e32 v159, 0xffff0000, v159
	v_pk_mul_f32 v[126:127], v[126:127], v[142:143]
	v_pk_mul_f32 v[124:125], v[124:125], v[140:141]
	v_pk_mul_f32 v[126:127], v[126:127], v[158:159]
	v_pk_mul_f32 v[124:125], v[124:125], v[136:137]
	s_waitcnt vmcnt(30)
	v_lshlrev_b32_e32 v136, 16, v160
	v_and_b32_e32 v137, 0xffff0000, v160
	v_lshlrev_b32_e32 v160, 16, v161
	v_and_b32_e32 v161, 0xffff0000, v161
	v_pk_mul_f32 v[122:123], v[122:123], v[146:147]
	v_pk_mul_f32 v[120:121], v[120:121], v[144:145]
	v_pk_mul_f32 v[122:123], v[122:123], v[160:161]
	v_pk_mul_f32 v[120:121], v[120:121], v[136:137]
	s_nop 0
	v_cvt_pk_bf16_f32 v120, v120, v121
	v_cvt_pk_bf16_f32 v121, v122, v123
	v_cvt_pk_bf16_f32 v122, v124, v125
	v_cvt_pk_bf16_f32 v123, v126, v127
	s_nop 1
	v_permlane16_swap_b32_e32 v120, v122
	v_permlane16_swap_b32_e32 v121, v123
	global_store_dwordx4 v130, v[120:123], s[0:1]
	s_waitcnt vmcnt(30)
	v_lshlrev_b32_e32 v136, 16, v162
	v_and_b32_e32 v137, 0xffff0000, v162
	v_lshlrev_b32_e32 v162, 16, v163
	v_and_b32_e32 v163, 0xffff0000, v163
	v_pk_mul_f32 v[118:119], v[118:119], v[152:153]
	v_pk_mul_f32 v[116:117], v[116:117], v[150:151]
	v_pk_mul_f32 v[118:119], v[118:119], v[162:163]
	v_pk_mul_f32 v[116:117], v[116:117], v[136:137]
	s_waitcnt vmcnt(29)
	v_lshlrev_b32_e32 v136, 16, v164
	v_and_b32_e32 v137, 0xffff0000, v164
	v_lshlrev_b32_e32 v164, 16, v165
	v_and_b32_e32 v165, 0xffff0000, v165
	v_pk_mul_f32 v[114:115], v[114:115], v[156:157]
	v_pk_mul_f32 v[112:113], v[112:113], v[154:155]
	v_pk_mul_f32 v[114:115], v[114:115], v[164:165]
	v_pk_mul_f32 v[112:113], v[112:113], v[136:137]
	s_nop 0
	v_cvt_pk_bf16_f32 v112, v112, v113
	v_cvt_pk_bf16_f32 v113, v114, v115
	v_cvt_pk_bf16_f32 v114, v116, v117
	v_cvt_pk_bf16_f32 v115, v118, v119
	s_nop 1
	v_permlane16_swap_b32_e32 v112, v114
	v_permlane16_swap_b32_e32 v113, v115
	global_store_dwordx4 v130, v[112:115], s[0:1] offset:256
	s_waitcnt vmcnt(29)
	v_lshlrev_b32_e32 v136, 16, v166
	v_and_b32_e32 v137, 0xffff0000, v166
	v_lshlrev_b32_e32 v166, 16, v167
	v_and_b32_e32 v167, 0xffff0000, v167
	v_pk_mul_f32 v[110:111], v[110:111], v[142:143]
	v_pk_mul_f32 v[108:109], v[108:109], v[140:141]
	v_pk_mul_f32 v[110:111], v[110:111], v[166:167]
	v_pk_mul_f32 v[108:109], v[108:109], v[136:137]
	s_waitcnt vmcnt(28)
	v_lshlrev_b32_e32 v136, 16, v168
	v_and_b32_e32 v137, 0xffff0000, v168
	v_lshlrev_b32_e32 v168, 16, v169
	v_and_b32_e32 v169, 0xffff0000, v169
	v_pk_mul_f32 v[106:107], v[106:107], v[146:147]
	v_pk_mul_f32 v[104:105], v[104:105], v[144:145]
	v_pk_mul_f32 v[106:107], v[106:107], v[168:169]
	v_pk_mul_f32 v[104:105], v[104:105], v[136:137]
	s_nop 0
	v_cvt_pk_bf16_f32 v104, v104, v105
	v_cvt_pk_bf16_f32 v105, v106, v107
	v_cvt_pk_bf16_f32 v106, v108, v109
	v_cvt_pk_bf16_f32 v107, v110, v111
	s_nop 1
	v_permlane16_swap_b32_e32 v104, v106
	v_permlane16_swap_b32_e32 v105, v107
	global_store_dwordx4 v131, v[104:107], s[0:1]
	s_waitcnt vmcnt(28)
	v_lshlrev_b32_e32 v136, 16, v170
	v_and_b32_e32 v137, 0xffff0000, v170
	v_lshlrev_b32_e32 v170, 16, v171
	v_and_b32_e32 v171, 0xffff0000, v171
	v_pk_mul_f32 v[102:103], v[102:103], v[152:153]
	v_pk_mul_f32 v[100:101], v[100:101], v[150:151]
	v_pk_mul_f32 v[102:103], v[102:103], v[170:171]
	v_pk_mul_f32 v[100:101], v[100:101], v[136:137]
	s_waitcnt vmcnt(27)
	v_lshlrev_b32_e32 v136, 16, v178
	v_and_b32_e32 v137, 0xffff0000, v178
	v_lshlrev_b32_e32 v178, 16, v179
	v_and_b32_e32 v179, 0xffff0000, v179
	v_pk_mul_f32 v[98:99], v[98:99], v[156:157]
	v_pk_mul_f32 v[96:97], v[96:97], v[154:155]
	v_pk_mul_f32 v[98:99], v[98:99], v[178:179]
	v_pk_mul_f32 v[96:97], v[96:97], v[136:137]
	s_nop 0
	v_cvt_pk_bf16_f32 v96, v96, v97
	v_cvt_pk_bf16_f32 v97, v98, v99
	v_cvt_pk_bf16_f32 v98, v100, v101
	v_cvt_pk_bf16_f32 v99, v102, v103
	s_nop 1
	v_permlane16_swap_b32_e32 v96, v98
	v_permlane16_swap_b32_e32 v97, v99
	global_store_dwordx4 v131, v[96:99], s[0:1] offset:256
	s_waitcnt vmcnt(27)
	v_lshlrev_b32_e32 v136, 16, v180
	v_and_b32_e32 v137, 0xffff0000, v180
	v_lshlrev_b32_e32 v180, 16, v181
	v_and_b32_e32 v181, 0xffff0000, v181
	v_pk_mul_f32 v[94:95], v[94:95], v[142:143]
	v_pk_mul_f32 v[92:93], v[92:93], v[140:141]
	v_pk_mul_f32 v[94:95], v[94:95], v[180:181]
	v_pk_mul_f32 v[92:93], v[92:93], v[136:137]
	s_waitcnt vmcnt(26)
	v_lshlrev_b32_e32 v136, 16, v182
	v_and_b32_e32 v137, 0xffff0000, v182
	v_lshlrev_b32_e32 v182, 16, v183
	v_and_b32_e32 v183, 0xffff0000, v183
	v_pk_mul_f32 v[90:91], v[90:91], v[146:147]
	v_pk_mul_f32 v[88:89], v[88:89], v[144:145]
	v_pk_mul_f32 v[90:91], v[90:91], v[182:183]
	v_pk_mul_f32 v[88:89], v[88:89], v[136:137]
	s_nop 0
	v_cvt_pk_bf16_f32 v88, v88, v89
	v_cvt_pk_bf16_f32 v89, v90, v91
	v_cvt_pk_bf16_f32 v90, v92, v93
	v_cvt_pk_bf16_f32 v91, v94, v95
	s_nop 1
	v_permlane16_swap_b32_e32 v88, v90
	v_permlane16_swap_b32_e32 v89, v91
	global_store_dwordx4 v132, v[88:91], s[0:1]
	s_waitcnt vmcnt(26)
	v_lshlrev_b32_e32 v136, 16, v184
	v_and_b32_e32 v137, 0xffff0000, v184
	v_lshlrev_b32_e32 v184, 16, v185
	v_and_b32_e32 v185, 0xffff0000, v185
	v_pk_mul_f32 v[86:87], v[86:87], v[152:153]
	v_pk_mul_f32 v[84:85], v[84:85], v[150:151]
	v_pk_mul_f32 v[86:87], v[86:87], v[184:185]
	v_pk_mul_f32 v[84:85], v[84:85], v[136:137]
	s_waitcnt vmcnt(25)
	v_lshlrev_b32_e32 v136, 16, v186
	v_and_b32_e32 v137, 0xffff0000, v186
	v_lshlrev_b32_e32 v186, 16, v187
	v_and_b32_e32 v187, 0xffff0000, v187
	v_pk_mul_f32 v[82:83], v[82:83], v[156:157]
	v_pk_mul_f32 v[80:81], v[80:81], v[154:155]
	v_pk_mul_f32 v[82:83], v[82:83], v[186:187]
	v_pk_mul_f32 v[80:81], v[80:81], v[136:137]
	s_nop 0
	v_cvt_pk_bf16_f32 v80, v80, v81
	v_cvt_pk_bf16_f32 v81, v82, v83
	v_cvt_pk_bf16_f32 v82, v84, v85
	v_cvt_pk_bf16_f32 v83, v86, v87
	s_nop 1
	v_permlane16_swap_b32_e32 v80, v82
	v_permlane16_swap_b32_e32 v81, v83
	global_store_dwordx4 v132, v[80:83], s[0:1] offset:256
	s_waitcnt vmcnt(25)
	v_lshlrev_b32_e32 v136, 16, v188
	v_and_b32_e32 v137, 0xffff0000, v188
	v_lshlrev_b32_e32 v188, 16, v189
	v_and_b32_e32 v189, 0xffff0000, v189
	v_pk_mul_f32 v[78:79], v[78:79], v[142:143]
	v_pk_mul_f32 v[76:77], v[76:77], v[140:141]
	v_pk_mul_f32 v[78:79], v[78:79], v[188:189]
	v_pk_mul_f32 v[76:77], v[76:77], v[136:137]
	s_waitcnt vmcnt(24)
	v_lshlrev_b32_e32 v136, 16, v190
	v_and_b32_e32 v137, 0xffff0000, v190
	v_lshlrev_b32_e32 v190, 16, v191
	v_and_b32_e32 v191, 0xffff0000, v191
	v_pk_mul_f32 v[74:75], v[74:75], v[146:147]
	v_pk_mul_f32 v[72:73], v[72:73], v[144:145]
	v_pk_mul_f32 v[74:75], v[74:75], v[190:191]
	v_pk_mul_f32 v[72:73], v[72:73], v[136:137]
	s_nop 0
	v_cvt_pk_bf16_f32 v72, v72, v73
	v_cvt_pk_bf16_f32 v73, v74, v75
	v_cvt_pk_bf16_f32 v74, v76, v77
	v_cvt_pk_bf16_f32 v75, v78, v79
	s_nop 1
	v_permlane16_swap_b32_e32 v72, v74
	v_permlane16_swap_b32_e32 v73, v75
	global_store_dwordx4 v133, v[72:75], s[0:1]
	s_waitcnt vmcnt(24)
	v_lshlrev_b32_e32 v136, 16, v192
	v_and_b32_e32 v137, 0xffff0000, v192
	v_lshlrev_b32_e32 v192, 16, v193
	v_and_b32_e32 v193, 0xffff0000, v193
	v_pk_mul_f32 v[70:71], v[70:71], v[152:153]
	v_pk_mul_f32 v[68:69], v[68:69], v[150:151]
	v_pk_mul_f32 v[70:71], v[70:71], v[192:193]
	v_pk_mul_f32 v[68:69], v[68:69], v[136:137]
	s_waitcnt vmcnt(23)
	v_lshlrev_b32_e32 v136, 16, v194
	v_and_b32_e32 v137, 0xffff0000, v194
	v_lshlrev_b32_e32 v194, 16, v195
	v_and_b32_e32 v195, 0xffff0000, v195
	v_pk_mul_f32 v[66:67], v[66:67], v[156:157]
	v_pk_mul_f32 v[64:65], v[64:65], v[154:155]
	v_pk_mul_f32 v[66:67], v[66:67], v[194:195]
	v_pk_mul_f32 v[64:65], v[64:65], v[136:137]
	s_nop 0
	v_cvt_pk_bf16_f32 v64, v64, v65
	v_cvt_pk_bf16_f32 v65, v66, v67
	v_cvt_pk_bf16_f32 v66, v68, v69
	v_cvt_pk_bf16_f32 v67, v70, v71
	s_nop 1
	v_permlane16_swap_b32_e32 v64, v66
	v_permlane16_swap_b32_e32 v65, v67
	global_store_dwordx4 v133, v[64:67], s[0:1] offset:256
	s_waitcnt vmcnt(23)
	v_lshlrev_b32_e32 v136, 16, v196
	v_and_b32_e32 v137, 0xffff0000, v196
	v_lshlrev_b32_e32 v196, 16, v197
	v_and_b32_e32 v197, 0xffff0000, v197
	v_pk_mul_f32 v[62:63], v[62:63], v[142:143]
	v_pk_mul_f32 v[60:61], v[60:61], v[140:141]
	v_pk_mul_f32 v[62:63], v[62:63], v[196:197]
	v_pk_mul_f32 v[60:61], v[60:61], v[136:137]
	s_waitcnt vmcnt(22)
	v_lshlrev_b32_e32 v136, 16, v198
	v_and_b32_e32 v137, 0xffff0000, v198
	v_lshlrev_b32_e32 v198, 16, v199
	v_and_b32_e32 v199, 0xffff0000, v199
	v_pk_mul_f32 v[58:59], v[58:59], v[146:147]
	v_pk_mul_f32 v[56:57], v[56:57], v[144:145]
	v_pk_mul_f32 v[58:59], v[58:59], v[198:199]
	v_pk_mul_f32 v[56:57], v[56:57], v[136:137]
	s_nop 0
	v_cvt_pk_bf16_f32 v56, v56, v57
	v_cvt_pk_bf16_f32 v57, v58, v59
	v_cvt_pk_bf16_f32 v58, v60, v61
	v_cvt_pk_bf16_f32 v59, v62, v63
	s_nop 1
	v_permlane16_swap_b32_e32 v56, v58
	v_permlane16_swap_b32_e32 v57, v59
	global_store_dwordx4 v135, v[56:59], s[0:1]
	s_waitcnt vmcnt(22)
	v_lshlrev_b32_e32 v136, 16, v200
	v_and_b32_e32 v137, 0xffff0000, v200
	v_lshlrev_b32_e32 v200, 16, v201
	v_and_b32_e32 v201, 0xffff0000, v201
	v_pk_mul_f32 v[54:55], v[54:55], v[152:153]
	v_pk_mul_f32 v[52:53], v[52:53], v[150:151]
	v_pk_mul_f32 v[54:55], v[54:55], v[200:201]
	v_pk_mul_f32 v[52:53], v[52:53], v[136:137]
	s_waitcnt vmcnt(21)
	v_lshlrev_b32_e32 v136, 16, v202
	v_and_b32_e32 v137, 0xffff0000, v202
	v_lshlrev_b32_e32 v202, 16, v203
	v_and_b32_e32 v203, 0xffff0000, v203
	v_pk_mul_f32 v[50:51], v[50:51], v[156:157]
	v_pk_mul_f32 v[48:49], v[48:49], v[154:155]
	v_pk_mul_f32 v[50:51], v[50:51], v[202:203]
	v_pk_mul_f32 v[48:49], v[48:49], v[136:137]
	s_nop 0
	v_cvt_pk_bf16_f32 v48, v48, v49
	v_cvt_pk_bf16_f32 v49, v50, v51
	v_cvt_pk_bf16_f32 v50, v52, v53
	v_cvt_pk_bf16_f32 v51, v54, v55
	s_nop 1
	v_permlane16_swap_b32_e32 v48, v50
	v_permlane16_swap_b32_e32 v49, v51
	global_store_dwordx4 v135, v[48:51], s[0:1] offset:256
	s_waitcnt vmcnt(21)
	v_lshlrev_b32_e32 v136, 16, v204
	v_and_b32_e32 v137, 0xffff0000, v204
	v_lshlrev_b32_e32 v204, 16, v205
	v_and_b32_e32 v205, 0xffff0000, v205
	v_pk_mul_f32 v[46:47], v[46:47], v[142:143]
	v_pk_mul_f32 v[44:45], v[44:45], v[140:141]
	v_pk_mul_f32 v[46:47], v[46:47], v[204:205]
	v_pk_mul_f32 v[44:45], v[44:45], v[136:137]
	s_waitcnt vmcnt(20)
	v_lshlrev_b32_e32 v136, 16, v206
	v_and_b32_e32 v137, 0xffff0000, v206
	v_lshlrev_b32_e32 v206, 16, v207
	v_and_b32_e32 v207, 0xffff0000, v207
	v_pk_mul_f32 v[42:43], v[42:43], v[146:147]
	v_pk_mul_f32 v[40:41], v[40:41], v[144:145]
	v_pk_mul_f32 v[42:43], v[42:43], v[206:207]
	v_pk_mul_f32 v[40:41], v[40:41], v[136:137]
	s_nop 0
	v_cvt_pk_bf16_f32 v40, v40, v41
	v_cvt_pk_bf16_f32 v41, v42, v43
	v_cvt_pk_bf16_f32 v42, v44, v45
	v_cvt_pk_bf16_f32 v43, v46, v47
	s_nop 1
	v_permlane16_swap_b32_e32 v40, v42
	v_permlane16_swap_b32_e32 v41, v43
	global_store_dwordx4 v138, v[40:43], s[0:1]
	s_waitcnt vmcnt(20)
	v_lshlrev_b32_e32 v136, 16, v208
	v_and_b32_e32 v137, 0xffff0000, v208
	v_lshlrev_b32_e32 v208, 16, v209
	v_and_b32_e32 v209, 0xffff0000, v209
	v_pk_mul_f32 v[38:39], v[38:39], v[152:153]
	v_pk_mul_f32 v[36:37], v[36:37], v[150:151]
	v_pk_mul_f32 v[38:39], v[38:39], v[208:209]
	v_pk_mul_f32 v[36:37], v[36:37], v[136:137]
	s_waitcnt vmcnt(19)
	v_lshlrev_b32_e32 v136, 16, v210
	v_and_b32_e32 v137, 0xffff0000, v210
	v_lshlrev_b32_e32 v210, 16, v211
	v_and_b32_e32 v211, 0xffff0000, v211
	v_pk_mul_f32 v[34:35], v[34:35], v[156:157]
	v_pk_mul_f32 v[32:33], v[32:33], v[154:155]
	v_pk_mul_f32 v[34:35], v[34:35], v[210:211]
	v_pk_mul_f32 v[32:33], v[32:33], v[136:137]
	s_nop 0
	v_cvt_pk_bf16_f32 v32, v32, v33
	v_cvt_pk_bf16_f32 v33, v34, v35
	v_cvt_pk_bf16_f32 v34, v36, v37
	v_cvt_pk_bf16_f32 v35, v38, v39
	s_nop 1
	v_permlane16_swap_b32_e32 v32, v34
	v_permlane16_swap_b32_e32 v33, v35
	global_store_dwordx4 v138, v[32:35], s[0:1] offset:256
	s_waitcnt vmcnt(19)
	v_lshlrev_b32_e32 v136, 16, v212
	v_and_b32_e32 v137, 0xffff0000, v212
	v_lshlrev_b32_e32 v212, 16, v213
	v_and_b32_e32 v213, 0xffff0000, v213
	v_pk_mul_f32 v[30:31], v[30:31], v[142:143]
	v_pk_mul_f32 v[28:29], v[28:29], v[140:141]
	v_pk_mul_f32 v[30:31], v[30:31], v[212:213]
	v_pk_mul_f32 v[28:29], v[28:29], v[136:137]
	s_waitcnt vmcnt(18)
	v_lshlrev_b32_e32 v136, 16, v214
	v_and_b32_e32 v137, 0xffff0000, v214
	v_lshlrev_b32_e32 v214, 16, v215
	v_and_b32_e32 v215, 0xffff0000, v215
	v_pk_mul_f32 v[26:27], v[26:27], v[146:147]
	v_pk_mul_f32 v[24:25], v[24:25], v[144:145]
	v_pk_mul_f32 v[26:27], v[26:27], v[214:215]
	v_pk_mul_f32 v[24:25], v[24:25], v[136:137]
	s_nop 0
	v_cvt_pk_bf16_f32 v24, v24, v25
	v_cvt_pk_bf16_f32 v25, v26, v27
	v_cvt_pk_bf16_f32 v26, v28, v29
	v_cvt_pk_bf16_f32 v27, v30, v31
	s_nop 1
	v_permlane16_swap_b32_e32 v24, v26
	v_permlane16_swap_b32_e32 v25, v27
	global_store_dwordx4 v139, v[24:27], s[0:1]
	s_waitcnt vmcnt(18)
	v_lshlrev_b32_e32 v136, 16, v216
	v_and_b32_e32 v137, 0xffff0000, v216
	v_lshlrev_b32_e32 v216, 16, v217
	v_and_b32_e32 v217, 0xffff0000, v217
	v_pk_mul_f32 v[22:23], v[22:23], v[152:153]
	v_pk_mul_f32 v[20:21], v[20:21], v[150:151]
	v_pk_mul_f32 v[22:23], v[22:23], v[216:217]
	v_pk_mul_f32 v[20:21], v[20:21], v[136:137]
	s_waitcnt vmcnt(17)
	v_lshlrev_b32_e32 v136, 16, v218
	v_and_b32_e32 v137, 0xffff0000, v218
	v_lshlrev_b32_e32 v218, 16, v219
	v_and_b32_e32 v219, 0xffff0000, v219
	v_pk_mul_f32 v[18:19], v[18:19], v[156:157]
	v_pk_mul_f32 v[16:17], v[16:17], v[154:155]
	v_pk_mul_f32 v[18:19], v[18:19], v[218:219]
	v_pk_mul_f32 v[16:17], v[16:17], v[136:137]
	s_nop 0
	v_cvt_pk_bf16_f32 v16, v16, v17
	v_cvt_pk_bf16_f32 v17, v18, v19
	v_cvt_pk_bf16_f32 v18, v20, v21
	v_cvt_pk_bf16_f32 v19, v22, v23
	s_nop 1
	v_permlane16_swap_b32_e32 v16, v18
	v_permlane16_swap_b32_e32 v17, v19
	global_store_dwordx4 v139, v[16:19], s[0:1] offset:256
	s_waitcnt vmcnt(17)
	v_lshlrev_b32_e32 v136, 16, v220
	v_and_b32_e32 v137, 0xffff0000, v220
	v_lshlrev_b32_e32 v220, 16, v221
	v_and_b32_e32 v221, 0xffff0000, v221
	v_pk_mul_f32 v[14:15], v[14:15], v[142:143]
	v_pk_mul_f32 v[12:13], v[12:13], v[140:141]
	v_pk_mul_f32 v[14:15], v[14:15], v[220:221]
	v_pk_mul_f32 v[12:13], v[12:13], v[136:137]
	s_waitcnt vmcnt(16)
	v_lshlrev_b32_e32 v136, 16, v222
	v_and_b32_e32 v137, 0xffff0000, v222
	v_lshlrev_b32_e32 v222, 16, v223
	v_and_b32_e32 v223, 0xffff0000, v223
	v_pk_mul_f32 v[10:11], v[10:11], v[146:147]
	v_pk_mul_f32 v[8:9], v[8:9], v[144:145]
	v_pk_mul_f32 v[10:11], v[10:11], v[222:223]
	v_pk_mul_f32 v[8:9], v[8:9], v[136:137]
	s_nop 0
	v_cvt_pk_bf16_f32 v8, v8, v9
	v_cvt_pk_bf16_f32 v9, v10, v11
	v_cvt_pk_bf16_f32 v10, v12, v13
	v_cvt_pk_bf16_f32 v11, v14, v15
	s_nop 1
	v_permlane16_swap_b32_e32 v8, v10
	v_permlane16_swap_b32_e32 v9, v11
	global_store_dwordx4 v148, v[8:11], s[0:1]
	s_waitcnt vmcnt(16)
	v_lshlrev_b32_e32 v136, 16, v224
	v_and_b32_e32 v137, 0xffff0000, v224
	v_lshlrev_b32_e32 v224, 16, v225
	v_and_b32_e32 v225, 0xffff0000, v225
	v_pk_mul_f32 v[6:7], v[6:7], v[152:153]
	v_pk_mul_f32 v[4:5], v[4:5], v[150:151]
	v_pk_mul_f32 v[6:7], v[6:7], v[224:225]
	v_pk_mul_f32 v[4:5], v[4:5], v[136:137]
	s_waitcnt vmcnt(15)
	v_lshlrev_b32_e32 v136, 16, v226
	v_and_b32_e32 v137, 0xffff0000, v226
	v_lshlrev_b32_e32 v226, 16, v227
	v_and_b32_e32 v227, 0xffff0000, v227
	v_pk_mul_f32 v[2:3], v[2:3], v[156:157]
	v_pk_mul_f32 v[0:1], v[0:1], v[154:155]
	v_pk_mul_f32 v[2:3], v[2:3], v[226:227]
	v_pk_mul_f32 v[0:1], v[0:1], v[136:137]
	s_nop 0
	v_cvt_pk_bf16_f32 v0, v0, v1
	v_cvt_pk_bf16_f32 v1, v2, v3
	v_cvt_pk_bf16_f32 v2, v4, v5
	v_cvt_pk_bf16_f32 v3, v6, v7
	s_nop 1
	v_permlane16_swap_b32_e32 v0, v2
	v_permlane16_swap_b32_e32 v1, v3
	global_store_dwordx4 v148, v[0:3], s[0:1] offset:256
	v_readlane_b32 s22, v254, 54
	s_add_i32 s41, s41, s22
	s_cmpk_gt_i32 s41, 0x10f
	v_readlane_b32 s23, v254, 55
	s_cbranch_scc1 .LBB0_2033
